# H (MoE hidden) stored in 16x32-byte tiled layout: up-epilogue stores fully coalesced (512 B per store), down A staging reads tiled layout
# speedup vs baseline: 1.0038x; 1.0038x over previous
.LBB0_766:
	v_mov_b32_e32 v218, 0xbd38aa3b
	v_mov_b32_e32 v219, 0xbd38aa3b
	v_mov_b32_e32 v220, 0x44800000
	v_mov_b32_e32 v221, 0x44800000
	v_lshrrev_b32_e32 v224, 4, v187
	v_lshl_add_u32 v224, s49, 4, v224
	v_lshlrev_b32_e32 v222, 14, v224
	v_lshrrev_b32_e32 v224, 5, v188
	v_lshl_add_u32 v224, s47, 2, v224
	v_lshl_add_u32 v222, v224, 9, v222
	v_and_b32_e32 v224, 15, v187
	v_lshl_add_u32 v222, v224, 5, v222
	v_and_b32_e32 v224, 31, v188
	v_add_u32_e32 v222, v222, v224
	s_mov_b32 s47, s39
	s_mov_b32 s49, s45
	s_mov_b32 s50, s46
	v_pk_mul_f32 v[226:227], v[174:175], v[218:219]
	v_pk_mul_f32 v[228:229], v[176:177], v[218:219]
	v_pk_mul_f32 v[230:231], v[166:167], v[218:219]
	v_pk_mul_f32 v[232:233], v[168:169], v[218:219]
	v_exp_f32_e32 v226, v226
	v_exp_f32_e32 v227, v227
	v_exp_f32_e32 v228, v228
	v_exp_f32_e32 v229, v229
	v_exp_f32_e32 v230, v230
	v_exp_f32_e32 v231, v231
	v_exp_f32_e32 v232, v232
	v_exp_f32_e32 v233, v233
	v_pk_fma_f32 v[226:227], v[226:227], v[220:221], v[220:221]
	v_pk_fma_f32 v[228:229], v[228:229], v[220:221], v[220:221]
	v_pk_fma_f32 v[230:231], v[230:231], v[220:221], v[220:221]
	v_pk_fma_f32 v[232:233], v[232:233], v[220:221], v[220:221]
	v_rcp_f32_e32 v226, v226
	v_rcp_f32_e32 v227, v227
	v_rcp_f32_e32 v228, v228
	v_rcp_f32_e32 v229, v229
	v_rcp_f32_e32 v230, v230
	v_rcp_f32_e32 v231, v231
	v_rcp_f32_e32 v232, v232
	v_rcp_f32_e32 v233, v233
	v_pk_mul_f32 v[174:175], v[174:175], v[170:171]
	v_pk_mul_f32 v[176:177], v[176:177], v[172:173]
	v_pk_mul_f32 v[166:167], v[166:167], v[162:163]
	v_pk_mul_f32 v[168:169], v[168:169], v[164:165]
	v_pk_mul_f32 v[174:175], v[174:175], v[226:227]
	v_pk_mul_f32 v[176:177], v[176:177], v[228:229]
	v_pk_mul_f32 v[166:167], v[166:167], v[230:231]
	v_pk_mul_f32 v[168:169], v[168:169], v[232:233]
	v_mov_b32_e32 v223, v222
	v_cvt_pk_fp8_f32 v234, v174, v175
	v_cvt_pk_fp8_f32 v235, v166, v167
	v_cvt_pk_fp8_f32 v234, v176, v177 op_sel:[0,0,1]
	v_cvt_pk_fp8_f32 v235, v168, v169 op_sel:[0,0,1]
	s_nop 0
	global_store_dwordx2 v223, v[234:235], s[70:71]
	s_mov_b32 s100, 1
	v_pk_mul_f32 v[226:227], v[158:159], v[218:219]
	v_pk_mul_f32 v[228:229], v[160:161], v[218:219]
	v_pk_mul_f32 v[230:231], v[150:151], v[218:219]
	v_pk_mul_f32 v[232:233], v[152:153], v[218:219]
	v_exp_f32_e32 v226, v226
	v_exp_f32_e32 v227, v227
	v_exp_f32_e32 v228, v228
	v_exp_f32_e32 v229, v229
	v_exp_f32_e32 v230, v230
	v_exp_f32_e32 v231, v231
	v_exp_f32_e32 v232, v232
	v_exp_f32_e32 v233, v233
	v_pk_fma_f32 v[226:227], v[226:227], v[220:221], v[220:221]
	v_pk_fma_f32 v[228:229], v[228:229], v[220:221], v[220:221]
	v_pk_fma_f32 v[230:231], v[230:231], v[220:221], v[220:221]
	v_pk_fma_f32 v[232:233], v[232:233], v[220:221], v[220:221]
	v_rcp_f32_e32 v226, v226
	v_rcp_f32_e32 v227, v227
	v_rcp_f32_e32 v228, v228
	v_rcp_f32_e32 v229, v229
	v_rcp_f32_e32 v230, v230
	v_rcp_f32_e32 v231, v231
	v_rcp_f32_e32 v232, v232
	v_rcp_f32_e32 v233, v233
	v_pk_mul_f32 v[158:159], v[158:159], v[154:155]
	v_pk_mul_f32 v[160:161], v[160:161], v[156:157]
	v_pk_mul_f32 v[150:151], v[150:151], v[146:147]
	v_pk_mul_f32 v[152:153], v[152:153], v[148:149]
	v_pk_mul_f32 v[158:159], v[158:159], v[226:227]
	v_pk_mul_f32 v[160:161], v[160:161], v[228:229]
	v_pk_mul_f32 v[150:151], v[150:151], v[230:231]
	v_pk_mul_f32 v[152:153], v[152:153], v[232:233]
	v_add_u32_e32 v225, 0x4000, v222
	v_cvt_pk_fp8_f32 v236, v158, v159
	v_cvt_pk_fp8_f32 v237, v150, v151
	v_cvt_pk_fp8_f32 v236, v160, v161 op_sel:[0,0,1]
	v_cvt_pk_fp8_f32 v237, v152, v153 op_sel:[0,0,1]
	s_nop 0
	global_store_dwordx2 v225, v[236:237], s[70:71]
	s_mov_b32 s100, 1
	v_pk_mul_f32 v[226:227], v[142:143], v[218:219]
	v_pk_mul_f32 v[228:229], v[144:145], v[218:219]
	v_pk_mul_f32 v[230:231], v[134:135], v[218:219]
	v_pk_mul_f32 v[232:233], v[136:137], v[218:219]
	v_exp_f32_e32 v226, v226
	v_exp_f32_e32 v227, v227
	v_exp_f32_e32 v228, v228
	v_exp_f32_e32 v229, v229
	v_exp_f32_e32 v230, v230
	v_exp_f32_e32 v231, v231
	v_exp_f32_e32 v232, v232
	v_exp_f32_e32 v233, v233
	v_pk_fma_f32 v[226:227], v[226:227], v[220:221], v[220:221]
	v_pk_fma_f32 v[228:229], v[228:229], v[220:221], v[220:221]
	v_pk_fma_f32 v[230:231], v[230:231], v[220:221], v[220:221]
	v_pk_fma_f32 v[232:233], v[232:233], v[220:221], v[220:221]
	v_rcp_f32_e32 v226, v226
	v_rcp_f32_e32 v227, v227
	v_rcp_f32_e32 v228, v228
	v_rcp_f32_e32 v229, v229
	v_rcp_f32_e32 v230, v230
	v_rcp_f32_e32 v231, v231
	v_rcp_f32_e32 v232, v232
	v_rcp_f32_e32 v233, v233
	v_pk_mul_f32 v[142:143], v[142:143], v[138:139]
	v_pk_mul_f32 v[144:145], v[144:145], v[140:141]
	v_pk_mul_f32 v[134:135], v[134:135], v[130:131]
	v_pk_mul_f32 v[136:137], v[136:137], v[132:133]
	v_pk_mul_f32 v[142:143], v[142:143], v[226:227]
	v_pk_mul_f32 v[144:145], v[144:145], v[228:229]
	v_pk_mul_f32 v[134:135], v[134:135], v[230:231]
	v_pk_mul_f32 v[136:137], v[136:137], v[232:233]
	v_add_u32_e32 v223, 0x8000, v222
	v_cvt_pk_fp8_f32 v234, v142, v143
	v_cvt_pk_fp8_f32 v235, v134, v135
	v_cvt_pk_fp8_f32 v234, v144, v145 op_sel:[0,0,1]
	v_cvt_pk_fp8_f32 v235, v136, v137 op_sel:[0,0,1]
	s_nop 0
	global_store_dwordx2 v223, v[234:235], s[70:71]
	s_mov_b32 s100, 1
	v_pk_mul_f32 v[226:227], v[126:127], v[218:219]
	v_pk_mul_f32 v[228:229], v[128:129], v[218:219]
	v_pk_mul_f32 v[230:231], v[118:119], v[218:219]
	v_pk_mul_f32 v[232:233], v[120:121], v[218:219]
	v_exp_f32_e32 v226, v226
	v_exp_f32_e32 v227, v227
	v_exp_f32_e32 v228, v228
	v_exp_f32_e32 v229, v229
	v_exp_f32_e32 v230, v230
	v_exp_f32_e32 v231, v231
	v_exp_f32_e32 v232, v232
	v_exp_f32_e32 v233, v233
	v_pk_fma_f32 v[226:227], v[226:227], v[220:221], v[220:221]
	v_pk_fma_f32 v[228:229], v[228:229], v[220:221], v[220:221]
	v_pk_fma_f32 v[230:231], v[230:231], v[220:221], v[220:221]
	v_pk_fma_f32 v[232:233], v[232:233], v[220:221], v[220:221]
	v_rcp_f32_e32 v226, v226
	v_rcp_f32_e32 v227, v227
	v_rcp_f32_e32 v228, v228
	v_rcp_f32_e32 v229, v229
	v_rcp_f32_e32 v230, v230
	v_rcp_f32_e32 v231, v231
	v_rcp_f32_e32 v232, v232
	v_rcp_f32_e32 v233, v233
	v_pk_mul_f32 v[126:127], v[126:127], v[122:123]
	v_pk_mul_f32 v[128:129], v[128:129], v[124:125]
	v_pk_mul_f32 v[118:119], v[118:119], v[114:115]
	v_pk_mul_f32 v[120:121], v[120:121], v[116:117]
	v_pk_mul_f32 v[126:127], v[126:127], v[226:227]
	v_pk_mul_f32 v[128:129], v[128:129], v[228:229]
	v_pk_mul_f32 v[118:119], v[118:119], v[230:231]
	v_pk_mul_f32 v[120:121], v[120:121], v[232:233]
	v_add_u32_e32 v225, 0xc000, v222
	v_cvt_pk_fp8_f32 v236, v126, v127
	v_cvt_pk_fp8_f32 v237, v118, v119
	v_cvt_pk_fp8_f32 v236, v128, v129 op_sel:[0,0,1]
	v_cvt_pk_fp8_f32 v237, v120, v121 op_sel:[0,0,1]
	s_nop 0
	global_store_dwordx2 v225, v[236:237], s[70:71]
	s_mov_b32 s100, 1
	v_pk_mul_f32 v[226:227], v[110:111], v[218:219]
	v_pk_mul_f32 v[228:229], v[112:113], v[218:219]
	v_pk_mul_f32 v[230:231], v[102:103], v[218:219]
	v_pk_mul_f32 v[232:233], v[104:105], v[218:219]
	v_exp_f32_e32 v226, v226
	v_exp_f32_e32 v227, v227
	v_exp_f32_e32 v228, v228
	v_exp_f32_e32 v229, v229
	v_exp_f32_e32 v230, v230
	v_exp_f32_e32 v231, v231
	v_exp_f32_e32 v232, v232
	v_exp_f32_e32 v233, v233
	v_pk_fma_f32 v[226:227], v[226:227], v[220:221], v[220:221]
	v_pk_fma_f32 v[228:229], v[228:229], v[220:221], v[220:221]
	v_pk_fma_f32 v[230:231], v[230:231], v[220:221], v[220:221]
	v_pk_fma_f32 v[232:233], v[232:233], v[220:221], v[220:221]
	v_rcp_f32_e32 v226, v226
	v_rcp_f32_e32 v227, v227
	v_rcp_f32_e32 v228, v228
	v_rcp_f32_e32 v229, v229
	v_rcp_f32_e32 v230, v230
	v_rcp_f32_e32 v231, v231
	v_rcp_f32_e32 v232, v232
	v_rcp_f32_e32 v233, v233
	v_pk_mul_f32 v[110:111], v[110:111], v[106:107]
	v_pk_mul_f32 v[112:113], v[112:113], v[108:109]
	v_pk_mul_f32 v[102:103], v[102:103], v[98:99]
	v_pk_mul_f32 v[104:105], v[104:105], v[100:101]
	v_pk_mul_f32 v[110:111], v[110:111], v[226:227]
	v_pk_mul_f32 v[112:113], v[112:113], v[228:229]
	v_pk_mul_f32 v[102:103], v[102:103], v[230:231]
	v_pk_mul_f32 v[104:105], v[104:105], v[232:233]
	v_add_u32_e32 v223, 0x20000, v222
	v_cvt_pk_fp8_f32 v234, v110, v111
	v_cvt_pk_fp8_f32 v235, v102, v103
	v_cvt_pk_fp8_f32 v234, v112, v113 op_sel:[0,0,1]
	v_cvt_pk_fp8_f32 v235, v104, v105 op_sel:[0,0,1]
	s_nop 0
	global_store_dwordx2 v223, v[234:235], s[70:71]
	s_mov_b32 s100, 1
	v_pk_mul_f32 v[226:227], v[94:95], v[218:219]
	v_pk_mul_f32 v[228:229], v[96:97], v[218:219]
	v_pk_mul_f32 v[230:231], v[86:87], v[218:219]
	v_pk_mul_f32 v[232:233], v[88:89], v[218:219]
	v_exp_f32_e32 v226, v226
	v_exp_f32_e32 v227, v227
	v_exp_f32_e32 v228, v228
	v_exp_f32_e32 v229, v229
	v_exp_f32_e32 v230, v230
	v_exp_f32_e32 v231, v231
	v_exp_f32_e32 v232, v232
	v_exp_f32_e32 v233, v233
	v_pk_fma_f32 v[226:227], v[226:227], v[220:221], v[220:221]
	v_pk_fma_f32 v[228:229], v[228:229], v[220:221], v[220:221]
	v_pk_fma_f32 v[230:231], v[230:231], v[220:221], v[220:221]
	v_pk_fma_f32 v[232:233], v[232:233], v[220:221], v[220:221]
	v_rcp_f32_e32 v226, v226
	v_rcp_f32_e32 v227, v227
	v_rcp_f32_e32 v228, v228
	v_rcp_f32_e32 v229, v229
	v_rcp_f32_e32 v230, v230
	v_rcp_f32_e32 v231, v231
	v_rcp_f32_e32 v232, v232
	v_rcp_f32_e32 v233, v233
	v_pk_mul_f32 v[94:95], v[94:95], v[90:91]
	v_pk_mul_f32 v[96:97], v[96:97], v[92:93]
	v_pk_mul_f32 v[86:87], v[86:87], v[82:83]
	v_pk_mul_f32 v[88:89], v[88:89], v[84:85]
	v_pk_mul_f32 v[94:95], v[94:95], v[226:227]
	v_pk_mul_f32 v[96:97], v[96:97], v[228:229]
	v_pk_mul_f32 v[86:87], v[86:87], v[230:231]
	v_pk_mul_f32 v[88:89], v[88:89], v[232:233]
	v_add_u32_e32 v225, 0x24000, v222
	v_cvt_pk_fp8_f32 v236, v94, v95
	v_cvt_pk_fp8_f32 v237, v86, v87
	v_cvt_pk_fp8_f32 v236, v96, v97 op_sel:[0,0,1]
	v_cvt_pk_fp8_f32 v237, v88, v89 op_sel:[0,0,1]
	s_nop 0
	global_store_dwordx2 v225, v[236:237], s[70:71]
	s_mov_b32 s100, 1
	v_pk_mul_f32 v[226:227], v[78:79], v[218:219]
	v_pk_mul_f32 v[228:229], v[80:81], v[218:219]
	v_pk_mul_f32 v[230:231], v[70:71], v[218:219]
	v_pk_mul_f32 v[232:233], v[72:73], v[218:219]
	v_exp_f32_e32 v226, v226
	v_exp_f32_e32 v227, v227
	v_exp_f32_e32 v228, v228
	v_exp_f32_e32 v229, v229
	v_exp_f32_e32 v230, v230
	v_exp_f32_e32 v231, v231
	v_exp_f32_e32 v232, v232
	v_exp_f32_e32 v233, v233
	v_pk_fma_f32 v[226:227], v[226:227], v[220:221], v[220:221]
	v_pk_fma_f32 v[228:229], v[228:229], v[220:221], v[220:221]
	v_pk_fma_f32 v[230:231], v[230:231], v[220:221], v[220:221]
	v_pk_fma_f32 v[232:233], v[232:233], v[220:221], v[220:221]
	v_rcp_f32_e32 v226, v226
	v_rcp_f32_e32 v227, v227
	v_rcp_f32_e32 v228, v228
	v_rcp_f32_e32 v229, v229
	v_rcp_f32_e32 v230, v230
	v_rcp_f32_e32 v231, v231
	v_rcp_f32_e32 v232, v232
	v_rcp_f32_e32 v233, v233
	v_pk_mul_f32 v[78:79], v[78:79], v[74:75]
	v_pk_mul_f32 v[80:81], v[80:81], v[76:77]
	v_pk_mul_f32 v[70:71], v[70:71], v[66:67]
	v_pk_mul_f32 v[72:73], v[72:73], v[68:69]
	v_pk_mul_f32 v[78:79], v[78:79], v[226:227]
	v_pk_mul_f32 v[80:81], v[80:81], v[228:229]
	v_pk_mul_f32 v[70:71], v[70:71], v[230:231]
	v_pk_mul_f32 v[72:73], v[72:73], v[232:233]
	v_add_u32_e32 v223, 0x28000, v222
	v_cvt_pk_fp8_f32 v234, v78, v79
	v_cvt_pk_fp8_f32 v235, v70, v71
	v_cvt_pk_fp8_f32 v234, v80, v81 op_sel:[0,0,1]
	v_cvt_pk_fp8_f32 v235, v72, v73 op_sel:[0,0,1]
	s_nop 0
	global_store_dwordx2 v223, v[234:235], s[70:71]
	s_mov_b32 s100, 1
	v_pk_mul_f32 v[226:227], v[62:63], v[218:219]
	v_pk_mul_f32 v[228:229], v[64:65], v[218:219]
	v_pk_mul_f32 v[230:231], v[54:55], v[218:219]
	v_pk_mul_f32 v[232:233], v[56:57], v[218:219]
	v_exp_f32_e32 v226, v226
	v_exp_f32_e32 v227, v227
	v_exp_f32_e32 v228, v228
	v_exp_f32_e32 v229, v229
	v_exp_f32_e32 v230, v230
	v_exp_f32_e32 v231, v231
	v_exp_f32_e32 v232, v232
	v_exp_f32_e32 v233, v233
	v_pk_fma_f32 v[226:227], v[226:227], v[220:221], v[220:221]
	v_pk_fma_f32 v[228:229], v[228:229], v[220:221], v[220:221]
	v_pk_fma_f32 v[230:231], v[230:231], v[220:221], v[220:221]
	v_pk_fma_f32 v[232:233], v[232:233], v[220:221], v[220:221]
	v_rcp_f32_e32 v226, v226
	v_rcp_f32_e32 v227, v227
	v_rcp_f32_e32 v228, v228
	v_rcp_f32_e32 v229, v229
	v_rcp_f32_e32 v230, v230
	v_rcp_f32_e32 v231, v231
	v_rcp_f32_e32 v232, v232
	v_rcp_f32_e32 v233, v233
	v_pk_mul_f32 v[62:63], v[62:63], v[58:59]
	v_pk_mul_f32 v[64:65], v[64:65], v[60:61]
	v_pk_mul_f32 v[54:55], v[54:55], v[50:51]
	v_pk_mul_f32 v[56:57], v[56:57], v[52:53]
	v_pk_mul_f32 v[62:63], v[62:63], v[226:227]
	v_pk_mul_f32 v[64:65], v[64:65], v[228:229]
	v_pk_mul_f32 v[54:55], v[54:55], v[230:231]
	v_pk_mul_f32 v[56:57], v[56:57], v[232:233]
	v_add_u32_e32 v225, 0x2c000, v222
	v_cvt_pk_fp8_f32 v236, v62, v63
	v_cvt_pk_fp8_f32 v237, v54, v55
	v_cvt_pk_fp8_f32 v236, v64, v65 op_sel:[0,0,1]
	v_cvt_pk_fp8_f32 v237, v56, v57 op_sel:[0,0,1]
	s_nop 0
	global_store_dwordx2 v225, v[236:237], s[70:71]
	s_mov_b32 s100, 1
	s_and_b64 vcc, exec, s[4:5]
	s_cbranch_vccnz .LBB0_777

.LBB0_830:
	s_cmp_gt_i32 s60, 10
	s_cselect_b64 s[4:5], -1, 0
	s_cmp_lt_i32 s61, 11
	s_cselect_b64 s[6:7], -1, 0
	s_or_b64 s[4:5], s[4:5], s[6:7]
	s_and_b64 vcc, exec, s[4:5]
	s_cbranch_vccnz .LBB0_895
	s_waitcnt vmcnt(0)
	v_mov_b32_e32 v2, v0
	s_cmpk_gt_i32 s2, 0x43f
	v_readfirstlane_b32 s3, v2
	s_cbranch_scc1 .LBB0_845
	v_bfe_i32 v4, v2, 27, 1
	v_lshlrev_b32_e32 v1, 4, v2
	v_lshrrev_b32_e32 v4, 22, v4
	v_add_u32_e32 v4, v1, v4
	v_and_b32_e32 v4, 0xfffffc00, v4
	v_sub_u32_e32 v1, v1, v4
	v_ashrrev_i32_e32 v3, 31, v2
	v_lshrrev_b32_e32 v4, 4, v1
	v_lshrrev_b32_e32 v3, 26, v3
	v_bitop3_b32 v1, v4, v1, 32 bitop3:0x6c
	s_add_u32 s8, s52, 0x6b00000
	v_add_u32_e32 v3, v2, v3
	v_ashrrev_i32_e32 v5, 31, v1
	s_addc_u32 s6, s53, 0
	v_ashrrev_i32_e32 v3, 6, v3
	v_lshrrev_b32_e32 v5, 26, v5
	s_ashr_i32 s20, s2, 31
	v_lshlrev_b32_e32 v4, 3, v3
	v_add_u32_e32 v5, v1, v5
	s_lshr_b32 s7, s20, 29
	v_and_b32_e32 v4, -16, v4
	v_ashrrev_i32_e32 v6, 6, v5
	s_add_i32 s7, s2, s7
	s_ashr_i32 s4, s3, 6
	v_add_u32_e32 v4, v6, v4
	v_and_b32_e32 v6, 3, v6
	s_mov_b32 s5, 0x3fffe0
	s_ashr_i32 s12, s7, 3
	s_and_b32 s7, s7, -8
	s_and_b32 s45, s71, 0xffff
	v_and_or_b32 v6, v4, s5, v6
	s_ashr_i32 s5, s3, 8
	s_and_b32 s9, s6, 0xffff
	s_lshl_b32 s6, s4, 10
	s_sub_i32 s7, s2, s7
	s_cmp_lt_i32 s7, 0
	s_movk_i32 s21, 0x89
	s_cselect_b32 s13, s21, 0x88
	s_mul_i32 s7, s13, s7
	s_add_i32 s7, s7, s12
	s_ashr_i32 s12, s7, 31
	s_lshr_b32 s12, s12, 27
	s_add_i32 s12, s7, s12
	s_ashr_i32 s13, s12, 5
	s_andn2_b32 s12, s12, 31
	s_sub_i32 s7, s7, s12
	s_bfe_i32 s12, s7, 0x80000
	s_bfe_u32 s12, s12, 0x3000c
	s_add_i32 s12, s7, s12
	s_bfe_i32 s14, s12, 0x80000
	s_and_b32 s12, s12, 0xf8
	s_sub_i32 s7, s7, s12
	s_lshl_b32 s13, s13, 3
	s_sext_i32_i8 s7, s7
	v_and_b32_e32 v5, 0xc0, v5
	s_add_i32 s73, s13, s7
	v_sub_u32_e32 v1, v1, v5
	v_mov_b32_e32 v5, 1
	s_mul_hi_i32 s7, s73, 0x78787879
	v_lshlrev_b32_e32 v3, 5, v3
	v_ashrrev_i16_sdwa v1, v5, sext(v1) dst_sel:DWORD dst_unused:UNUSED_PAD src0_sel:DWORD src1_sel:BYTE_0
	v_lshlrev_b32_e32 v5, 1, v4
	v_lshrrev_b32_e32 v7, 2, v4
	s_sext_i32_i16 s14, s14
	s_lshr_b32 s12, s7, 31
	s_lshr_b32 s7, s7, 3
	v_and_b32_e32 v3, 32, v3
	v_bfe_i32 v1, v1, 0, 16
	v_and_b32_e32 v5, 24, v5
	v_and_b32_e32 v7, 4, v7
	s_ashr_i32 s72, s14, 3
	s_add_i32 s7, s7, s12
	s_add_i32 s22, s6, 0
	s_mov_b32 s47, 0x20000
	s_brev_b32 s46, -2
	v_or3_b32 v5, v6, v7, v5
	v_add_lshl_u32 v3, v3, v1, 1
	s_lshl_b32 s7, s7, 20
	s_lshl_b32 s12, s72, 18
	s_add_i32 s23, s22, 0x10000
	v_and_b32_e32 v254, 3, v4
	v_lshrrev_b32_e32 v5, 2, v4
	v_and_b32_e32 v5, 4, v5
	v_or_b32_e32 v254, v254, v5
	v_lshlrev_b32_e32 v5, 2, v4
	v_and_b32_e32 v5, 0x30, v5
	v_or_b32_e32 v254, v254, v5
	v_lshlrev_b32_e32 v5, 1, v4
	v_and_b32_e32 v5, 0x40, v5
	v_or_b32_e32 v254, v254, v5
	v_lshl_add_u32 v134, v254, 10, v3
	s_mov_b32 s10, s46
	s_mov_b32 s11, s47
	s_add_i32 s78, s7, s12
	s_mov_b32 m0, s23
	s_add_i32 s24, s22, 0x12000
	s_mov_b32 s100, 0
	buffer_load_dwordx4 v134, s[8:11], s78 offen lds
	s_or_b32 s6, s78, 0x20000
	s_mov_b32 m0, s24
	v_lshrrev_b32_e32 v254, 4, v4
	v_lshlrev_b32_e32 v1, 14, v254
	v_lshrrev_b32_e32 v254, 5, v3
	v_lshl_add_u32 v1, v254, 9, v1
	v_and_b32_e32 v254, 15, v4
	v_lshl_add_u32 v1, v254, 5, v1
	v_and_b32_e32 v254, 31, v3
	v_add_u32_e32 v1, v1, v254
	buffer_load_dwordx4 v134, s[8:11], s6 offen lds
	s_lshl_b32 s79, s73, 18
	s_mov_b32 m0, s22
	s_add_i32 s25, s22, 0x2000
	buffer_load_dwordx4 v1, s[44:47], s79 offen lds
	s_or_b32 s6, s79, 0x10000
	s_mov_b32 m0, s25
	s_add_i32 s26, s22, 0x14000
	buffer_load_dwordx4 v1, s[44:47], s6 offen lds
	s_or_b32 s6, s78, 0x2000
	s_mov_b32 m0, s26
	s_add_i32 s27, s22, 0x16000
	buffer_load_dwordx4 v134, s[8:11], s6 offen lds
	s_or_b32 s6, s78, 0x22000
	s_mov_b32 m0, s27
	s_add_i32 s28, s22, 0x4000
	buffer_load_dwordx4 v134, s[8:11], s6 offen lds
	s_or_b32 s6, s79, 0x20000
	s_mov_b32 m0, s28
	s_add_i32 s29, s22, 0x6000
	buffer_load_dwordx4 v1, s[44:47], s6 offen lds
	s_or_b32 s6, s79, 0x30000
	s_mov_b32 m0, s29
	s_cmp_lg_u32 s5, 1
	buffer_load_dwordx4 v1, s[44:47], s6 offen lds
	s_mov_b32 s30, 0
	s_cbranch_scc1 .LBB0_834
	s_barrier
.LBB0_834:
	s_add_i32 s31, s22, 0x18000
	s_or_b32 s6, s78, 0x80
	s_mov_b32 s10, s46
	s_mov_b32 s11, s47
	s_mov_b32 m0, s31
	s_add_i32 s34, s22, 0x1a000
	s_waitcnt vmcnt(4)
	s_barrier
	buffer_load_dwordx4 v134, s[8:11], s6 offen lds
	s_or_b32 s6, s78, 0x20080
	s_mov_b32 m0, s34
	s_add_i32 s35, s22, 0x8000
	buffer_load_dwordx4 v134, s[8:11], s6 offen lds
	s_or_b32 s6, s79, 0x800
	s_mov_b32 m0, s35
	s_add_i32 s36, s22, 0xa000
	buffer_load_dwordx4 v1, s[44:47], s6 offen lds
	s_or_b32 s6, s79, 0x10800
	s_mov_b32 m0, s36
	s_add_i32 s37, s22, 0x1c000
	buffer_load_dwordx4 v1, s[44:47], s6 offen lds
	s_or_b32 s6, s78, 0x2080
	s_mov_b32 m0, s37
	s_add_i32 s38, s22, 0x1e000
	buffer_load_dwordx4 v134, s[8:11], s6 offen lds
	s_or_b32 s6, s78, 0x22080
	s_mov_b32 m0, s38
	v_and_b32_e32 v3, 15, v2
	buffer_load_dwordx4 v134, s[8:11], s6 offen lds
	v_lshrrev_b32_e32 v4, 1, v2
	s_and_b32 s4, s4, 3
	v_and_b32_e32 v4, 24, v4
	v_lshlrev_b32_e32 v5, 6, v3
	v_lshlrev_b32_e32 v2, 2, v2
	v_lshl_or_b32 v5, v4, 1, v5
	v_and_b32_e32 v2, 32, v2
	s_lshl_b32 s6, s5, 13
	s_lshl_b32 s7, s4, 12
	v_bitop3_b32 v6, v5, s6, v2 bitop3:0xde
	v_bitop3_b32 v2, v5, s7, v2 bitop3:0xde
	s_waitcnt vmcnt(6)
	v_add_u32_e32 v2, 0, v2
	s_add_i32 s39, s22, 0xc000
	v_lshl_or_b32 v135, s5, 6, v3
	s_add_i32 s41, s22, 0xe000
	s_ashr_i32 s42, s56, 31
	v_lshl_or_b32 v136, s4, 5, v4
	v_add_u32_e32 v137, 0x10000, v2
	v_add_u32_e32 v138, 0, v6
	v_add_u32_e32 v139, 0x14000, v2
	v_add_u32_e32 v140, 0x18000, v2
	v_add_u32_e32 v141, 0x1c000, v2
	s_mov_b64 s[12:13], 0x20000
	s_mov_b64 s[14:15], 0x24000
	s_mov_b32 s43, 0x24000
	s_mov_b64 s[16:17], 0x28000
	s_mov_b32 s49, 0x28000
	s_mov_b64 s[18:19], 0x2c000
	s_mov_b32 s50, 0x2c000
	s_barrier

.LBB0_839:
	s_lshl_b32 s59, s57, 18
	s_and_b64 s[6:7], s[6:7], exec
	v_mov_b32_e32 v2, 0
	s_cselect_b32 s6, s59, s79
	s_add_i32 s7, s79, 0x30800
	s_addk_i32 s78, 0x100
	s_mov_b32 s79, -2
	ds_read_b128 v[142:145], v137
	ds_read_b128 v[146:149], v137 offset:1024
	ds_read_b128 v[150:153], v137 offset:2048
	ds_read_b128 v[154:157], v137 offset:3072
	s_add_i32 s10, s7, 0xfffd0800
	s_cmp_eq_u32 s79, 4
	s_cselect_b32 s87, s6, s10
	s_cselect_b32 s86, s58, s78
	s_or_b32 s88, s87, 0x800
	s_add_i32 s10, s7, 0xffff0000
	s_mov_b32 m0, s39
	ds_read_b128 v[158:161], v138
	ds_read_b128 v[162:165], v138 offset:1024
	ds_read_b128 v[166:169], v138 offset:2048
	ds_read_b128 v[170:173], v138 offset:3072
	ds_read_b128 v[174:177], v138 offset:4096
	ds_read_b128 v[178:181], v138 offset:5120
	ds_read_b128 v[182:185], v138 offset:6144
	ds_read_b128 v[186:189], v138 offset:7168
	buffer_load_dwordx4 v1, s[44:47], s10 offen lds
	s_mov_b32 m0, s41
	s_nop 0
	buffer_load_dwordx4 v1, s[44:47], s7 offen lds
	s_waitcnt lgkmcnt(8)
	s_barrier
	s_waitcnt lgkmcnt(0)
	s_setprio 1
	s_waitcnt lgkmcnt(4)
	v_mfma_f32_16x16x128_f8f6f4 v[114:117], v[142:149], v[166:173], 0
	v_mfma_f32_16x16x128_f8f6f4 v[106:109], v[150:157], v[166:173], 0
	s_waitcnt lgkmcnt(2)
	v_mfma_f32_16x16x128_f8f6f4 v[98:101], v[142:149], v[174:181], 0
	v_mfma_f32_16x16x128_f8f6f4 v[198:201], v[142:149], v[158:165], 0
	v_mfma_f32_16x16x128_f8f6f4 v[202:205], v[150:157], v[158:165], 0
	v_mfma_f32_16x16x128_f8f6f4 v[206:209], v[150:157], v[174:181], 0
	s_waitcnt lgkmcnt(0)
	v_mfma_f32_16x16x128_f8f6f4 v[210:213], v[142:149], v[182:189], 0
	v_mfma_f32_16x16x128_f8f6f4 v[214:217], v[150:157], v[182:189], 0
	s_setprio 0
	s_barrier
	s_mov_b32 m0, s23
	s_mov_b32 s10, s46
	s_mov_b32 s11, s47
	ds_read_b128 v[122:125], v139
	ds_read_b128 v[126:129], v139 offset:1024
	ds_read_b128 v[190:193], v139 offset:2048
	ds_read_b128 v[194:197], v139 offset:3072
	buffer_load_dwordx4 v134, s[8:11], s86 offen lds
	s_add_i32 s33, s86, 0x20000
	s_mov_b32 m0, s24
	s_nop 0
	buffer_load_dwordx4 v134, s[8:11], s33 offen lds
	s_barrier
	s_waitcnt lgkmcnt(0)
	s_setprio 1
	s_waitcnt lgkmcnt(2)
	v_mfma_f32_16x16x128_f8f6f4 v[118:121], v[122:129], v[158:165], 0
	s_waitcnt lgkmcnt(0)
	v_mfma_f32_16x16x128_f8f6f4 v[110:113], v[190:197], v[158:165], 0
	v_mfma_f32_16x16x128_f8f6f4 v[102:105], v[122:129], v[166:173], 0
	v_mfma_f32_16x16x128_f8f6f4 v[158:161], v[190:197], v[166:173], 0
	v_mfma_f32_16x16x128_f8f6f4 v[162:165], v[122:129], v[174:181], 0
	v_mfma_f32_16x16x128_f8f6f4 v[166:169], v[190:197], v[174:181], 0
	v_mfma_f32_16x16x128_f8f6f4 v[170:173], v[122:129], v[182:189], 0
	v_mfma_f32_16x16x128_f8f6f4 v[174:177], v[190:197], v[182:189], 0
	s_setprio 0
	s_mov_b32 m0, s22
	s_barrier
	ds_read_b128 v[66:69], v138 offset:16384
	s_nop 1
	ds_read_b128 v[70:73], v138 offset:17408
	ds_read_b128 v[74:77], v138 offset:18432
	ds_read_b128 v[78:81], v138 offset:19456
	ds_read_b128 v[82:85], v138 offset:20480
	ds_read_b128 v[86:89], v138 offset:21504
	ds_read_b128 v[90:93], v138 offset:22528
	ds_read_b128 v[94:97], v138 offset:23552
	buffer_load_dwordx4 v1, s[44:47], s87 offen lds
	s_add_i32 s33, s87, 0x10000
	s_mov_b32 m0, s25
	s_nop 0
	buffer_load_dwordx4 v1, s[44:47], s33 offen lds
	s_barrier
	s_waitcnt lgkmcnt(0)
	s_setprio 1
	s_waitcnt lgkmcnt(6)
	v_mfma_f32_16x16x128_f8f6f4 v[62:65], v[142:149], v[66:73], 0
	v_mfma_f32_16x16x128_f8f6f4 v[58:61], v[150:157], v[66:73], 0
	s_waitcnt lgkmcnt(4)
	v_mfma_f32_16x16x128_f8f6f4 v[50:53], v[142:149], v[74:81], 0
	s_waitcnt lgkmcnt(0)
	v_mfma_f32_16x16x128_f8f6f4 v[230:233], v[142:149], v[90:97], 0
	v_mfma_f32_16x16x128_f8f6f4 v[218:221], v[150:157], v[74:81], 0
	v_mfma_f32_16x16x128_f8f6f4 v[222:225], v[142:149], v[82:89], 0
	v_mfma_f32_16x16x128_f8f6f4 v[226:229], v[150:157], v[82:89], 0
	v_mfma_f32_16x16x128_f8f6f4 v[234:237], v[150:157], v[90:97], 0
	s_setprio 0
	s_barrier
	s_mov_b32 m0, s26
	s_add_i32 s33, s86, 0x2000
	buffer_load_dwordx4 v134, s[8:11], s33 offen lds
	s_add_i32 s33, s86, 0x22000
	s_mov_b32 m0, s27
	s_nop 0
	buffer_load_dwordx4 v134, s[8:11], s33 offen lds
	s_cmp_eq_u32 s100, 0
	s_cbranch_scc1 .Lfw_4_a_p
	s_waitcnt vmcnt(16)
	s_mov_b32 s100, 0
	s_branch .Lfw_4_b_p

.Lfw_4_b_p:
	s_barrier
	s_setprio 1
	v_mfma_f32_16x16x128_f8f6f4 v[54:57], v[122:129], v[66:73], 0
	v_mfma_f32_16x16x128_f8f6f4 v[238:241], v[190:197], v[66:73], 0
	v_mfma_f32_16x16x128_f8f6f4 v[242:245], v[122:129], v[74:81], 0
	v_mfma_f32_16x16x128_f8f6f4 v[246:249], v[190:197], v[74:81], 0
	v_mfma_f32_16x16x128_f8f6f4 v[250:253], v[122:129], v[82:89], 0
	v_mfma_f32_16x16x128_f8f6f4 v[130:133], v[190:197], v[82:89], 0
	v_mfma_f32_16x16x128_f8f6f4 v[66:69], v[122:129], v[90:97], 0
	v_mfma_f32_16x16x128_f8f6f4 v[190:193], v[190:197], v[90:97], 0
	s_setprio 0
	s_barrier
	s_nop 4
	ds_read_b128 v[2:5], v140
	ds_read_b128 v[6:9], v140 offset:1024
	ds_read_b128 v[10:13], v140 offset:2048
	ds_read_b128 v[14:17], v140 offset:3072
	s_mov_b32 m0, s28
	s_add_i32 s33, s87, 0x20000
	ds_read_b128 v[18:21], v138 offset:32768
	ds_read_b128 v[22:25], v138 offset:33792
	ds_read_b128 v[26:29], v138 offset:34816
	ds_read_b128 v[30:33], v138 offset:35840
	ds_read_b128 v[34:37], v138 offset:36864
	ds_read_b128 v[38:41], v138 offset:37888
	ds_read_b128 v[42:45], v138 offset:38912
	ds_read_b128 v[46:49], v138 offset:39936
	buffer_load_dwordx4 v1, s[44:47], s33 offen lds
	s_add_i32 s33, s87, 0x30000
	s_mov_b32 m0, s29
	s_nop 0
	buffer_load_dwordx4 v1, s[44:47], s33 offen lds
	s_waitcnt lgkmcnt(8)
	s_barrier
	s_waitcnt lgkmcnt(0)
	s_setprio 1
	s_waitcnt lgkmcnt(6)
	v_mfma_f32_16x16x128_f8f6f4 v[126:129], v[2:9], v[18:25], v[198:201]
	v_mfma_f32_16x16x128_f8f6f4 v[122:125], v[10:17], v[18:25], v[202:205]
	s_waitcnt lgkmcnt(4)
	v_mfma_f32_16x16x128_f8f6f4 v[114:117], v[2:9], v[26:33], v[114:117]
	v_mfma_f32_16x16x128_f8f6f4 v[106:109], v[10:17], v[26:33], v[106:109]
	s_waitcnt lgkmcnt(2)
	v_mfma_f32_16x16x128_f8f6f4 v[98:101], v[2:9], v[34:41], v[98:101]
	v_mfma_f32_16x16x128_f8f6f4 v[90:93], v[10:17], v[34:41], v[206:209]
	s_waitcnt lgkmcnt(0)
	v_mfma_f32_16x16x128_f8f6f4 v[82:85], v[2:9], v[42:49], v[210:213]
	v_mfma_f32_16x16x128_f8f6f4 v[74:77], v[10:17], v[42:49], v[214:217]
	s_setprio 0
	s_barrier
	s_mov_b32 m0, s31
	s_add_i32 s33, s86, 0x80
	ds_read_b128 v[142:145], v141
	ds_read_b128 v[146:149], v141 offset:1024
	ds_read_b128 v[150:153], v141 offset:2048
	ds_read_b128 v[154:157], v141 offset:3072
	buffer_load_dwordx4 v134, s[8:11], s33 offen lds
	s_add_i32 s33, s86, 0x20080
	s_mov_b32 m0, s34
	s_nop 0
	buffer_load_dwordx4 v134, s[8:11], s33 offen lds
	s_waitcnt vmcnt(10)
	s_barrier
	s_waitcnt lgkmcnt(0)
	s_setprio 1
	s_waitcnt lgkmcnt(2)
	v_mfma_f32_16x16x128_f8f6f4 v[118:121], v[142:149], v[18:25], v[118:121]
	s_waitcnt lgkmcnt(0)
	v_mfma_f32_16x16x128_f8f6f4 v[110:113], v[150:157], v[18:25], v[110:113]
	v_mfma_f32_16x16x128_f8f6f4 v[102:105], v[142:149], v[26:33], v[102:105]
	v_mfma_f32_16x16x128_f8f6f4 v[94:97], v[150:157], v[26:33], v[158:161]
	v_mfma_f32_16x16x128_f8f6f4 v[86:89], v[142:149], v[34:41], v[162:165]
	v_mfma_f32_16x16x128_f8f6f4 v[78:81], v[150:157], v[34:41], v[166:169]
	v_mfma_f32_16x16x128_f8f6f4 v[70:73], v[142:149], v[42:49], v[170:173]
	v_mfma_f32_16x16x128_f8f6f4 v[18:21], v[150:157], v[42:49], v[174:177]
	s_setprio 0
	s_mov_b32 m0, s35
	s_barrier
	ds_read_b128 v[158:161], v138 offset:49152
	ds_read_b128 v[162:165], v138 offset:50176
	ds_read_b128 v[166:169], v138 offset:51200
	ds_read_b128 v[170:173], v138 offset:52224
	ds_read_b128 v[174:177], v138 offset:53248
	ds_read_b128 v[178:181], v138 offset:54272
	ds_read_b128 v[182:185], v138 offset:55296
	ds_read_b128 v[186:189], v138 offset:56320
	buffer_load_dwordx4 v1, s[44:47], s88 offen lds
	s_add_i32 s87, s87, 0x10800
	s_mov_b32 m0, s36
	s_nop 0
	buffer_load_dwordx4 v1, s[44:47], s87 offen lds
	s_barrier
	s_waitcnt lgkmcnt(0)
	s_setprio 1
	s_waitcnt lgkmcnt(6)
	v_mfma_f32_16x16x128_f8f6f4 v[62:65], v[2:9], v[158:165], v[62:65]
	v_mfma_f32_16x16x128_f8f6f4 v[58:61], v[10:17], v[158:165], v[58:61]
	s_waitcnt lgkmcnt(4)
	v_mfma_f32_16x16x128_f8f6f4 v[50:53], v[2:9], v[166:173], v[50:53]
	v_mfma_f32_16x16x128_f8f6f4 v[42:45], v[10:17], v[166:173], v[218:221]
	s_waitcnt lgkmcnt(2)
	v_mfma_f32_16x16x128_f8f6f4 v[34:37], v[2:9], v[174:181], v[222:225]
	v_mfma_f32_16x16x128_f8f6f4 v[26:29], v[10:17], v[174:181], v[226:229]
	s_waitcnt lgkmcnt(0)
	v_mfma_f32_16x16x128_f8f6f4 v[230:233], v[2:9], v[182:189], v[230:233]
	v_mfma_f32_16x16x128_f8f6f4 v[10:13], v[10:17], v[182:189], v[234:237]
	s_setprio 0
	s_barrier
	s_mov_b32 m0, s37
	s_add_i32 s33, s86, 0x2080
	buffer_load_dwordx4 v134, s[8:11], s33 offen lds
	s_add_i32 s86, s86, 0x22080
	s_mov_b32 m0, s38
	s_nop 0
	buffer_load_dwordx4 v134, s[8:11], s86 offen lds
	s_waitcnt vmcnt(6)
	s_barrier
	s_setprio 1
	v_mfma_f32_16x16x128_f8f6f4 v[54:57], v[142:149], v[158:165], v[54:57]
	v_mfma_f32_16x16x128_f8f6f4 v[46:49], v[150:157], v[158:165], v[238:241]
	v_mfma_f32_16x16x128_f8f6f4 v[38:41], v[142:149], v[166:173], v[242:245]
	v_mfma_f32_16x16x128_f8f6f4 v[30:33], v[150:157], v[166:173], v[246:249]
	v_mfma_f32_16x16x128_f8f6f4 v[22:25], v[142:149], v[174:181], v[250:253]
	v_mfma_f32_16x16x128_f8f6f4 v[14:17], v[150:157], v[174:181], v[130:133]
	v_mfma_f32_16x16x128_f8f6f4 v[6:9], v[142:149], v[182:189], v[66:69]
	v_mfma_f32_16x16x128_f8f6f4 v[2:5], v[150:157], v[182:189], v[190:193]
	s_setprio 0
	s_add_i32 s79, s79, 2
	s_addk_i32 s7, 0x1000
	s_addk_i32 s78, 0x100
	s_cmp_gt_u32 s79, 5
	s_barrier
.LBB0_840:
	ds_read_b128 v[142:145], v137
	ds_read_b128 v[146:149], v137 offset:1024
	ds_read_b128 v[150:153], v137 offset:2048
	ds_read_b128 v[154:157], v137 offset:3072
	s_add_i32 s10, s7, 0xfffd0800
	s_cmp_eq_u32 s79, 4
	s_cselect_b32 s87, s6, s10
	s_cselect_b32 s86, s58, s78
	s_or_b32 s88, s87, 0x800
	s_add_i32 s10, s7, 0xffff0000
	s_mov_b32 m0, s39
	ds_read_b128 v[158:161], v138
	ds_read_b128 v[162:165], v138 offset:1024
	ds_read_b128 v[166:169], v138 offset:2048
	ds_read_b128 v[170:173], v138 offset:3072
	ds_read_b128 v[174:177], v138 offset:4096
	ds_read_b128 v[178:181], v138 offset:5120
	ds_read_b128 v[182:185], v138 offset:6144
	ds_read_b128 v[186:189], v138 offset:7168
	buffer_load_dwordx4 v1, s[44:47], s10 offen lds
	s_mov_b32 m0, s41
	s_nop 0
	buffer_load_dwordx4 v1, s[44:47], s7 offen lds
	s_waitcnt lgkmcnt(8)
	s_barrier
	s_waitcnt lgkmcnt(0)
	s_setprio 1
	s_waitcnt lgkmcnt(4)
	v_mfma_f32_16x16x128_f8f6f4 v[114:117], v[142:149], v[166:173], v[114:117]
	v_mfma_f32_16x16x128_f8f6f4 v[106:109], v[150:157], v[166:173], v[106:109]
	s_waitcnt lgkmcnt(2)
	v_mfma_f32_16x16x128_f8f6f4 v[98:101], v[142:149], v[174:181], v[98:101]
	v_mfma_f32_16x16x128_f8f6f4 v[198:201], v[142:149], v[158:165], v[126:129]
	v_mfma_f32_16x16x128_f8f6f4 v[202:205], v[150:157], v[158:165], v[122:125]
	v_mfma_f32_16x16x128_f8f6f4 v[206:209], v[150:157], v[174:181], v[90:93]
	s_waitcnt lgkmcnt(0)
	v_mfma_f32_16x16x128_f8f6f4 v[210:213], v[142:149], v[182:189], v[82:85]
	v_mfma_f32_16x16x128_f8f6f4 v[214:217], v[150:157], v[182:189], v[74:77]
	s_setprio 0
	s_barrier
	s_mov_b32 m0, s23
	s_mov_b32 s10, s46
	s_mov_b32 s11, s47
	ds_read_b128 v[122:125], v139
	ds_read_b128 v[126:129], v139 offset:1024
	ds_read_b128 v[190:193], v139 offset:2048
	ds_read_b128 v[194:197], v139 offset:3072
	buffer_load_dwordx4 v134, s[8:11], s86 offen lds
	s_add_i32 s33, s86, 0x20000
	s_mov_b32 m0, s24
	s_nop 0
	buffer_load_dwordx4 v134, s[8:11], s33 offen lds
	s_barrier
	s_waitcnt lgkmcnt(0)
	s_setprio 1
	s_waitcnt lgkmcnt(2)
	v_mfma_f32_16x16x128_f8f6f4 v[118:121], v[122:129], v[158:165], v[118:121]
	s_waitcnt lgkmcnt(0)
	v_mfma_f32_16x16x128_f8f6f4 v[110:113], v[190:197], v[158:165], v[110:113]
	v_mfma_f32_16x16x128_f8f6f4 v[102:105], v[122:129], v[166:173], v[102:105]
	v_mfma_f32_16x16x128_f8f6f4 v[158:161], v[190:197], v[166:173], v[94:97]
	v_mfma_f32_16x16x128_f8f6f4 v[162:165], v[122:129], v[174:181], v[86:89]
	v_mfma_f32_16x16x128_f8f6f4 v[166:169], v[190:197], v[174:181], v[78:81]
	v_mfma_f32_16x16x128_f8f6f4 v[170:173], v[122:129], v[182:189], v[70:73]
	v_mfma_f32_16x16x128_f8f6f4 v[174:177], v[190:197], v[182:189], v[18:21]
	s_setprio 0
	s_mov_b32 m0, s22
	s_barrier
	ds_read_b128 v[66:69], v138 offset:16384
	s_nop 1
	ds_read_b128 v[70:73], v138 offset:17408
	ds_read_b128 v[74:77], v138 offset:18432
	ds_read_b128 v[78:81], v138 offset:19456
	ds_read_b128 v[82:85], v138 offset:20480
	ds_read_b128 v[86:89], v138 offset:21504
	ds_read_b128 v[90:93], v138 offset:22528
	ds_read_b128 v[94:97], v138 offset:23552
	buffer_load_dwordx4 v1, s[44:47], s87 offen lds
	s_add_i32 s33, s87, 0x10000
	s_mov_b32 m0, s25
	s_nop 0
	buffer_load_dwordx4 v1, s[44:47], s33 offen lds
	s_barrier
	s_waitcnt lgkmcnt(0)
	s_setprio 1
	s_waitcnt lgkmcnt(6)
	v_mfma_f32_16x16x128_f8f6f4 v[62:65], v[142:149], v[66:73], v[62:65]
	v_mfma_f32_16x16x128_f8f6f4 v[58:61], v[150:157], v[66:73], v[58:61]
	s_waitcnt lgkmcnt(4)
	v_mfma_f32_16x16x128_f8f6f4 v[50:53], v[142:149], v[74:81], v[50:53]
	s_waitcnt lgkmcnt(0)
	v_mfma_f32_16x16x128_f8f6f4 v[230:233], v[142:149], v[90:97], v[230:233]
	v_mfma_f32_16x16x128_f8f6f4 v[218:221], v[150:157], v[74:81], v[42:45]
	v_mfma_f32_16x16x128_f8f6f4 v[222:225], v[142:149], v[82:89], v[34:37]
	v_mfma_f32_16x16x128_f8f6f4 v[226:229], v[150:157], v[82:89], v[26:29]
	v_mfma_f32_16x16x128_f8f6f4 v[234:237], v[150:157], v[90:97], v[10:13]
	s_setprio 0
	s_barrier
	s_mov_b32 m0, s26
	s_add_i32 s33, s86, 0x2000
	buffer_load_dwordx4 v134, s[8:11], s33 offen lds
	s_add_i32 s33, s86, 0x22000
	s_mov_b32 m0, s27
	s_nop 0
	buffer_load_dwordx4 v134, s[8:11], s33 offen lds
	s_cmp_eq_u32 s100, 0
	s_cbranch_scc1 .Lfw_4_a
	s_waitcnt vmcnt(16)
	s_mov_b32 s100, 0
	s_branch .Lfw_4_b

.Lfw_4_b:
	s_barrier
	s_setprio 1
	v_mfma_f32_16x16x128_f8f6f4 v[54:57], v[122:129], v[66:73], v[54:57]
	v_mfma_f32_16x16x128_f8f6f4 v[238:241], v[190:197], v[66:73], v[46:49]
	v_mfma_f32_16x16x128_f8f6f4 v[242:245], v[122:129], v[74:81], v[38:41]
	v_mfma_f32_16x16x128_f8f6f4 v[246:249], v[190:197], v[74:81], v[30:33]
	v_mfma_f32_16x16x128_f8f6f4 v[250:253], v[122:129], v[82:89], v[22:25]
	v_mfma_f32_16x16x128_f8f6f4 v[130:133], v[190:197], v[82:89], v[14:17]
	v_mfma_f32_16x16x128_f8f6f4 v[66:69], v[122:129], v[90:97], v[6:9]
	v_mfma_f32_16x16x128_f8f6f4 v[190:193], v[190:197], v[90:97], v[2:5]
	s_setprio 0
	s_barrier
	s_nop 4
	ds_read_b128 v[2:5], v140
	ds_read_b128 v[6:9], v140 offset:1024
	ds_read_b128 v[10:13], v140 offset:2048
	ds_read_b128 v[14:17], v140 offset:3072
	s_mov_b32 m0, s28
	s_add_i32 s33, s87, 0x20000
	ds_read_b128 v[18:21], v138 offset:32768
	ds_read_b128 v[22:25], v138 offset:33792
	ds_read_b128 v[26:29], v138 offset:34816
	ds_read_b128 v[30:33], v138 offset:35840
	ds_read_b128 v[34:37], v138 offset:36864
	ds_read_b128 v[38:41], v138 offset:37888
	ds_read_b128 v[42:45], v138 offset:38912
	ds_read_b128 v[46:49], v138 offset:39936
	buffer_load_dwordx4 v1, s[44:47], s33 offen lds
	s_add_i32 s33, s87, 0x30000
	s_mov_b32 m0, s29
	s_nop 0
	buffer_load_dwordx4 v1, s[44:47], s33 offen lds
	s_waitcnt lgkmcnt(8)
	s_barrier
	s_waitcnt lgkmcnt(0)
	s_setprio 1
	s_waitcnt lgkmcnt(6)
	v_mfma_f32_16x16x128_f8f6f4 v[126:129], v[2:9], v[18:25], v[198:201]
	v_mfma_f32_16x16x128_f8f6f4 v[122:125], v[10:17], v[18:25], v[202:205]
	s_waitcnt lgkmcnt(4)
	v_mfma_f32_16x16x128_f8f6f4 v[114:117], v[2:9], v[26:33], v[114:117]
	v_mfma_f32_16x16x128_f8f6f4 v[106:109], v[10:17], v[26:33], v[106:109]
	s_waitcnt lgkmcnt(2)
	v_mfma_f32_16x16x128_f8f6f4 v[98:101], v[2:9], v[34:41], v[98:101]
	v_mfma_f32_16x16x128_f8f6f4 v[90:93], v[10:17], v[34:41], v[206:209]
	s_waitcnt lgkmcnt(0)
	v_mfma_f32_16x16x128_f8f6f4 v[82:85], v[2:9], v[42:49], v[210:213]
	v_mfma_f32_16x16x128_f8f6f4 v[74:77], v[10:17], v[42:49], v[214:217]
	s_setprio 0
	s_barrier
	s_mov_b32 m0, s31
	s_add_i32 s33, s86, 0x80
	ds_read_b128 v[142:145], v141
	ds_read_b128 v[146:149], v141 offset:1024
	ds_read_b128 v[150:153], v141 offset:2048
	ds_read_b128 v[154:157], v141 offset:3072
	buffer_load_dwordx4 v134, s[8:11], s33 offen lds
	s_add_i32 s33, s86, 0x20080
	s_mov_b32 m0, s34
	s_nop 0
	buffer_load_dwordx4 v134, s[8:11], s33 offen lds
	s_waitcnt vmcnt(10)
	s_barrier
	s_waitcnt lgkmcnt(0)
	s_setprio 1
	s_waitcnt lgkmcnt(2)
	v_mfma_f32_16x16x128_f8f6f4 v[118:121], v[142:149], v[18:25], v[118:121]
	s_waitcnt lgkmcnt(0)
	v_mfma_f32_16x16x128_f8f6f4 v[110:113], v[150:157], v[18:25], v[110:113]
	v_mfma_f32_16x16x128_f8f6f4 v[102:105], v[142:149], v[26:33], v[102:105]
	v_mfma_f32_16x16x128_f8f6f4 v[94:97], v[150:157], v[26:33], v[158:161]
	v_mfma_f32_16x16x128_f8f6f4 v[86:89], v[142:149], v[34:41], v[162:165]
	v_mfma_f32_16x16x128_f8f6f4 v[78:81], v[150:157], v[34:41], v[166:169]
	v_mfma_f32_16x16x128_f8f6f4 v[70:73], v[142:149], v[42:49], v[170:173]
	v_mfma_f32_16x16x128_f8f6f4 v[18:21], v[150:157], v[42:49], v[174:177]
	s_setprio 0
	s_mov_b32 m0, s35
	s_barrier
	ds_read_b128 v[158:161], v138 offset:49152
	ds_read_b128 v[162:165], v138 offset:50176
	ds_read_b128 v[166:169], v138 offset:51200
	ds_read_b128 v[170:173], v138 offset:52224
	ds_read_b128 v[174:177], v138 offset:53248
	ds_read_b128 v[178:181], v138 offset:54272
	ds_read_b128 v[182:185], v138 offset:55296
	ds_read_b128 v[186:189], v138 offset:56320
	buffer_load_dwordx4 v1, s[44:47], s88 offen lds
	s_add_i32 s87, s87, 0x10800
	s_mov_b32 m0, s36
	s_nop 0
	buffer_load_dwordx4 v1, s[44:47], s87 offen lds
	s_barrier
	s_waitcnt lgkmcnt(0)
	s_setprio 1
	s_waitcnt lgkmcnt(6)
	v_mfma_f32_16x16x128_f8f6f4 v[62:65], v[2:9], v[158:165], v[62:65]
	v_mfma_f32_16x16x128_f8f6f4 v[58:61], v[10:17], v[158:165], v[58:61]
	s_waitcnt lgkmcnt(4)
	v_mfma_f32_16x16x128_f8f6f4 v[50:53], v[2:9], v[166:173], v[50:53]
	v_mfma_f32_16x16x128_f8f6f4 v[42:45], v[10:17], v[166:173], v[218:221]
	s_waitcnt lgkmcnt(2)
	v_mfma_f32_16x16x128_f8f6f4 v[34:37], v[2:9], v[174:181], v[222:225]
	v_mfma_f32_16x16x128_f8f6f4 v[26:29], v[10:17], v[174:181], v[226:229]
	s_waitcnt lgkmcnt(0)
	v_mfma_f32_16x16x128_f8f6f4 v[230:233], v[2:9], v[182:189], v[230:233]
	v_mfma_f32_16x16x128_f8f6f4 v[10:13], v[10:17], v[182:189], v[234:237]
	s_setprio 0
	s_barrier
	s_mov_b32 m0, s37
	s_add_i32 s33, s86, 0x2080
	buffer_load_dwordx4 v134, s[8:11], s33 offen lds
	s_add_i32 s86, s86, 0x22080
	s_mov_b32 m0, s38
	s_nop 0
	buffer_load_dwordx4 v134, s[8:11], s86 offen lds
	s_waitcnt vmcnt(6)
	s_barrier
	s_setprio 1
	v_mfma_f32_16x16x128_f8f6f4 v[54:57], v[142:149], v[158:165], v[54:57]
	v_mfma_f32_16x16x128_f8f6f4 v[46:49], v[150:157], v[158:165], v[238:241]
	v_mfma_f32_16x16x128_f8f6f4 v[38:41], v[142:149], v[166:173], v[242:245]
	v_mfma_f32_16x16x128_f8f6f4 v[30:33], v[150:157], v[166:173], v[246:249]
	v_mfma_f32_16x16x128_f8f6f4 v[22:25], v[142:149], v[174:181], v[250:253]
	v_mfma_f32_16x16x128_f8f6f4 v[14:17], v[150:157], v[174:181], v[130:133]
	v_mfma_f32_16x16x128_f8f6f4 v[6:9], v[142:149], v[182:189], v[66:69]
	v_mfma_f32_16x16x128_f8f6f4 v[2:5], v[150:157], v[182:189], v[190:193]
	s_setprio 0
	s_add_i32 s79, s79, 2
	s_addk_i32 s7, 0x1000
	s_addk_i32 s78, 0x100
	s_cmp_gt_u32 s79, 5
	s_barrier
	s_cbranch_scc0 .LBB0_840
	v_lshl_add_u32 v152, s73, 8, v135
	v_lshlrev_b32_e32 v153, 1, v136
	v_lshl_or_b32 v153, s72, 8, v153
	v_lshl_add_u32 v152, v152, 10, v153
	s_mov_b32 s72, s51
	s_mov_b32 s73, s57
	s_mov_b32 s78, s58
	s_mov_b32 s79, s59
	v_pk_mul_f32 v[126:127], v[126:127], 0.5 op_sel_hi:[1,0]
	v_pk_mul_f32 v[128:129], v[128:129], 0.5 op_sel_hi:[1,0]
	v_pk_mul_f32 v[122:123], v[122:123], 0.5 op_sel_hi:[1,0]
	v_pk_mul_f32 v[124:125], v[124:125], 0.5 op_sel_hi:[1,0]
	v_pk_mul_f32 v[118:119], v[118:119], 0.5 op_sel_hi:[1,0]
	v_pk_mul_f32 v[120:121], v[120:121], 0.5 op_sel_hi:[1,0]
	v_pk_mul_f32 v[110:111], v[110:111], 0.5 op_sel_hi:[1,0]
	v_pk_mul_f32 v[112:113], v[112:113], 0.5 op_sel_hi:[1,0]
	v_cvt_pk_fp8_f32 v144, v126, v127
	v_cvt_pk_fp8_f32 v145, v122, v123
	v_cvt_pk_fp8_f32 v146, v118, v119
	v_cvt_pk_fp8_f32 v147, v110, v111
	v_cvt_pk_fp8_f32 v144, v128, v129 op_sel:[0,0,1]
	v_cvt_pk_fp8_f32 v145, v124, v125 op_sel:[0,0,1]
	v_cvt_pk_fp8_f32 v146, v120, v121 op_sel:[0,0,1]
	v_cvt_pk_fp8_f32 v147, v112, v113 op_sel:[0,0,1]
	v_mov_b32_e32 v154, v152
	s_nop 0
	global_store_dwordx4 v154, v[144:147], s[68:69]
	s_mov_b32 s100, 1
	v_pk_mul_f32 v[114:115], v[114:115], 0.5 op_sel_hi:[1,0]
	v_pk_mul_f32 v[116:117], v[116:117], 0.5 op_sel_hi:[1,0]
	v_pk_mul_f32 v[106:107], v[106:107], 0.5 op_sel_hi:[1,0]
	v_pk_mul_f32 v[108:109], v[108:109], 0.5 op_sel_hi:[1,0]
	v_pk_mul_f32 v[102:103], v[102:103], 0.5 op_sel_hi:[1,0]
	v_pk_mul_f32 v[104:105], v[104:105], 0.5 op_sel_hi:[1,0]
	v_pk_mul_f32 v[94:95], v[94:95], 0.5 op_sel_hi:[1,0]
	v_pk_mul_f32 v[96:97], v[96:97], 0.5 op_sel_hi:[1,0]
	v_cvt_pk_fp8_f32 v148, v114, v115
	v_cvt_pk_fp8_f32 v149, v106, v107
	v_cvt_pk_fp8_f32 v150, v102, v103
	v_cvt_pk_fp8_f32 v151, v94, v95
	v_cvt_pk_fp8_f32 v148, v116, v117 op_sel:[0,0,1]
	v_cvt_pk_fp8_f32 v149, v108, v109 op_sel:[0,0,1]
	v_cvt_pk_fp8_f32 v150, v104, v105 op_sel:[0,0,1]
	v_cvt_pk_fp8_f32 v151, v96, v97 op_sel:[0,0,1]
	v_add_u32_e32 v155, 0x4000, v152
	s_nop 0
	global_store_dwordx4 v155, v[148:151], s[68:69]
	s_mov_b32 s100, 1
	v_pk_mul_f32 v[98:99], v[98:99], 0.5 op_sel_hi:[1,0]
	v_pk_mul_f32 v[100:101], v[100:101], 0.5 op_sel_hi:[1,0]
	v_pk_mul_f32 v[90:91], v[90:91], 0.5 op_sel_hi:[1,0]
	v_pk_mul_f32 v[92:93], v[92:93], 0.5 op_sel_hi:[1,0]
	v_pk_mul_f32 v[86:87], v[86:87], 0.5 op_sel_hi:[1,0]
	v_pk_mul_f32 v[88:89], v[88:89], 0.5 op_sel_hi:[1,0]
	v_pk_mul_f32 v[78:79], v[78:79], 0.5 op_sel_hi:[1,0]
	v_pk_mul_f32 v[80:81], v[80:81], 0.5 op_sel_hi:[1,0]
	v_cvt_pk_fp8_f32 v144, v98, v99
	v_cvt_pk_fp8_f32 v145, v90, v91
	v_cvt_pk_fp8_f32 v146, v86, v87
	v_cvt_pk_fp8_f32 v147, v78, v79
	v_cvt_pk_fp8_f32 v144, v100, v101 op_sel:[0,0,1]
	v_cvt_pk_fp8_f32 v145, v92, v93 op_sel:[0,0,1]
	v_cvt_pk_fp8_f32 v146, v88, v89 op_sel:[0,0,1]
	v_cvt_pk_fp8_f32 v147, v80, v81 op_sel:[0,0,1]
	v_add_u32_e32 v154, 0x8000, v152
	s_nop 0
	global_store_dwordx4 v154, v[144:147], s[68:69]
	s_mov_b32 s100, 1
	v_pk_mul_f32 v[82:83], v[82:83], 0.5 op_sel_hi:[1,0]
	v_pk_mul_f32 v[84:85], v[84:85], 0.5 op_sel_hi:[1,0]
	v_pk_mul_f32 v[74:75], v[74:75], 0.5 op_sel_hi:[1,0]
	v_pk_mul_f32 v[76:77], v[76:77], 0.5 op_sel_hi:[1,0]
	v_pk_mul_f32 v[70:71], v[70:71], 0.5 op_sel_hi:[1,0]
	v_pk_mul_f32 v[72:73], v[72:73], 0.5 op_sel_hi:[1,0]
	v_pk_mul_f32 v[18:19], v[18:19], 0.5 op_sel_hi:[1,0]
	v_pk_mul_f32 v[20:21], v[20:21], 0.5 op_sel_hi:[1,0]
	v_cvt_pk_fp8_f32 v148, v82, v83
	v_cvt_pk_fp8_f32 v149, v74, v75
	v_cvt_pk_fp8_f32 v150, v70, v71
	v_cvt_pk_fp8_f32 v151, v18, v19
	v_cvt_pk_fp8_f32 v148, v84, v85 op_sel:[0,0,1]
	v_cvt_pk_fp8_f32 v149, v76, v77 op_sel:[0,0,1]
	v_cvt_pk_fp8_f32 v150, v72, v73 op_sel:[0,0,1]
	v_cvt_pk_fp8_f32 v151, v20, v21 op_sel:[0,0,1]
	v_add_u32_e32 v155, 0xc000, v152
	s_nop 0
	global_store_dwordx4 v155, v[148:151], s[68:69]
	s_mov_b32 s100, 1
	v_pk_mul_f32 v[62:63], v[62:63], 0.5 op_sel_hi:[1,0]
	v_pk_mul_f32 v[64:65], v[64:65], 0.5 op_sel_hi:[1,0]
	v_pk_mul_f32 v[58:59], v[58:59], 0.5 op_sel_hi:[1,0]
	v_pk_mul_f32 v[60:61], v[60:61], 0.5 op_sel_hi:[1,0]
	v_pk_mul_f32 v[54:55], v[54:55], 0.5 op_sel_hi:[1,0]
	v_pk_mul_f32 v[56:57], v[56:57], 0.5 op_sel_hi:[1,0]
	v_pk_mul_f32 v[46:47], v[46:47], 0.5 op_sel_hi:[1,0]
	v_pk_mul_f32 v[48:49], v[48:49], 0.5 op_sel_hi:[1,0]
	v_cvt_pk_fp8_f32 v144, v62, v63
	v_cvt_pk_fp8_f32 v145, v58, v59
	v_cvt_pk_fp8_f32 v146, v54, v55
	v_cvt_pk_fp8_f32 v147, v46, v47
	v_cvt_pk_fp8_f32 v144, v64, v65 op_sel:[0,0,1]
	v_cvt_pk_fp8_f32 v145, v60, v61 op_sel:[0,0,1]
	v_cvt_pk_fp8_f32 v146, v56, v57 op_sel:[0,0,1]
	v_cvt_pk_fp8_f32 v147, v48, v49 op_sel:[0,0,1]
	v_add_u32_e32 v154, 0x20000, v152
	s_nop 0
	global_store_dwordx4 v154, v[144:147], s[68:69]
	s_mov_b32 s100, 1
	v_pk_mul_f32 v[50:51], v[50:51], 0.5 op_sel_hi:[1,0]
	v_pk_mul_f32 v[52:53], v[52:53], 0.5 op_sel_hi:[1,0]
	v_pk_mul_f32 v[42:43], v[42:43], 0.5 op_sel_hi:[1,0]
	v_pk_mul_f32 v[44:45], v[44:45], 0.5 op_sel_hi:[1,0]
	v_pk_mul_f32 v[38:39], v[38:39], 0.5 op_sel_hi:[1,0]
	v_pk_mul_f32 v[40:41], v[40:41], 0.5 op_sel_hi:[1,0]
	v_pk_mul_f32 v[30:31], v[30:31], 0.5 op_sel_hi:[1,0]
	v_pk_mul_f32 v[32:33], v[32:33], 0.5 op_sel_hi:[1,0]
	v_cvt_pk_fp8_f32 v148, v50, v51
	v_cvt_pk_fp8_f32 v149, v42, v43
	v_cvt_pk_fp8_f32 v150, v38, v39
	v_cvt_pk_fp8_f32 v151, v30, v31
	v_cvt_pk_fp8_f32 v148, v52, v53 op_sel:[0,0,1]
	v_cvt_pk_fp8_f32 v149, v44, v45 op_sel:[0,0,1]
	v_cvt_pk_fp8_f32 v150, v40, v41 op_sel:[0,0,1]
	v_cvt_pk_fp8_f32 v151, v32, v33 op_sel:[0,0,1]
	v_add_u32_e32 v155, 0x24000, v152
	s_nop 0
	global_store_dwordx4 v155, v[148:151], s[68:69]
	s_mov_b32 s100, 1
	v_pk_mul_f32 v[34:35], v[34:35], 0.5 op_sel_hi:[1,0]
	v_pk_mul_f32 v[36:37], v[36:37], 0.5 op_sel_hi:[1,0]
	v_pk_mul_f32 v[26:27], v[26:27], 0.5 op_sel_hi:[1,0]
	v_pk_mul_f32 v[28:29], v[28:29], 0.5 op_sel_hi:[1,0]
	v_pk_mul_f32 v[22:23], v[22:23], 0.5 op_sel_hi:[1,0]
	v_pk_mul_f32 v[24:25], v[24:25], 0.5 op_sel_hi:[1,0]
	v_pk_mul_f32 v[14:15], v[14:15], 0.5 op_sel_hi:[1,0]
	v_pk_mul_f32 v[16:17], v[16:17], 0.5 op_sel_hi:[1,0]
	v_cvt_pk_fp8_f32 v144, v34, v35
	v_cvt_pk_fp8_f32 v145, v26, v27
	v_cvt_pk_fp8_f32 v146, v22, v23
	v_cvt_pk_fp8_f32 v147, v14, v15
	v_cvt_pk_fp8_f32 v144, v36, v37 op_sel:[0,0,1]
	v_cvt_pk_fp8_f32 v145, v28, v29 op_sel:[0,0,1]
	v_cvt_pk_fp8_f32 v146, v24, v25 op_sel:[0,0,1]
	v_cvt_pk_fp8_f32 v147, v16, v17 op_sel:[0,0,1]
	v_add_u32_e32 v154, 0x28000, v152
	s_nop 0
	global_store_dwordx4 v154, v[144:147], s[68:69]
	s_mov_b32 s100, 1
	v_pk_mul_f32 v[230:231], v[230:231], 0.5 op_sel_hi:[1,0]
	v_pk_mul_f32 v[232:233], v[232:233], 0.5 op_sel_hi:[1,0]
	v_pk_mul_f32 v[10:11], v[10:11], 0.5 op_sel_hi:[1,0]
	v_pk_mul_f32 v[12:13], v[12:13], 0.5 op_sel_hi:[1,0]
	v_pk_mul_f32 v[6:7], v[6:7], 0.5 op_sel_hi:[1,0]
	v_pk_mul_f32 v[8:9], v[8:9], 0.5 op_sel_hi:[1,0]
	v_pk_mul_f32 v[2:3], v[2:3], 0.5 op_sel_hi:[1,0]
	v_pk_mul_f32 v[4:5], v[4:5], 0.5 op_sel_hi:[1,0]
	v_cvt_pk_fp8_f32 v148, v230, v231
	v_cvt_pk_fp8_f32 v149, v10, v11
	v_cvt_pk_fp8_f32 v150, v6, v7
	v_cvt_pk_fp8_f32 v151, v2, v3
	v_cvt_pk_fp8_f32 v148, v232, v233 op_sel:[0,0,1]
	v_cvt_pk_fp8_f32 v149, v12, v13 op_sel:[0,0,1]
	v_cvt_pk_fp8_f32 v150, v8, v9 op_sel:[0,0,1]
	v_cvt_pk_fp8_f32 v151, v4, v5 op_sel:[0,0,1]
	v_add_u32_e32 v155, 0x2c000, v152
	s_nop 0
	global_store_dwordx4 v155, v[148:151], s[68:69]
	s_mov_b32 s100, 1
	s_and_b64 vcc, exec, s[4:5]
	s_cbranch_vccz .LBB0_835
	s_waitcnt vmcnt(0)
	s_cmpk_gt_u32 s3, 0xff
	s_cbranch_scc1 .LBB0_844
	s_barrier

.LBB0_1650:
	v_mov_b32_e32 v218, 0xbd38aa3b
	v_mov_b32_e32 v219, 0xbd38aa3b
	v_mov_b32_e32 v220, 0x44800000
	v_mov_b32_e32 v221, 0x44800000
	v_lshrrev_b32_e32 v224, 4, v187
	v_lshl_add_u32 v224, s49, 4, v224
	v_lshlrev_b32_e32 v222, 14, v224
	v_lshrrev_b32_e32 v224, 5, v188
	v_lshl_add_u32 v224, s47, 2, v224
	v_lshl_add_u32 v222, v224, 9, v222
	v_and_b32_e32 v224, 15, v187
	v_lshl_add_u32 v222, v224, 5, v222
	v_and_b32_e32 v224, 31, v188
	v_add_u32_e32 v222, v222, v224
	s_mov_b32 s47, s39
	s_mov_b32 s49, s45
	s_mov_b32 s57, s46
	v_pk_mul_f32 v[226:227], v[174:175], v[218:219]
	v_pk_mul_f32 v[228:229], v[176:177], v[218:219]
	v_pk_mul_f32 v[230:231], v[166:167], v[218:219]
	v_pk_mul_f32 v[232:233], v[168:169], v[218:219]
	v_exp_f32_e32 v226, v226
	v_exp_f32_e32 v227, v227
	v_exp_f32_e32 v228, v228
	v_exp_f32_e32 v229, v229
	v_exp_f32_e32 v230, v230
	v_exp_f32_e32 v231, v231
	v_exp_f32_e32 v232, v232
	v_exp_f32_e32 v233, v233
	v_pk_fma_f32 v[226:227], v[226:227], v[220:221], v[220:221]
	v_pk_fma_f32 v[228:229], v[228:229], v[220:221], v[220:221]
	v_pk_fma_f32 v[230:231], v[230:231], v[220:221], v[220:221]
	v_pk_fma_f32 v[232:233], v[232:233], v[220:221], v[220:221]
	v_rcp_f32_e32 v226, v226
	v_rcp_f32_e32 v227, v227
	v_rcp_f32_e32 v228, v228
	v_rcp_f32_e32 v229, v229
	v_rcp_f32_e32 v230, v230
	v_rcp_f32_e32 v231, v231
	v_rcp_f32_e32 v232, v232
	v_rcp_f32_e32 v233, v233
	v_pk_mul_f32 v[174:175], v[174:175], v[170:171]
	v_pk_mul_f32 v[176:177], v[176:177], v[172:173]
	v_pk_mul_f32 v[166:167], v[166:167], v[162:163]
	v_pk_mul_f32 v[168:169], v[168:169], v[164:165]
	v_pk_mul_f32 v[174:175], v[174:175], v[226:227]
	v_pk_mul_f32 v[176:177], v[176:177], v[228:229]
	v_pk_mul_f32 v[166:167], v[166:167], v[230:231]
	v_pk_mul_f32 v[168:169], v[168:169], v[232:233]
	v_mov_b32_e32 v223, v222
	v_cvt_pk_fp8_f32 v234, v174, v175
	v_cvt_pk_fp8_f32 v235, v166, v167
	v_cvt_pk_fp8_f32 v234, v176, v177 op_sel:[0,0,1]
	v_cvt_pk_fp8_f32 v235, v168, v169 op_sel:[0,0,1]
	s_nop 0
	global_store_dwordx2 v223, v[234:235], s[70:71]
	s_mov_b32 s100, 1
	v_pk_mul_f32 v[226:227], v[158:159], v[218:219]
	v_pk_mul_f32 v[228:229], v[160:161], v[218:219]
	v_pk_mul_f32 v[230:231], v[150:151], v[218:219]
	v_pk_mul_f32 v[232:233], v[152:153], v[218:219]
	v_exp_f32_e32 v226, v226
	v_exp_f32_e32 v227, v227
	v_exp_f32_e32 v228, v228
	v_exp_f32_e32 v229, v229
	v_exp_f32_e32 v230, v230
	v_exp_f32_e32 v231, v231
	v_exp_f32_e32 v232, v232
	v_exp_f32_e32 v233, v233
	v_pk_fma_f32 v[226:227], v[226:227], v[220:221], v[220:221]
	v_pk_fma_f32 v[228:229], v[228:229], v[220:221], v[220:221]
	v_pk_fma_f32 v[230:231], v[230:231], v[220:221], v[220:221]
	v_pk_fma_f32 v[232:233], v[232:233], v[220:221], v[220:221]
	v_rcp_f32_e32 v226, v226
	v_rcp_f32_e32 v227, v227
	v_rcp_f32_e32 v228, v228
	v_rcp_f32_e32 v229, v229
	v_rcp_f32_e32 v230, v230
	v_rcp_f32_e32 v231, v231
	v_rcp_f32_e32 v232, v232
	v_rcp_f32_e32 v233, v233
	v_pk_mul_f32 v[158:159], v[158:159], v[154:155]
	v_pk_mul_f32 v[160:161], v[160:161], v[156:157]
	v_pk_mul_f32 v[150:151], v[150:151], v[146:147]
	v_pk_mul_f32 v[152:153], v[152:153], v[148:149]
	v_pk_mul_f32 v[158:159], v[158:159], v[226:227]
	v_pk_mul_f32 v[160:161], v[160:161], v[228:229]
	v_pk_mul_f32 v[150:151], v[150:151], v[230:231]
	v_pk_mul_f32 v[152:153], v[152:153], v[232:233]
	v_add_u32_e32 v225, 0x4000, v222
	v_cvt_pk_fp8_f32 v236, v158, v159
	v_cvt_pk_fp8_f32 v237, v150, v151
	v_cvt_pk_fp8_f32 v236, v160, v161 op_sel:[0,0,1]
	v_cvt_pk_fp8_f32 v237, v152, v153 op_sel:[0,0,1]
	s_nop 0
	global_store_dwordx2 v225, v[236:237], s[70:71]
	s_mov_b32 s100, 1
	v_pk_mul_f32 v[226:227], v[142:143], v[218:219]
	v_pk_mul_f32 v[228:229], v[144:145], v[218:219]
	v_pk_mul_f32 v[230:231], v[134:135], v[218:219]
	v_pk_mul_f32 v[232:233], v[136:137], v[218:219]
	v_exp_f32_e32 v226, v226
	v_exp_f32_e32 v227, v227
	v_exp_f32_e32 v228, v228
	v_exp_f32_e32 v229, v229
	v_exp_f32_e32 v230, v230
	v_exp_f32_e32 v231, v231
	v_exp_f32_e32 v232, v232
	v_exp_f32_e32 v233, v233
	v_pk_fma_f32 v[226:227], v[226:227], v[220:221], v[220:221]
	v_pk_fma_f32 v[228:229], v[228:229], v[220:221], v[220:221]
	v_pk_fma_f32 v[230:231], v[230:231], v[220:221], v[220:221]
	v_pk_fma_f32 v[232:233], v[232:233], v[220:221], v[220:221]
	v_rcp_f32_e32 v226, v226
	v_rcp_f32_e32 v227, v227
	v_rcp_f32_e32 v228, v228
	v_rcp_f32_e32 v229, v229
	v_rcp_f32_e32 v230, v230
	v_rcp_f32_e32 v231, v231
	v_rcp_f32_e32 v232, v232
	v_rcp_f32_e32 v233, v233
	v_pk_mul_f32 v[142:143], v[142:143], v[138:139]
	v_pk_mul_f32 v[144:145], v[144:145], v[140:141]
	v_pk_mul_f32 v[134:135], v[134:135], v[130:131]
	v_pk_mul_f32 v[136:137], v[136:137], v[132:133]
	v_pk_mul_f32 v[142:143], v[142:143], v[226:227]
	v_pk_mul_f32 v[144:145], v[144:145], v[228:229]
	v_pk_mul_f32 v[134:135], v[134:135], v[230:231]
	v_pk_mul_f32 v[136:137], v[136:137], v[232:233]
	v_add_u32_e32 v223, 0x8000, v222
	v_cvt_pk_fp8_f32 v234, v142, v143
	v_cvt_pk_fp8_f32 v235, v134, v135
	v_cvt_pk_fp8_f32 v234, v144, v145 op_sel:[0,0,1]
	v_cvt_pk_fp8_f32 v235, v136, v137 op_sel:[0,0,1]
	s_nop 0
	global_store_dwordx2 v223, v[234:235], s[70:71]
	s_mov_b32 s100, 1
	v_pk_mul_f32 v[226:227], v[126:127], v[218:219]
	v_pk_mul_f32 v[228:229], v[128:129], v[218:219]
	v_pk_mul_f32 v[230:231], v[118:119], v[218:219]
	v_pk_mul_f32 v[232:233], v[120:121], v[218:219]
	v_exp_f32_e32 v226, v226
	v_exp_f32_e32 v227, v227
	v_exp_f32_e32 v228, v228
	v_exp_f32_e32 v229, v229
	v_exp_f32_e32 v230, v230
	v_exp_f32_e32 v231, v231
	v_exp_f32_e32 v232, v232
	v_exp_f32_e32 v233, v233
	v_pk_fma_f32 v[226:227], v[226:227], v[220:221], v[220:221]
	v_pk_fma_f32 v[228:229], v[228:229], v[220:221], v[220:221]
	v_pk_fma_f32 v[230:231], v[230:231], v[220:221], v[220:221]
	v_pk_fma_f32 v[232:233], v[232:233], v[220:221], v[220:221]
	v_rcp_f32_e32 v226, v226
	v_rcp_f32_e32 v227, v227
	v_rcp_f32_e32 v228, v228
	v_rcp_f32_e32 v229, v229
	v_rcp_f32_e32 v230, v230
	v_rcp_f32_e32 v231, v231
	v_rcp_f32_e32 v232, v232
	v_rcp_f32_e32 v233, v233
	v_pk_mul_f32 v[126:127], v[126:127], v[122:123]
	v_pk_mul_f32 v[128:129], v[128:129], v[124:125]
	v_pk_mul_f32 v[118:119], v[118:119], v[114:115]
	v_pk_mul_f32 v[120:121], v[120:121], v[116:117]
	v_pk_mul_f32 v[126:127], v[126:127], v[226:227]
	v_pk_mul_f32 v[128:129], v[128:129], v[228:229]
	v_pk_mul_f32 v[118:119], v[118:119], v[230:231]
	v_pk_mul_f32 v[120:121], v[120:121], v[232:233]
	v_add_u32_e32 v225, 0xc000, v222
	v_cvt_pk_fp8_f32 v236, v126, v127
	v_cvt_pk_fp8_f32 v237, v118, v119
	v_cvt_pk_fp8_f32 v236, v128, v129 op_sel:[0,0,1]
	v_cvt_pk_fp8_f32 v237, v120, v121 op_sel:[0,0,1]
	s_nop 0
	global_store_dwordx2 v225, v[236:237], s[70:71]
	s_mov_b32 s100, 1
	v_pk_mul_f32 v[226:227], v[110:111], v[218:219]
	v_pk_mul_f32 v[228:229], v[112:113], v[218:219]
	v_pk_mul_f32 v[230:231], v[102:103], v[218:219]
	v_pk_mul_f32 v[232:233], v[104:105], v[218:219]
	v_exp_f32_e32 v226, v226
	v_exp_f32_e32 v227, v227
	v_exp_f32_e32 v228, v228
	v_exp_f32_e32 v229, v229
	v_exp_f32_e32 v230, v230
	v_exp_f32_e32 v231, v231
	v_exp_f32_e32 v232, v232
	v_exp_f32_e32 v233, v233
	v_pk_fma_f32 v[226:227], v[226:227], v[220:221], v[220:221]
	v_pk_fma_f32 v[228:229], v[228:229], v[220:221], v[220:221]
	v_pk_fma_f32 v[230:231], v[230:231], v[220:221], v[220:221]
	v_pk_fma_f32 v[232:233], v[232:233], v[220:221], v[220:221]
	v_rcp_f32_e32 v226, v226
	v_rcp_f32_e32 v227, v227
	v_rcp_f32_e32 v228, v228
	v_rcp_f32_e32 v229, v229
	v_rcp_f32_e32 v230, v230
	v_rcp_f32_e32 v231, v231
	v_rcp_f32_e32 v232, v232
	v_rcp_f32_e32 v233, v233
	v_pk_mul_f32 v[110:111], v[110:111], v[106:107]
	v_pk_mul_f32 v[112:113], v[112:113], v[108:109]
	v_pk_mul_f32 v[102:103], v[102:103], v[98:99]
	v_pk_mul_f32 v[104:105], v[104:105], v[100:101]
	v_pk_mul_f32 v[110:111], v[110:111], v[226:227]
	v_pk_mul_f32 v[112:113], v[112:113], v[228:229]
	v_pk_mul_f32 v[102:103], v[102:103], v[230:231]
	v_pk_mul_f32 v[104:105], v[104:105], v[232:233]
	v_add_u32_e32 v223, 0x20000, v222
	v_cvt_pk_fp8_f32 v234, v110, v111
	v_cvt_pk_fp8_f32 v235, v102, v103
	v_cvt_pk_fp8_f32 v234, v112, v113 op_sel:[0,0,1]
	v_cvt_pk_fp8_f32 v235, v104, v105 op_sel:[0,0,1]
	s_nop 0
	global_store_dwordx2 v223, v[234:235], s[70:71]
	s_mov_b32 s100, 1
	v_pk_mul_f32 v[226:227], v[94:95], v[218:219]
	v_pk_mul_f32 v[228:229], v[96:97], v[218:219]
	v_pk_mul_f32 v[230:231], v[86:87], v[218:219]
	v_pk_mul_f32 v[232:233], v[88:89], v[218:219]
	v_exp_f32_e32 v226, v226
	v_exp_f32_e32 v227, v227
	v_exp_f32_e32 v228, v228
	v_exp_f32_e32 v229, v229
	v_exp_f32_e32 v230, v230
	v_exp_f32_e32 v231, v231
	v_exp_f32_e32 v232, v232
	v_exp_f32_e32 v233, v233
	v_pk_fma_f32 v[226:227], v[226:227], v[220:221], v[220:221]
	v_pk_fma_f32 v[228:229], v[228:229], v[220:221], v[220:221]
	v_pk_fma_f32 v[230:231], v[230:231], v[220:221], v[220:221]
	v_pk_fma_f32 v[232:233], v[232:233], v[220:221], v[220:221]
	v_rcp_f32_e32 v226, v226
	v_rcp_f32_e32 v227, v227
	v_rcp_f32_e32 v228, v228
	v_rcp_f32_e32 v229, v229
	v_rcp_f32_e32 v230, v230
	v_rcp_f32_e32 v231, v231
	v_rcp_f32_e32 v232, v232
	v_rcp_f32_e32 v233, v233
	v_pk_mul_f32 v[94:95], v[94:95], v[90:91]
	v_pk_mul_f32 v[96:97], v[96:97], v[92:93]
	v_pk_mul_f32 v[86:87], v[86:87], v[82:83]
	v_pk_mul_f32 v[88:89], v[88:89], v[84:85]
	v_pk_mul_f32 v[94:95], v[94:95], v[226:227]
	v_pk_mul_f32 v[96:97], v[96:97], v[228:229]
	v_pk_mul_f32 v[86:87], v[86:87], v[230:231]
	v_pk_mul_f32 v[88:89], v[88:89], v[232:233]
	v_add_u32_e32 v225, 0x24000, v222
	v_cvt_pk_fp8_f32 v236, v94, v95
	v_cvt_pk_fp8_f32 v237, v86, v87
	v_cvt_pk_fp8_f32 v236, v96, v97 op_sel:[0,0,1]
	v_cvt_pk_fp8_f32 v237, v88, v89 op_sel:[0,0,1]
	s_nop 0
	global_store_dwordx2 v225, v[236:237], s[70:71]
	s_mov_b32 s100, 1
	v_pk_mul_f32 v[226:227], v[78:79], v[218:219]
	v_pk_mul_f32 v[228:229], v[80:81], v[218:219]
	v_pk_mul_f32 v[230:231], v[70:71], v[218:219]
	v_pk_mul_f32 v[232:233], v[72:73], v[218:219]
	v_exp_f32_e32 v226, v226
	v_exp_f32_e32 v227, v227
	v_exp_f32_e32 v228, v228
	v_exp_f32_e32 v229, v229
	v_exp_f32_e32 v230, v230
	v_exp_f32_e32 v231, v231
	v_exp_f32_e32 v232, v232
	v_exp_f32_e32 v233, v233
	v_pk_fma_f32 v[226:227], v[226:227], v[220:221], v[220:221]
	v_pk_fma_f32 v[228:229], v[228:229], v[220:221], v[220:221]
	v_pk_fma_f32 v[230:231], v[230:231], v[220:221], v[220:221]
	v_pk_fma_f32 v[232:233], v[232:233], v[220:221], v[220:221]
	v_rcp_f32_e32 v226, v226
	v_rcp_f32_e32 v227, v227
	v_rcp_f32_e32 v228, v228
	v_rcp_f32_e32 v229, v229
	v_rcp_f32_e32 v230, v230
	v_rcp_f32_e32 v231, v231
	v_rcp_f32_e32 v232, v232
	v_rcp_f32_e32 v233, v233
	v_pk_mul_f32 v[78:79], v[78:79], v[74:75]
	v_pk_mul_f32 v[80:81], v[80:81], v[76:77]
	v_pk_mul_f32 v[70:71], v[70:71], v[66:67]
	v_pk_mul_f32 v[72:73], v[72:73], v[68:69]
	v_pk_mul_f32 v[78:79], v[78:79], v[226:227]
	v_pk_mul_f32 v[80:81], v[80:81], v[228:229]
	v_pk_mul_f32 v[70:71], v[70:71], v[230:231]
	v_pk_mul_f32 v[72:73], v[72:73], v[232:233]
	v_add_u32_e32 v223, 0x28000, v222
	v_cvt_pk_fp8_f32 v234, v78, v79
	v_cvt_pk_fp8_f32 v235, v70, v71
	v_cvt_pk_fp8_f32 v234, v80, v81 op_sel:[0,0,1]
	v_cvt_pk_fp8_f32 v235, v72, v73 op_sel:[0,0,1]
	s_nop 0
	global_store_dwordx2 v223, v[234:235], s[70:71]
	s_mov_b32 s100, 1
	v_pk_mul_f32 v[226:227], v[62:63], v[218:219]
	v_pk_mul_f32 v[228:229], v[64:65], v[218:219]
	v_pk_mul_f32 v[230:231], v[54:55], v[218:219]
	v_pk_mul_f32 v[232:233], v[56:57], v[218:219]
	v_exp_f32_e32 v226, v226
	v_exp_f32_e32 v227, v227
	v_exp_f32_e32 v228, v228
	v_exp_f32_e32 v229, v229
	v_exp_f32_e32 v230, v230
	v_exp_f32_e32 v231, v231
	v_exp_f32_e32 v232, v232
	v_exp_f32_e32 v233, v233
	v_pk_fma_f32 v[226:227], v[226:227], v[220:221], v[220:221]
	v_pk_fma_f32 v[228:229], v[228:229], v[220:221], v[220:221]
	v_pk_fma_f32 v[230:231], v[230:231], v[220:221], v[220:221]
	v_pk_fma_f32 v[232:233], v[232:233], v[220:221], v[220:221]
	v_rcp_f32_e32 v226, v226
	v_rcp_f32_e32 v227, v227
	v_rcp_f32_e32 v228, v228
	v_rcp_f32_e32 v229, v229
	v_rcp_f32_e32 v230, v230
	v_rcp_f32_e32 v231, v231
	v_rcp_f32_e32 v232, v232
	v_rcp_f32_e32 v233, v233
	v_pk_mul_f32 v[62:63], v[62:63], v[58:59]
	v_pk_mul_f32 v[64:65], v[64:65], v[60:61]
	v_pk_mul_f32 v[54:55], v[54:55], v[50:51]
	v_pk_mul_f32 v[56:57], v[56:57], v[52:53]
	v_pk_mul_f32 v[62:63], v[62:63], v[226:227]
	v_pk_mul_f32 v[64:65], v[64:65], v[228:229]
	v_pk_mul_f32 v[54:55], v[54:55], v[230:231]
	v_pk_mul_f32 v[56:57], v[56:57], v[232:233]
	v_add_u32_e32 v225, 0x2c000, v222
	v_cvt_pk_fp8_f32 v236, v62, v63
	v_cvt_pk_fp8_f32 v237, v54, v55
	v_cvt_pk_fp8_f32 v236, v64, v65 op_sel:[0,0,1]
	v_cvt_pk_fp8_f32 v237, v56, v57 op_sel:[0,0,1]
	s_nop 0
	global_store_dwordx2 v225, v[236:237], s[70:71]
	s_mov_b32 s100, 1
	s_and_b64 vcc, exec, s[4:5]
	s_cbranch_vccnz .LBB0_1661

.LBB0_1714:
	s_cmp_gt_i32 s60, 22
	s_cselect_b64 s[4:5], -1, 0
	s_cmp_lt_i32 s61, 23
	s_cselect_b64 s[6:7], -1, 0
	s_or_b64 s[4:5], s[4:5], s[6:7]
	s_and_b64 vcc, exec, s[4:5]
	s_cbranch_vccnz .LBB0_1779
	s_waitcnt vmcnt(0)
	v_mov_b32_e32 v2, v0
	s_cmpk_gt_i32 s2, 0x43f
	v_readfirstlane_b32 s3, v2
	s_cbranch_scc1 .LBB0_1729
	v_bfe_i32 v4, v2, 27, 1
	v_lshlrev_b32_e32 v1, 4, v2
	v_lshrrev_b32_e32 v4, 22, v4
	v_add_u32_e32 v4, v1, v4
	v_and_b32_e32 v4, 0xfffffc00, v4
	v_sub_u32_e32 v1, v1, v4
	v_ashrrev_i32_e32 v3, 31, v2
	v_lshrrev_b32_e32 v4, 4, v1
	v_lshrrev_b32_e32 v3, 26, v3
	v_bitop3_b32 v1, v4, v1, 32 bitop3:0x6c
	s_add_u32 s8, s52, 0x7b00000
	v_add_u32_e32 v3, v2, v3
	v_ashrrev_i32_e32 v5, 31, v1
	s_addc_u32 s6, s53, 0
	v_ashrrev_i32_e32 v3, 6, v3
	v_lshrrev_b32_e32 v5, 26, v5
	s_ashr_i32 s20, s2, 31
	v_lshlrev_b32_e32 v4, 3, v3
	v_add_u32_e32 v5, v1, v5
	s_lshr_b32 s7, s20, 29
	v_and_b32_e32 v4, -16, v4
	v_ashrrev_i32_e32 v6, 6, v5
	s_add_i32 s7, s2, s7
	s_ashr_i32 s4, s3, 6
	v_add_u32_e32 v4, v6, v4
	v_and_b32_e32 v6, 3, v6
	s_mov_b32 s5, 0x3fffe0
	s_ashr_i32 s12, s7, 3
	s_and_b32 s7, s7, -8
	s_and_b32 s45, s71, 0xffff
	v_and_or_b32 v6, v4, s5, v6
	s_ashr_i32 s5, s3, 8
	s_and_b32 s9, s6, 0xffff
	s_lshl_b32 s6, s4, 10
	s_sub_i32 s7, s2, s7
	s_cmp_lt_i32 s7, 0
	s_movk_i32 s21, 0x89
	s_cselect_b32 s13, s21, 0x88
	s_mul_i32 s7, s13, s7
	s_add_i32 s7, s7, s12
	s_ashr_i32 s12, s7, 31
	s_lshr_b32 s12, s12, 27
	s_add_i32 s12, s7, s12
	s_ashr_i32 s13, s12, 5
	s_andn2_b32 s12, s12, 31
	s_sub_i32 s7, s7, s12
	s_bfe_i32 s12, s7, 0x80000
	s_bfe_u32 s12, s12, 0x3000c
	s_add_i32 s12, s7, s12
	s_bfe_i32 s14, s12, 0x80000
	s_and_b32 s12, s12, 0xf8
	s_sub_i32 s7, s7, s12
	s_lshl_b32 s13, s13, 3
	s_sext_i32_i8 s7, s7
	v_and_b32_e32 v5, 0xc0, v5
	s_add_i32 s79, s13, s7
	v_sub_u32_e32 v1, v1, v5
	v_mov_b32_e32 v5, 1
	s_mul_hi_i32 s7, s79, 0x78787879
	v_lshlrev_b32_e32 v3, 5, v3
	v_ashrrev_i16_sdwa v1, v5, sext(v1) dst_sel:DWORD dst_unused:UNUSED_PAD src0_sel:DWORD src1_sel:BYTE_0
	v_lshlrev_b32_e32 v5, 1, v4
	v_lshrrev_b32_e32 v7, 2, v4
	s_sext_i32_i16 s14, s14
	s_lshr_b32 s12, s7, 31
	s_lshr_b32 s7, s7, 3
	v_and_b32_e32 v3, 32, v3
	v_bfe_i32 v1, v1, 0, 16
	v_and_b32_e32 v5, 24, v5
	v_and_b32_e32 v7, 4, v7
	s_ashr_i32 s78, s14, 3
	s_add_i32 s7, s7, s12
	s_add_i32 s22, s6, 0
	s_mov_b32 s47, 0x20000
	s_brev_b32 s46, -2
	v_or3_b32 v5, v6, v7, v5
	v_add_lshl_u32 v3, v3, v1, 1
	s_lshl_b32 s7, s7, 20
	s_lshl_b32 s12, s78, 18
	s_add_i32 s23, s22, 0x10000
	v_and_b32_e32 v254, 3, v4
	v_lshrrev_b32_e32 v5, 2, v4
	v_and_b32_e32 v5, 4, v5
	v_or_b32_e32 v254, v254, v5
	v_lshlrev_b32_e32 v5, 2, v4
	v_and_b32_e32 v5, 0x30, v5
	v_or_b32_e32 v254, v254, v5
	v_lshlrev_b32_e32 v5, 1, v4
	v_and_b32_e32 v5, 0x40, v5
	v_or_b32_e32 v254, v254, v5
	v_lshl_add_u32 v134, v254, 10, v3
	s_mov_b32 s10, s46
	s_mov_b32 s11, s47
	s_add_i32 s84, s7, s12
	s_mov_b32 m0, s23
	s_add_i32 s24, s22, 0x12000
	s_mov_b32 s100, 0
	buffer_load_dwordx4 v134, s[8:11], s84 offen lds
	s_or_b32 s6, s84, 0x20000
	s_mov_b32 m0, s24
	v_lshrrev_b32_e32 v254, 4, v4
	v_lshlrev_b32_e32 v1, 14, v254
	v_lshrrev_b32_e32 v254, 5, v3
	v_lshl_add_u32 v1, v254, 9, v1
	v_and_b32_e32 v254, 15, v4
	v_lshl_add_u32 v1, v254, 5, v1
	v_and_b32_e32 v254, 31, v3
	v_add_u32_e32 v1, v1, v254
	buffer_load_dwordx4 v134, s[8:11], s6 offen lds
	s_lshl_b32 s85, s79, 18
	s_mov_b32 m0, s22
	s_add_i32 s25, s22, 0x2000
	buffer_load_dwordx4 v1, s[44:47], s85 offen lds
	s_or_b32 s6, s85, 0x10000
	s_mov_b32 m0, s25
	s_add_i32 s26, s22, 0x14000
	buffer_load_dwordx4 v1, s[44:47], s6 offen lds
	s_or_b32 s6, s84, 0x2000
	s_mov_b32 m0, s26
	s_add_i32 s27, s22, 0x16000
	buffer_load_dwordx4 v134, s[8:11], s6 offen lds
	s_or_b32 s6, s84, 0x22000
	s_mov_b32 m0, s27
	s_add_i32 s28, s22, 0x4000
	buffer_load_dwordx4 v134, s[8:11], s6 offen lds
	s_or_b32 s6, s85, 0x20000
	s_mov_b32 m0, s28
	s_add_i32 s29, s22, 0x6000
	buffer_load_dwordx4 v1, s[44:47], s6 offen lds
	s_or_b32 s6, s85, 0x30000
	s_mov_b32 m0, s29
	s_cmp_lg_u32 s5, 1
	buffer_load_dwordx4 v1, s[44:47], s6 offen lds
	s_mov_b32 s30, 0
	s_cbranch_scc1 .LBB0_1718
	s_barrier
.LBB0_1718:
	s_add_i32 s31, s22, 0x18000
	s_or_b32 s6, s84, 0x80
	s_mov_b32 s10, s46
	s_mov_b32 s11, s47
	s_mov_b32 m0, s31
	s_add_i32 s34, s22, 0x1a000
	s_waitcnt vmcnt(4)
	s_barrier
	buffer_load_dwordx4 v134, s[8:11], s6 offen lds
	s_or_b32 s6, s84, 0x20080
	s_mov_b32 m0, s34
	s_add_i32 s35, s22, 0x8000
	buffer_load_dwordx4 v134, s[8:11], s6 offen lds
	s_or_b32 s6, s85, 0x800
	s_mov_b32 m0, s35
	s_add_i32 s36, s22, 0xa000
	buffer_load_dwordx4 v1, s[44:47], s6 offen lds
	s_or_b32 s6, s85, 0x10800
	s_mov_b32 m0, s36
	s_add_i32 s37, s22, 0x1c000
	buffer_load_dwordx4 v1, s[44:47], s6 offen lds
	s_or_b32 s6, s84, 0x2080
	s_mov_b32 m0, s37
	s_add_i32 s38, s22, 0x1e000
	buffer_load_dwordx4 v134, s[8:11], s6 offen lds
	s_or_b32 s6, s84, 0x22080
	s_mov_b32 m0, s38
	v_and_b32_e32 v3, 15, v2
	buffer_load_dwordx4 v134, s[8:11], s6 offen lds
	v_lshrrev_b32_e32 v4, 1, v2
	s_and_b32 s4, s4, 3
	v_and_b32_e32 v4, 24, v4
	v_lshlrev_b32_e32 v5, 6, v3
	v_lshlrev_b32_e32 v2, 2, v2
	v_lshl_or_b32 v5, v4, 1, v5
	v_and_b32_e32 v2, 32, v2
	s_lshl_b32 s6, s5, 13
	s_lshl_b32 s7, s4, 12
	v_bitop3_b32 v6, v5, s6, v2 bitop3:0xde
	v_bitop3_b32 v2, v5, s7, v2 bitop3:0xde
	s_waitcnt vmcnt(6)
	v_add_u32_e32 v2, 0, v2
	s_add_i32 s39, s22, 0xc000
	v_lshl_or_b32 v135, s5, 6, v3
	s_add_i32 s41, s22, 0xe000
	s_ashr_i32 s42, s56, 31
	v_lshl_or_b32 v136, s4, 5, v4
	v_add_u32_e32 v137, 0x10000, v2
	v_add_u32_e32 v138, 0, v6
	v_add_u32_e32 v139, 0x14000, v2
	v_add_u32_e32 v140, 0x18000, v2
	v_add_u32_e32 v141, 0x1c000, v2
	s_mov_b64 s[12:13], 0x20000
	s_mov_b64 s[14:15], 0x24000
	s_mov_b32 s43, 0x24000
	s_mov_b64 s[16:17], 0x28000
	s_mov_b32 s49, 0x28000
	s_mov_b64 s[18:19], 0x2c000
	s_mov_b32 s57, 0x2c000
	s_barrier

.LBB0_1723:
	s_lshl_b32 s73, s59, 18
	s_and_b64 s[6:7], s[6:7], exec
	v_mov_b32_e32 v2, 0
	s_cselect_b32 s6, s73, s85
	s_add_i32 s7, s85, 0x30800
	s_addk_i32 s84, 0x100
	s_mov_b32 s85, -2
	ds_read_b128 v[142:145], v137
	ds_read_b128 v[146:149], v137 offset:1024
	ds_read_b128 v[150:153], v137 offset:2048
	ds_read_b128 v[154:157], v137 offset:3072
	s_add_i32 s10, s7, 0xfffd0800
	s_cmp_eq_u32 s85, 4
	s_cselect_b32 s87, s6, s10
	s_cselect_b32 s86, s72, s84
	s_or_b32 s88, s87, 0x800
	s_add_i32 s10, s7, 0xffff0000
	s_mov_b32 m0, s39
	ds_read_b128 v[158:161], v138
	ds_read_b128 v[162:165], v138 offset:1024
	ds_read_b128 v[166:169], v138 offset:2048
	ds_read_b128 v[170:173], v138 offset:3072
	ds_read_b128 v[174:177], v138 offset:4096
	ds_read_b128 v[178:181], v138 offset:5120
	ds_read_b128 v[182:185], v138 offset:6144
	ds_read_b128 v[186:189], v138 offset:7168
	buffer_load_dwordx4 v1, s[44:47], s10 offen lds
	s_mov_b32 m0, s41
	s_nop 0
	buffer_load_dwordx4 v1, s[44:47], s7 offen lds
	s_waitcnt lgkmcnt(8)
	s_barrier
	s_waitcnt lgkmcnt(0)
	s_setprio 1
	s_waitcnt lgkmcnt(4)
	v_mfma_f32_16x16x128_f8f6f4 v[114:117], v[142:149], v[166:173], 0
	v_mfma_f32_16x16x128_f8f6f4 v[106:109], v[150:157], v[166:173], 0
	s_waitcnt lgkmcnt(2)
	v_mfma_f32_16x16x128_f8f6f4 v[98:101], v[142:149], v[174:181], 0
	v_mfma_f32_16x16x128_f8f6f4 v[198:201], v[142:149], v[158:165], 0
	v_mfma_f32_16x16x128_f8f6f4 v[202:205], v[150:157], v[158:165], 0
	v_mfma_f32_16x16x128_f8f6f4 v[206:209], v[150:157], v[174:181], 0
	s_waitcnt lgkmcnt(0)
	v_mfma_f32_16x16x128_f8f6f4 v[210:213], v[142:149], v[182:189], 0
	v_mfma_f32_16x16x128_f8f6f4 v[214:217], v[150:157], v[182:189], 0
	s_setprio 0
	s_barrier
	s_mov_b32 m0, s23
	s_mov_b32 s10, s46
	s_mov_b32 s11, s47
	ds_read_b128 v[122:125], v139
	ds_read_b128 v[126:129], v139 offset:1024
	ds_read_b128 v[190:193], v139 offset:2048
	ds_read_b128 v[194:197], v139 offset:3072
	buffer_load_dwordx4 v134, s[8:11], s86 offen lds
	s_add_i32 s33, s86, 0x20000
	s_mov_b32 m0, s24
	s_nop 0
	buffer_load_dwordx4 v134, s[8:11], s33 offen lds
	s_barrier
	s_waitcnt lgkmcnt(0)
	s_setprio 1
	s_waitcnt lgkmcnt(2)
	v_mfma_f32_16x16x128_f8f6f4 v[118:121], v[122:129], v[158:165], 0
	s_waitcnt lgkmcnt(0)
	v_mfma_f32_16x16x128_f8f6f4 v[110:113], v[190:197], v[158:165], 0
	v_mfma_f32_16x16x128_f8f6f4 v[102:105], v[122:129], v[166:173], 0
	v_mfma_f32_16x16x128_f8f6f4 v[158:161], v[190:197], v[166:173], 0
	v_mfma_f32_16x16x128_f8f6f4 v[162:165], v[122:129], v[174:181], 0
	v_mfma_f32_16x16x128_f8f6f4 v[166:169], v[190:197], v[174:181], 0
	v_mfma_f32_16x16x128_f8f6f4 v[170:173], v[122:129], v[182:189], 0
	v_mfma_f32_16x16x128_f8f6f4 v[174:177], v[190:197], v[182:189], 0
	s_setprio 0
	s_mov_b32 m0, s22
	s_barrier
	ds_read_b128 v[66:69], v138 offset:16384
	s_nop 1
	ds_read_b128 v[70:73], v138 offset:17408
	ds_read_b128 v[74:77], v138 offset:18432
	ds_read_b128 v[78:81], v138 offset:19456
	ds_read_b128 v[82:85], v138 offset:20480
	ds_read_b128 v[86:89], v138 offset:21504
	ds_read_b128 v[90:93], v138 offset:22528
	ds_read_b128 v[94:97], v138 offset:23552
	buffer_load_dwordx4 v1, s[44:47], s87 offen lds
	s_add_i32 s33, s87, 0x10000
	s_mov_b32 m0, s25
	s_nop 0
	buffer_load_dwordx4 v1, s[44:47], s33 offen lds
	s_barrier
	s_waitcnt lgkmcnt(0)
	s_setprio 1
	s_waitcnt lgkmcnt(6)
	v_mfma_f32_16x16x128_f8f6f4 v[62:65], v[142:149], v[66:73], 0
	v_mfma_f32_16x16x128_f8f6f4 v[58:61], v[150:157], v[66:73], 0
	s_waitcnt lgkmcnt(4)
	v_mfma_f32_16x16x128_f8f6f4 v[50:53], v[142:149], v[74:81], 0
	s_waitcnt lgkmcnt(0)
	v_mfma_f32_16x16x128_f8f6f4 v[230:233], v[142:149], v[90:97], 0
	v_mfma_f32_16x16x128_f8f6f4 v[218:221], v[150:157], v[74:81], 0
	v_mfma_f32_16x16x128_f8f6f4 v[222:225], v[142:149], v[82:89], 0
	v_mfma_f32_16x16x128_f8f6f4 v[226:229], v[150:157], v[82:89], 0
	v_mfma_f32_16x16x128_f8f6f4 v[234:237], v[150:157], v[90:97], 0
	s_setprio 0
	s_barrier
	s_mov_b32 m0, s26
	s_add_i32 s33, s86, 0x2000
	buffer_load_dwordx4 v134, s[8:11], s33 offen lds
	s_add_i32 s33, s86, 0x22000
	s_mov_b32 m0, s27
	s_nop 0
	buffer_load_dwordx4 v134, s[8:11], s33 offen lds
	s_cmp_eq_u32 s100, 0
	s_cbranch_scc1 .Lfw_8_a_p
	s_waitcnt vmcnt(16)
	s_mov_b32 s100, 0
	s_branch .Lfw_8_b_p

.Lfw_8_b_p:
	s_barrier
	s_setprio 1
	v_mfma_f32_16x16x128_f8f6f4 v[54:57], v[122:129], v[66:73], 0
	v_mfma_f32_16x16x128_f8f6f4 v[238:241], v[190:197], v[66:73], 0
	v_mfma_f32_16x16x128_f8f6f4 v[242:245], v[122:129], v[74:81], 0
	v_mfma_f32_16x16x128_f8f6f4 v[246:249], v[190:197], v[74:81], 0
	v_mfma_f32_16x16x128_f8f6f4 v[250:253], v[122:129], v[82:89], 0
	v_mfma_f32_16x16x128_f8f6f4 v[130:133], v[190:197], v[82:89], 0
	v_mfma_f32_16x16x128_f8f6f4 v[66:69], v[122:129], v[90:97], 0
	v_mfma_f32_16x16x128_f8f6f4 v[190:193], v[190:197], v[90:97], 0
	s_setprio 0
	s_barrier
	s_nop 4
	ds_read_b128 v[2:5], v140
	ds_read_b128 v[6:9], v140 offset:1024
	ds_read_b128 v[10:13], v140 offset:2048
	ds_read_b128 v[14:17], v140 offset:3072
	s_mov_b32 m0, s28
	s_add_i32 s33, s87, 0x20000
	ds_read_b128 v[18:21], v138 offset:32768
	ds_read_b128 v[22:25], v138 offset:33792
	ds_read_b128 v[26:29], v138 offset:34816
	ds_read_b128 v[30:33], v138 offset:35840
	ds_read_b128 v[34:37], v138 offset:36864
	ds_read_b128 v[38:41], v138 offset:37888
	ds_read_b128 v[42:45], v138 offset:38912
	ds_read_b128 v[46:49], v138 offset:39936
	buffer_load_dwordx4 v1, s[44:47], s33 offen lds
	s_add_i32 s33, s87, 0x30000
	s_mov_b32 m0, s29
	s_nop 0
	buffer_load_dwordx4 v1, s[44:47], s33 offen lds
	s_waitcnt lgkmcnt(8)
	s_barrier
	s_waitcnt lgkmcnt(0)
	s_setprio 1
	s_waitcnt lgkmcnt(6)
	v_mfma_f32_16x16x128_f8f6f4 v[126:129], v[2:9], v[18:25], v[198:201]
	v_mfma_f32_16x16x128_f8f6f4 v[122:125], v[10:17], v[18:25], v[202:205]
	s_waitcnt lgkmcnt(4)
	v_mfma_f32_16x16x128_f8f6f4 v[114:117], v[2:9], v[26:33], v[114:117]
	v_mfma_f32_16x16x128_f8f6f4 v[106:109], v[10:17], v[26:33], v[106:109]
	s_waitcnt lgkmcnt(2)
	v_mfma_f32_16x16x128_f8f6f4 v[98:101], v[2:9], v[34:41], v[98:101]
	v_mfma_f32_16x16x128_f8f6f4 v[90:93], v[10:17], v[34:41], v[206:209]
	s_waitcnt lgkmcnt(0)
	v_mfma_f32_16x16x128_f8f6f4 v[82:85], v[2:9], v[42:49], v[210:213]
	v_mfma_f32_16x16x128_f8f6f4 v[74:77], v[10:17], v[42:49], v[214:217]
	s_setprio 0
	s_barrier
	s_mov_b32 m0, s31
	s_add_i32 s33, s86, 0x80
	ds_read_b128 v[142:145], v141
	ds_read_b128 v[146:149], v141 offset:1024
	ds_read_b128 v[150:153], v141 offset:2048
	ds_read_b128 v[154:157], v141 offset:3072
	buffer_load_dwordx4 v134, s[8:11], s33 offen lds
	s_add_i32 s33, s86, 0x20080
	s_mov_b32 m0, s34
	s_nop 0
	buffer_load_dwordx4 v134, s[8:11], s33 offen lds
	s_waitcnt vmcnt(10)
	s_barrier
	s_waitcnt lgkmcnt(0)
	s_setprio 1
	s_waitcnt lgkmcnt(2)
	v_mfma_f32_16x16x128_f8f6f4 v[118:121], v[142:149], v[18:25], v[118:121]
	s_waitcnt lgkmcnt(0)
	v_mfma_f32_16x16x128_f8f6f4 v[110:113], v[150:157], v[18:25], v[110:113]
	v_mfma_f32_16x16x128_f8f6f4 v[102:105], v[142:149], v[26:33], v[102:105]
	v_mfma_f32_16x16x128_f8f6f4 v[94:97], v[150:157], v[26:33], v[158:161]
	v_mfma_f32_16x16x128_f8f6f4 v[86:89], v[142:149], v[34:41], v[162:165]
	v_mfma_f32_16x16x128_f8f6f4 v[78:81], v[150:157], v[34:41], v[166:169]
	v_mfma_f32_16x16x128_f8f6f4 v[70:73], v[142:149], v[42:49], v[170:173]
	v_mfma_f32_16x16x128_f8f6f4 v[18:21], v[150:157], v[42:49], v[174:177]
	s_setprio 0
	s_mov_b32 m0, s35
	s_barrier
	ds_read_b128 v[158:161], v138 offset:49152
	ds_read_b128 v[162:165], v138 offset:50176
	ds_read_b128 v[166:169], v138 offset:51200
	ds_read_b128 v[170:173], v138 offset:52224
	ds_read_b128 v[174:177], v138 offset:53248
	ds_read_b128 v[178:181], v138 offset:54272
	ds_read_b128 v[182:185], v138 offset:55296
	ds_read_b128 v[186:189], v138 offset:56320
	buffer_load_dwordx4 v1, s[44:47], s88 offen lds
	s_add_i32 s87, s87, 0x10800
	s_mov_b32 m0, s36
	s_nop 0
	buffer_load_dwordx4 v1, s[44:47], s87 offen lds
	s_barrier
	s_waitcnt lgkmcnt(0)
	s_setprio 1
	s_waitcnt lgkmcnt(6)
	v_mfma_f32_16x16x128_f8f6f4 v[62:65], v[2:9], v[158:165], v[62:65]
	v_mfma_f32_16x16x128_f8f6f4 v[58:61], v[10:17], v[158:165], v[58:61]
	s_waitcnt lgkmcnt(4)
	v_mfma_f32_16x16x128_f8f6f4 v[50:53], v[2:9], v[166:173], v[50:53]
	v_mfma_f32_16x16x128_f8f6f4 v[42:45], v[10:17], v[166:173], v[218:221]
	s_waitcnt lgkmcnt(2)
	v_mfma_f32_16x16x128_f8f6f4 v[34:37], v[2:9], v[174:181], v[222:225]
	v_mfma_f32_16x16x128_f8f6f4 v[26:29], v[10:17], v[174:181], v[226:229]
	s_waitcnt lgkmcnt(0)
	v_mfma_f32_16x16x128_f8f6f4 v[230:233], v[2:9], v[182:189], v[230:233]
	v_mfma_f32_16x16x128_f8f6f4 v[10:13], v[10:17], v[182:189], v[234:237]
	s_setprio 0
	s_barrier
	s_mov_b32 m0, s37
	s_add_i32 s33, s86, 0x2080
	buffer_load_dwordx4 v134, s[8:11], s33 offen lds
	s_add_i32 s86, s86, 0x22080
	s_mov_b32 m0, s38
	s_nop 0
	buffer_load_dwordx4 v134, s[8:11], s86 offen lds
	s_waitcnt vmcnt(6)
	s_barrier
	s_setprio 1
	v_mfma_f32_16x16x128_f8f6f4 v[54:57], v[142:149], v[158:165], v[54:57]
	v_mfma_f32_16x16x128_f8f6f4 v[46:49], v[150:157], v[158:165], v[238:241]
	v_mfma_f32_16x16x128_f8f6f4 v[38:41], v[142:149], v[166:173], v[242:245]
	v_mfma_f32_16x16x128_f8f6f4 v[30:33], v[150:157], v[166:173], v[246:249]
	v_mfma_f32_16x16x128_f8f6f4 v[22:25], v[142:149], v[174:181], v[250:253]
	v_mfma_f32_16x16x128_f8f6f4 v[14:17], v[150:157], v[174:181], v[130:133]
	v_mfma_f32_16x16x128_f8f6f4 v[6:9], v[142:149], v[182:189], v[66:69]
	v_mfma_f32_16x16x128_f8f6f4 v[2:5], v[150:157], v[182:189], v[190:193]
	s_setprio 0
	s_add_i32 s85, s85, 2
	s_addk_i32 s7, 0x1000
	s_addk_i32 s84, 0x100
	s_cmp_gt_u32 s85, 5
	s_barrier
.LBB0_1724:
	ds_read_b128 v[142:145], v137
	ds_read_b128 v[146:149], v137 offset:1024
	ds_read_b128 v[150:153], v137 offset:2048
	ds_read_b128 v[154:157], v137 offset:3072
	s_add_i32 s10, s7, 0xfffd0800
	s_cmp_eq_u32 s85, 4
	s_cselect_b32 s87, s6, s10
	s_cselect_b32 s86, s72, s84
	s_or_b32 s88, s87, 0x800
	s_add_i32 s10, s7, 0xffff0000
	s_mov_b32 m0, s39
	ds_read_b128 v[158:161], v138
	ds_read_b128 v[162:165], v138 offset:1024
	ds_read_b128 v[166:169], v138 offset:2048
	ds_read_b128 v[170:173], v138 offset:3072
	ds_read_b128 v[174:177], v138 offset:4096
	ds_read_b128 v[178:181], v138 offset:5120
	ds_read_b128 v[182:185], v138 offset:6144
	ds_read_b128 v[186:189], v138 offset:7168
	buffer_load_dwordx4 v1, s[44:47], s10 offen lds
	s_mov_b32 m0, s41
	s_nop 0
	buffer_load_dwordx4 v1, s[44:47], s7 offen lds
	s_waitcnt lgkmcnt(8)
	s_barrier
	s_waitcnt lgkmcnt(0)
	s_setprio 1
	s_waitcnt lgkmcnt(4)
	v_mfma_f32_16x16x128_f8f6f4 v[114:117], v[142:149], v[166:173], v[114:117]
	v_mfma_f32_16x16x128_f8f6f4 v[106:109], v[150:157], v[166:173], v[106:109]
	s_waitcnt lgkmcnt(2)
	v_mfma_f32_16x16x128_f8f6f4 v[98:101], v[142:149], v[174:181], v[98:101]
	v_mfma_f32_16x16x128_f8f6f4 v[198:201], v[142:149], v[158:165], v[126:129]
	v_mfma_f32_16x16x128_f8f6f4 v[202:205], v[150:157], v[158:165], v[122:125]
	v_mfma_f32_16x16x128_f8f6f4 v[206:209], v[150:157], v[174:181], v[90:93]
	s_waitcnt lgkmcnt(0)
	v_mfma_f32_16x16x128_f8f6f4 v[210:213], v[142:149], v[182:189], v[82:85]
	v_mfma_f32_16x16x128_f8f6f4 v[214:217], v[150:157], v[182:189], v[74:77]
	s_setprio 0
	s_barrier
	s_mov_b32 m0, s23
	s_mov_b32 s10, s46
	s_mov_b32 s11, s47
	ds_read_b128 v[122:125], v139
	ds_read_b128 v[126:129], v139 offset:1024
	ds_read_b128 v[190:193], v139 offset:2048
	ds_read_b128 v[194:197], v139 offset:3072
	buffer_load_dwordx4 v134, s[8:11], s86 offen lds
	s_add_i32 s33, s86, 0x20000
	s_mov_b32 m0, s24
	s_nop 0
	buffer_load_dwordx4 v134, s[8:11], s33 offen lds
	s_barrier
	s_waitcnt lgkmcnt(0)
	s_setprio 1
	s_waitcnt lgkmcnt(2)
	v_mfma_f32_16x16x128_f8f6f4 v[118:121], v[122:129], v[158:165], v[118:121]
	s_waitcnt lgkmcnt(0)
	v_mfma_f32_16x16x128_f8f6f4 v[110:113], v[190:197], v[158:165], v[110:113]
	v_mfma_f32_16x16x128_f8f6f4 v[102:105], v[122:129], v[166:173], v[102:105]
	v_mfma_f32_16x16x128_f8f6f4 v[158:161], v[190:197], v[166:173], v[94:97]
	v_mfma_f32_16x16x128_f8f6f4 v[162:165], v[122:129], v[174:181], v[86:89]
	v_mfma_f32_16x16x128_f8f6f4 v[166:169], v[190:197], v[174:181], v[78:81]
	v_mfma_f32_16x16x128_f8f6f4 v[170:173], v[122:129], v[182:189], v[70:73]
	v_mfma_f32_16x16x128_f8f6f4 v[174:177], v[190:197], v[182:189], v[18:21]
	s_setprio 0
	s_mov_b32 m0, s22
	s_barrier
	ds_read_b128 v[66:69], v138 offset:16384
	s_nop 1
	ds_read_b128 v[70:73], v138 offset:17408
	ds_read_b128 v[74:77], v138 offset:18432
	ds_read_b128 v[78:81], v138 offset:19456
	ds_read_b128 v[82:85], v138 offset:20480
	ds_read_b128 v[86:89], v138 offset:21504
	ds_read_b128 v[90:93], v138 offset:22528
	ds_read_b128 v[94:97], v138 offset:23552
	buffer_load_dwordx4 v1, s[44:47], s87 offen lds
	s_add_i32 s33, s87, 0x10000
	s_mov_b32 m0, s25
	s_nop 0
	buffer_load_dwordx4 v1, s[44:47], s33 offen lds
	s_barrier
	s_waitcnt lgkmcnt(0)
	s_setprio 1
	s_waitcnt lgkmcnt(6)
	v_mfma_f32_16x16x128_f8f6f4 v[62:65], v[142:149], v[66:73], v[62:65]
	v_mfma_f32_16x16x128_f8f6f4 v[58:61], v[150:157], v[66:73], v[58:61]
	s_waitcnt lgkmcnt(4)
	v_mfma_f32_16x16x128_f8f6f4 v[50:53], v[142:149], v[74:81], v[50:53]
	s_waitcnt lgkmcnt(0)
	v_mfma_f32_16x16x128_f8f6f4 v[230:233], v[142:149], v[90:97], v[230:233]
	v_mfma_f32_16x16x128_f8f6f4 v[218:221], v[150:157], v[74:81], v[42:45]
	v_mfma_f32_16x16x128_f8f6f4 v[222:225], v[142:149], v[82:89], v[34:37]
	v_mfma_f32_16x16x128_f8f6f4 v[226:229], v[150:157], v[82:89], v[26:29]
	v_mfma_f32_16x16x128_f8f6f4 v[234:237], v[150:157], v[90:97], v[10:13]
	s_setprio 0
	s_barrier
	s_mov_b32 m0, s26
	s_add_i32 s33, s86, 0x2000
	buffer_load_dwordx4 v134, s[8:11], s33 offen lds
	s_add_i32 s33, s86, 0x22000
	s_mov_b32 m0, s27
	s_nop 0
	buffer_load_dwordx4 v134, s[8:11], s33 offen lds
	s_cmp_eq_u32 s100, 0
	s_cbranch_scc1 .Lfw_8_a
	s_waitcnt vmcnt(16)
	s_mov_b32 s100, 0
	s_branch .Lfw_8_b

.Lfw_8_b:
	s_barrier
	s_setprio 1
	v_mfma_f32_16x16x128_f8f6f4 v[54:57], v[122:129], v[66:73], v[54:57]
	v_mfma_f32_16x16x128_f8f6f4 v[238:241], v[190:197], v[66:73], v[46:49]
	v_mfma_f32_16x16x128_f8f6f4 v[242:245], v[122:129], v[74:81], v[38:41]
	v_mfma_f32_16x16x128_f8f6f4 v[246:249], v[190:197], v[74:81], v[30:33]
	v_mfma_f32_16x16x128_f8f6f4 v[250:253], v[122:129], v[82:89], v[22:25]
	v_mfma_f32_16x16x128_f8f6f4 v[130:133], v[190:197], v[82:89], v[14:17]
	v_mfma_f32_16x16x128_f8f6f4 v[66:69], v[122:129], v[90:97], v[6:9]
	v_mfma_f32_16x16x128_f8f6f4 v[190:193], v[190:197], v[90:97], v[2:5]
	s_setprio 0
	s_barrier
	s_nop 4
	ds_read_b128 v[2:5], v140
	ds_read_b128 v[6:9], v140 offset:1024
	ds_read_b128 v[10:13], v140 offset:2048
	ds_read_b128 v[14:17], v140 offset:3072
	s_mov_b32 m0, s28
	s_add_i32 s33, s87, 0x20000
	ds_read_b128 v[18:21], v138 offset:32768
	ds_read_b128 v[22:25], v138 offset:33792
	ds_read_b128 v[26:29], v138 offset:34816
	ds_read_b128 v[30:33], v138 offset:35840
	ds_read_b128 v[34:37], v138 offset:36864
	ds_read_b128 v[38:41], v138 offset:37888
	ds_read_b128 v[42:45], v138 offset:38912
	ds_read_b128 v[46:49], v138 offset:39936
	buffer_load_dwordx4 v1, s[44:47], s33 offen lds
	s_add_i32 s33, s87, 0x30000
	s_mov_b32 m0, s29
	s_nop 0
	buffer_load_dwordx4 v1, s[44:47], s33 offen lds
	s_waitcnt lgkmcnt(8)
	s_barrier
	s_waitcnt lgkmcnt(0)
	s_setprio 1
	s_waitcnt lgkmcnt(6)
	v_mfma_f32_16x16x128_f8f6f4 v[126:129], v[2:9], v[18:25], v[198:201]
	v_mfma_f32_16x16x128_f8f6f4 v[122:125], v[10:17], v[18:25], v[202:205]
	s_waitcnt lgkmcnt(4)
	v_mfma_f32_16x16x128_f8f6f4 v[114:117], v[2:9], v[26:33], v[114:117]
	v_mfma_f32_16x16x128_f8f6f4 v[106:109], v[10:17], v[26:33], v[106:109]
	s_waitcnt lgkmcnt(2)
	v_mfma_f32_16x16x128_f8f6f4 v[98:101], v[2:9], v[34:41], v[98:101]
	v_mfma_f32_16x16x128_f8f6f4 v[90:93], v[10:17], v[34:41], v[206:209]
	s_waitcnt lgkmcnt(0)
	v_mfma_f32_16x16x128_f8f6f4 v[82:85], v[2:9], v[42:49], v[210:213]
	v_mfma_f32_16x16x128_f8f6f4 v[74:77], v[10:17], v[42:49], v[214:217]
	s_setprio 0
	s_barrier
	s_mov_b32 m0, s31
	s_add_i32 s33, s86, 0x80
	ds_read_b128 v[142:145], v141
	ds_read_b128 v[146:149], v141 offset:1024
	ds_read_b128 v[150:153], v141 offset:2048
	ds_read_b128 v[154:157], v141 offset:3072
	buffer_load_dwordx4 v134, s[8:11], s33 offen lds
	s_add_i32 s33, s86, 0x20080
	s_mov_b32 m0, s34
	s_nop 0
	buffer_load_dwordx4 v134, s[8:11], s33 offen lds
	s_waitcnt vmcnt(10)
	s_barrier
	s_waitcnt lgkmcnt(0)
	s_setprio 1
	s_waitcnt lgkmcnt(2)
	v_mfma_f32_16x16x128_f8f6f4 v[118:121], v[142:149], v[18:25], v[118:121]
	s_waitcnt lgkmcnt(0)
	v_mfma_f32_16x16x128_f8f6f4 v[110:113], v[150:157], v[18:25], v[110:113]
	v_mfma_f32_16x16x128_f8f6f4 v[102:105], v[142:149], v[26:33], v[102:105]
	v_mfma_f32_16x16x128_f8f6f4 v[94:97], v[150:157], v[26:33], v[158:161]
	v_mfma_f32_16x16x128_f8f6f4 v[86:89], v[142:149], v[34:41], v[162:165]
	v_mfma_f32_16x16x128_f8f6f4 v[78:81], v[150:157], v[34:41], v[166:169]
	v_mfma_f32_16x16x128_f8f6f4 v[70:73], v[142:149], v[42:49], v[170:173]
	v_mfma_f32_16x16x128_f8f6f4 v[18:21], v[150:157], v[42:49], v[174:177]
	s_setprio 0
	s_mov_b32 m0, s35
	s_barrier
	ds_read_b128 v[158:161], v138 offset:49152
	ds_read_b128 v[162:165], v138 offset:50176
	ds_read_b128 v[166:169], v138 offset:51200
	ds_read_b128 v[170:173], v138 offset:52224
	ds_read_b128 v[174:177], v138 offset:53248
	ds_read_b128 v[178:181], v138 offset:54272
	ds_read_b128 v[182:185], v138 offset:55296
	ds_read_b128 v[186:189], v138 offset:56320
	buffer_load_dwordx4 v1, s[44:47], s88 offen lds
	s_add_i32 s87, s87, 0x10800
	s_mov_b32 m0, s36
	s_nop 0
	buffer_load_dwordx4 v1, s[44:47], s87 offen lds
	s_barrier
	s_waitcnt lgkmcnt(0)
	s_setprio 1
	s_waitcnt lgkmcnt(6)
	v_mfma_f32_16x16x128_f8f6f4 v[62:65], v[2:9], v[158:165], v[62:65]
	v_mfma_f32_16x16x128_f8f6f4 v[58:61], v[10:17], v[158:165], v[58:61]
	s_waitcnt lgkmcnt(4)
	v_mfma_f32_16x16x128_f8f6f4 v[50:53], v[2:9], v[166:173], v[50:53]
	v_mfma_f32_16x16x128_f8f6f4 v[42:45], v[10:17], v[166:173], v[218:221]
	s_waitcnt lgkmcnt(2)
	v_mfma_f32_16x16x128_f8f6f4 v[34:37], v[2:9], v[174:181], v[222:225]
	v_mfma_f32_16x16x128_f8f6f4 v[26:29], v[10:17], v[174:181], v[226:229]
	s_waitcnt lgkmcnt(0)
	v_mfma_f32_16x16x128_f8f6f4 v[230:233], v[2:9], v[182:189], v[230:233]
	v_mfma_f32_16x16x128_f8f6f4 v[10:13], v[10:17], v[182:189], v[234:237]
	s_setprio 0
	s_barrier
	s_mov_b32 m0, s37
	s_add_i32 s33, s86, 0x2080
	buffer_load_dwordx4 v134, s[8:11], s33 offen lds
	s_add_i32 s86, s86, 0x22080
	s_mov_b32 m0, s38
	s_nop 0
	buffer_load_dwordx4 v134, s[8:11], s86 offen lds
	s_waitcnt vmcnt(6)
	s_barrier
	s_setprio 1
	v_mfma_f32_16x16x128_f8f6f4 v[54:57], v[142:149], v[158:165], v[54:57]
	v_mfma_f32_16x16x128_f8f6f4 v[46:49], v[150:157], v[158:165], v[238:241]
	v_mfma_f32_16x16x128_f8f6f4 v[38:41], v[142:149], v[166:173], v[242:245]
	v_mfma_f32_16x16x128_f8f6f4 v[30:33], v[150:157], v[166:173], v[246:249]
	v_mfma_f32_16x16x128_f8f6f4 v[22:25], v[142:149], v[174:181], v[250:253]
	v_mfma_f32_16x16x128_f8f6f4 v[14:17], v[150:157], v[174:181], v[130:133]
	v_mfma_f32_16x16x128_f8f6f4 v[6:9], v[142:149], v[182:189], v[66:69]
	v_mfma_f32_16x16x128_f8f6f4 v[2:5], v[150:157], v[182:189], v[190:193]
	s_setprio 0
	s_add_i32 s85, s85, 2
	s_addk_i32 s7, 0x1000
	s_addk_i32 s84, 0x100
	s_cmp_gt_u32 s85, 5
	s_barrier
	s_cbranch_scc0 .LBB0_1724
	v_lshl_add_u32 v152, s79, 8, v135
	v_lshlrev_b32_e32 v153, 1, v136
	v_lshl_or_b32 v153, s78, 8, v153
	v_lshl_add_u32 v152, v152, 10, v153
	s_mov_b32 s78, s58
	s_mov_b32 s79, s59
	s_mov_b32 s84, s72
	s_mov_b32 s85, s73
	v_pk_mul_f32 v[126:127], v[126:127], 0.5 op_sel_hi:[1,0]
	v_pk_mul_f32 v[128:129], v[128:129], 0.5 op_sel_hi:[1,0]
	v_pk_mul_f32 v[122:123], v[122:123], 0.5 op_sel_hi:[1,0]
	v_pk_mul_f32 v[124:125], v[124:125], 0.5 op_sel_hi:[1,0]
	v_pk_mul_f32 v[118:119], v[118:119], 0.5 op_sel_hi:[1,0]
	v_pk_mul_f32 v[120:121], v[120:121], 0.5 op_sel_hi:[1,0]
	v_pk_mul_f32 v[110:111], v[110:111], 0.5 op_sel_hi:[1,0]
	v_pk_mul_f32 v[112:113], v[112:113], 0.5 op_sel_hi:[1,0]
	v_cvt_pk_fp8_f32 v144, v126, v127
	v_cvt_pk_fp8_f32 v145, v122, v123
	v_cvt_pk_fp8_f32 v146, v118, v119
	v_cvt_pk_fp8_f32 v147, v110, v111
	v_cvt_pk_fp8_f32 v144, v128, v129 op_sel:[0,0,1]
	v_cvt_pk_fp8_f32 v145, v124, v125 op_sel:[0,0,1]
	v_cvt_pk_fp8_f32 v146, v120, v121 op_sel:[0,0,1]
	v_cvt_pk_fp8_f32 v147, v112, v113 op_sel:[0,0,1]
	v_mov_b32_e32 v154, v152
	s_nop 0
	global_store_dwordx4 v154, v[144:147], s[68:69]
	s_mov_b32 s100, 1
	v_pk_mul_f32 v[114:115], v[114:115], 0.5 op_sel_hi:[1,0]
	v_pk_mul_f32 v[116:117], v[116:117], 0.5 op_sel_hi:[1,0]
	v_pk_mul_f32 v[106:107], v[106:107], 0.5 op_sel_hi:[1,0]
	v_pk_mul_f32 v[108:109], v[108:109], 0.5 op_sel_hi:[1,0]
	v_pk_mul_f32 v[102:103], v[102:103], 0.5 op_sel_hi:[1,0]
	v_pk_mul_f32 v[104:105], v[104:105], 0.5 op_sel_hi:[1,0]
	v_pk_mul_f32 v[94:95], v[94:95], 0.5 op_sel_hi:[1,0]
	v_pk_mul_f32 v[96:97], v[96:97], 0.5 op_sel_hi:[1,0]
	v_cvt_pk_fp8_f32 v148, v114, v115
	v_cvt_pk_fp8_f32 v149, v106, v107
	v_cvt_pk_fp8_f32 v150, v102, v103
	v_cvt_pk_fp8_f32 v151, v94, v95
	v_cvt_pk_fp8_f32 v148, v116, v117 op_sel:[0,0,1]
	v_cvt_pk_fp8_f32 v149, v108, v109 op_sel:[0,0,1]
	v_cvt_pk_fp8_f32 v150, v104, v105 op_sel:[0,0,1]
	v_cvt_pk_fp8_f32 v151, v96, v97 op_sel:[0,0,1]
	v_add_u32_e32 v155, 0x4000, v152
	s_nop 0
	global_store_dwordx4 v155, v[148:151], s[68:69]
	s_mov_b32 s100, 1
	v_pk_mul_f32 v[98:99], v[98:99], 0.5 op_sel_hi:[1,0]
	v_pk_mul_f32 v[100:101], v[100:101], 0.5 op_sel_hi:[1,0]
	v_pk_mul_f32 v[90:91], v[90:91], 0.5 op_sel_hi:[1,0]
	v_pk_mul_f32 v[92:93], v[92:93], 0.5 op_sel_hi:[1,0]
	v_pk_mul_f32 v[86:87], v[86:87], 0.5 op_sel_hi:[1,0]
	v_pk_mul_f32 v[88:89], v[88:89], 0.5 op_sel_hi:[1,0]
	v_pk_mul_f32 v[78:79], v[78:79], 0.5 op_sel_hi:[1,0]
	v_pk_mul_f32 v[80:81], v[80:81], 0.5 op_sel_hi:[1,0]
	v_cvt_pk_fp8_f32 v144, v98, v99
	v_cvt_pk_fp8_f32 v145, v90, v91
	v_cvt_pk_fp8_f32 v146, v86, v87
	v_cvt_pk_fp8_f32 v147, v78, v79
	v_cvt_pk_fp8_f32 v144, v100, v101 op_sel:[0,0,1]
	v_cvt_pk_fp8_f32 v145, v92, v93 op_sel:[0,0,1]
	v_cvt_pk_fp8_f32 v146, v88, v89 op_sel:[0,0,1]
	v_cvt_pk_fp8_f32 v147, v80, v81 op_sel:[0,0,1]
	v_add_u32_e32 v154, 0x8000, v152
	s_nop 0
	global_store_dwordx4 v154, v[144:147], s[68:69]
	s_mov_b32 s100, 1
	v_pk_mul_f32 v[82:83], v[82:83], 0.5 op_sel_hi:[1,0]
	v_pk_mul_f32 v[84:85], v[84:85], 0.5 op_sel_hi:[1,0]
	v_pk_mul_f32 v[74:75], v[74:75], 0.5 op_sel_hi:[1,0]
	v_pk_mul_f32 v[76:77], v[76:77], 0.5 op_sel_hi:[1,0]
	v_pk_mul_f32 v[70:71], v[70:71], 0.5 op_sel_hi:[1,0]
	v_pk_mul_f32 v[72:73], v[72:73], 0.5 op_sel_hi:[1,0]
	v_pk_mul_f32 v[18:19], v[18:19], 0.5 op_sel_hi:[1,0]
	v_pk_mul_f32 v[20:21], v[20:21], 0.5 op_sel_hi:[1,0]
	v_cvt_pk_fp8_f32 v148, v82, v83
	v_cvt_pk_fp8_f32 v149, v74, v75
	v_cvt_pk_fp8_f32 v150, v70, v71
	v_cvt_pk_fp8_f32 v151, v18, v19
	v_cvt_pk_fp8_f32 v148, v84, v85 op_sel:[0,0,1]
	v_cvt_pk_fp8_f32 v149, v76, v77 op_sel:[0,0,1]
	v_cvt_pk_fp8_f32 v150, v72, v73 op_sel:[0,0,1]
	v_cvt_pk_fp8_f32 v151, v20, v21 op_sel:[0,0,1]
	v_add_u32_e32 v155, 0xc000, v152
	s_nop 0
	global_store_dwordx4 v155, v[148:151], s[68:69]
	s_mov_b32 s100, 1
	v_pk_mul_f32 v[62:63], v[62:63], 0.5 op_sel_hi:[1,0]
	v_pk_mul_f32 v[64:65], v[64:65], 0.5 op_sel_hi:[1,0]
	v_pk_mul_f32 v[58:59], v[58:59], 0.5 op_sel_hi:[1,0]
	v_pk_mul_f32 v[60:61], v[60:61], 0.5 op_sel_hi:[1,0]
	v_pk_mul_f32 v[54:55], v[54:55], 0.5 op_sel_hi:[1,0]
	v_pk_mul_f32 v[56:57], v[56:57], 0.5 op_sel_hi:[1,0]
	v_pk_mul_f32 v[46:47], v[46:47], 0.5 op_sel_hi:[1,0]
	v_pk_mul_f32 v[48:49], v[48:49], 0.5 op_sel_hi:[1,0]
	v_cvt_pk_fp8_f32 v144, v62, v63
	v_cvt_pk_fp8_f32 v145, v58, v59
	v_cvt_pk_fp8_f32 v146, v54, v55
	v_cvt_pk_fp8_f32 v147, v46, v47
	v_cvt_pk_fp8_f32 v144, v64, v65 op_sel:[0,0,1]
	v_cvt_pk_fp8_f32 v145, v60, v61 op_sel:[0,0,1]
	v_cvt_pk_fp8_f32 v146, v56, v57 op_sel:[0,0,1]
	v_cvt_pk_fp8_f32 v147, v48, v49 op_sel:[0,0,1]
	v_add_u32_e32 v154, 0x20000, v152
	s_nop 0
	global_store_dwordx4 v154, v[144:147], s[68:69]
	s_mov_b32 s100, 1
	v_pk_mul_f32 v[50:51], v[50:51], 0.5 op_sel_hi:[1,0]
	v_pk_mul_f32 v[52:53], v[52:53], 0.5 op_sel_hi:[1,0]
	v_pk_mul_f32 v[42:43], v[42:43], 0.5 op_sel_hi:[1,0]
	v_pk_mul_f32 v[44:45], v[44:45], 0.5 op_sel_hi:[1,0]
	v_pk_mul_f32 v[38:39], v[38:39], 0.5 op_sel_hi:[1,0]
	v_pk_mul_f32 v[40:41], v[40:41], 0.5 op_sel_hi:[1,0]
	v_pk_mul_f32 v[30:31], v[30:31], 0.5 op_sel_hi:[1,0]
	v_pk_mul_f32 v[32:33], v[32:33], 0.5 op_sel_hi:[1,0]
	v_cvt_pk_fp8_f32 v148, v50, v51
	v_cvt_pk_fp8_f32 v149, v42, v43
	v_cvt_pk_fp8_f32 v150, v38, v39
	v_cvt_pk_fp8_f32 v151, v30, v31
	v_cvt_pk_fp8_f32 v148, v52, v53 op_sel:[0,0,1]
	v_cvt_pk_fp8_f32 v149, v44, v45 op_sel:[0,0,1]
	v_cvt_pk_fp8_f32 v150, v40, v41 op_sel:[0,0,1]
	v_cvt_pk_fp8_f32 v151, v32, v33 op_sel:[0,0,1]
	v_add_u32_e32 v155, 0x24000, v152
	s_nop 0
	global_store_dwordx4 v155, v[148:151], s[68:69]
	s_mov_b32 s100, 1
	v_pk_mul_f32 v[34:35], v[34:35], 0.5 op_sel_hi:[1,0]
	v_pk_mul_f32 v[36:37], v[36:37], 0.5 op_sel_hi:[1,0]
	v_pk_mul_f32 v[26:27], v[26:27], 0.5 op_sel_hi:[1,0]
	v_pk_mul_f32 v[28:29], v[28:29], 0.5 op_sel_hi:[1,0]
	v_pk_mul_f32 v[22:23], v[22:23], 0.5 op_sel_hi:[1,0]
	v_pk_mul_f32 v[24:25], v[24:25], 0.5 op_sel_hi:[1,0]
	v_pk_mul_f32 v[14:15], v[14:15], 0.5 op_sel_hi:[1,0]
	v_pk_mul_f32 v[16:17], v[16:17], 0.5 op_sel_hi:[1,0]
	v_cvt_pk_fp8_f32 v144, v34, v35
	v_cvt_pk_fp8_f32 v145, v26, v27
	v_cvt_pk_fp8_f32 v146, v22, v23
	v_cvt_pk_fp8_f32 v147, v14, v15
	v_cvt_pk_fp8_f32 v144, v36, v37 op_sel:[0,0,1]
	v_cvt_pk_fp8_f32 v145, v28, v29 op_sel:[0,0,1]
	v_cvt_pk_fp8_f32 v146, v24, v25 op_sel:[0,0,1]
	v_cvt_pk_fp8_f32 v147, v16, v17 op_sel:[0,0,1]
	v_add_u32_e32 v154, 0x28000, v152
	s_nop 0
	global_store_dwordx4 v154, v[144:147], s[68:69]
	s_mov_b32 s100, 1
	v_pk_mul_f32 v[230:231], v[230:231], 0.5 op_sel_hi:[1,0]
	v_pk_mul_f32 v[232:233], v[232:233], 0.5 op_sel_hi:[1,0]
	v_pk_mul_f32 v[10:11], v[10:11], 0.5 op_sel_hi:[1,0]
	v_pk_mul_f32 v[12:13], v[12:13], 0.5 op_sel_hi:[1,0]
	v_pk_mul_f32 v[6:7], v[6:7], 0.5 op_sel_hi:[1,0]
	v_pk_mul_f32 v[8:9], v[8:9], 0.5 op_sel_hi:[1,0]
	v_pk_mul_f32 v[2:3], v[2:3], 0.5 op_sel_hi:[1,0]
	v_pk_mul_f32 v[4:5], v[4:5], 0.5 op_sel_hi:[1,0]
	v_cvt_pk_fp8_f32 v148, v230, v231
	v_cvt_pk_fp8_f32 v149, v10, v11
	v_cvt_pk_fp8_f32 v150, v6, v7
	v_cvt_pk_fp8_f32 v151, v2, v3
	v_cvt_pk_fp8_f32 v148, v232, v233 op_sel:[0,0,1]
	v_cvt_pk_fp8_f32 v149, v12, v13 op_sel:[0,0,1]
	v_cvt_pk_fp8_f32 v150, v8, v9 op_sel:[0,0,1]
	v_cvt_pk_fp8_f32 v151, v4, v5 op_sel:[0,0,1]
	v_add_u32_e32 v155, 0x2c000, v152
	s_nop 0
	global_store_dwordx4 v155, v[148:151], s[68:69]
	s_mov_b32 s100, 1
	s_and_b64 vcc, exec, s[4:5]
	s_cbranch_vccz .LBB0_1719
	s_waitcnt vmcnt(0)
	s_cmpk_gt_u32 s3, 0xff
	s_cbranch_scc1 .LBB0_1728
	s_barrier

.LBB0_2423:
	v_mov_b32_e32 v218, 0xbd38aa3b
	v_mov_b32_e32 v219, 0xbd38aa3b
	v_mov_b32_e32 v220, 0x44800000
	v_mov_b32_e32 v221, 0x44800000
	v_lshrrev_b32_e32 v224, 4, v187
	v_lshl_add_u32 v224, s47, 4, v224
	v_lshlrev_b32_e32 v222, 14, v224
	v_lshrrev_b32_e32 v224, 5, v188
	v_lshl_add_u32 v224, s46, 2, v224
	v_lshl_add_u32 v222, v224, 9, v222
	v_and_b32_e32 v224, 15, v187
	v_lshl_add_u32 v222, v224, 5, v222
	v_and_b32_e32 v224, 31, v188
	v_add_u32_e32 v222, v222, v224
	s_mov_b32 s46, s38
	s_mov_b32 s47, s39
	s_mov_b32 s49, s45
	v_pk_mul_f32 v[226:227], v[174:175], v[218:219]
	v_pk_mul_f32 v[228:229], v[176:177], v[218:219]
	v_pk_mul_f32 v[230:231], v[166:167], v[218:219]
	v_pk_mul_f32 v[232:233], v[168:169], v[218:219]
	v_exp_f32_e32 v226, v226
	v_exp_f32_e32 v227, v227
	v_exp_f32_e32 v228, v228
	v_exp_f32_e32 v229, v229
	v_exp_f32_e32 v230, v230
	v_exp_f32_e32 v231, v231
	v_exp_f32_e32 v232, v232
	v_exp_f32_e32 v233, v233
	v_pk_fma_f32 v[226:227], v[226:227], v[220:221], v[220:221]
	v_pk_fma_f32 v[228:229], v[228:229], v[220:221], v[220:221]
	v_pk_fma_f32 v[230:231], v[230:231], v[220:221], v[220:221]
	v_pk_fma_f32 v[232:233], v[232:233], v[220:221], v[220:221]
	v_rcp_f32_e32 v226, v226
	v_rcp_f32_e32 v227, v227
	v_rcp_f32_e32 v228, v228
	v_rcp_f32_e32 v229, v229
	v_rcp_f32_e32 v230, v230
	v_rcp_f32_e32 v231, v231
	v_rcp_f32_e32 v232, v232
	v_rcp_f32_e32 v233, v233
	v_pk_mul_f32 v[174:175], v[174:175], v[170:171]
	v_pk_mul_f32 v[176:177], v[176:177], v[172:173]
	v_pk_mul_f32 v[166:167], v[166:167], v[162:163]
	v_pk_mul_f32 v[168:169], v[168:169], v[164:165]
	v_pk_mul_f32 v[174:175], v[174:175], v[226:227]
	v_pk_mul_f32 v[176:177], v[176:177], v[228:229]
	v_pk_mul_f32 v[166:167], v[166:167], v[230:231]
	v_pk_mul_f32 v[168:169], v[168:169], v[232:233]
	v_mov_b32_e32 v223, v222
	v_cvt_pk_fp8_f32 v234, v174, v175
	v_cvt_pk_fp8_f32 v235, v166, v167
	v_cvt_pk_fp8_f32 v234, v176, v177 op_sel:[0,0,1]
	v_cvt_pk_fp8_f32 v235, v168, v169 op_sel:[0,0,1]
	s_nop 0
	global_store_dwordx2 v223, v[234:235], s[70:71]
	s_mov_b32 s100, 1
	v_pk_mul_f32 v[226:227], v[158:159], v[218:219]
	v_pk_mul_f32 v[228:229], v[160:161], v[218:219]
	v_pk_mul_f32 v[230:231], v[150:151], v[218:219]
	v_pk_mul_f32 v[232:233], v[152:153], v[218:219]
	v_exp_f32_e32 v226, v226
	v_exp_f32_e32 v227, v227
	v_exp_f32_e32 v228, v228
	v_exp_f32_e32 v229, v229
	v_exp_f32_e32 v230, v230
	v_exp_f32_e32 v231, v231
	v_exp_f32_e32 v232, v232
	v_exp_f32_e32 v233, v233
	v_pk_fma_f32 v[226:227], v[226:227], v[220:221], v[220:221]
	v_pk_fma_f32 v[228:229], v[228:229], v[220:221], v[220:221]
	v_pk_fma_f32 v[230:231], v[230:231], v[220:221], v[220:221]
	v_pk_fma_f32 v[232:233], v[232:233], v[220:221], v[220:221]
	v_rcp_f32_e32 v226, v226
	v_rcp_f32_e32 v227, v227
	v_rcp_f32_e32 v228, v228
	v_rcp_f32_e32 v229, v229
	v_rcp_f32_e32 v230, v230
	v_rcp_f32_e32 v231, v231
	v_rcp_f32_e32 v232, v232
	v_rcp_f32_e32 v233, v233
	v_pk_mul_f32 v[158:159], v[158:159], v[154:155]
	v_pk_mul_f32 v[160:161], v[160:161], v[156:157]
	v_pk_mul_f32 v[150:151], v[150:151], v[146:147]
	v_pk_mul_f32 v[152:153], v[152:153], v[148:149]
	v_pk_mul_f32 v[158:159], v[158:159], v[226:227]
	v_pk_mul_f32 v[160:161], v[160:161], v[228:229]
	v_pk_mul_f32 v[150:151], v[150:151], v[230:231]
	v_pk_mul_f32 v[152:153], v[152:153], v[232:233]
	v_add_u32_e32 v225, 0x4000, v222
	v_cvt_pk_fp8_f32 v236, v158, v159
	v_cvt_pk_fp8_f32 v237, v150, v151
	v_cvt_pk_fp8_f32 v236, v160, v161 op_sel:[0,0,1]
	v_cvt_pk_fp8_f32 v237, v152, v153 op_sel:[0,0,1]
	s_nop 0
	global_store_dwordx2 v225, v[236:237], s[70:71]
	s_mov_b32 s100, 1
	v_pk_mul_f32 v[226:227], v[142:143], v[218:219]
	v_pk_mul_f32 v[228:229], v[144:145], v[218:219]
	v_pk_mul_f32 v[230:231], v[134:135], v[218:219]
	v_pk_mul_f32 v[232:233], v[136:137], v[218:219]
	v_exp_f32_e32 v226, v226
	v_exp_f32_e32 v227, v227
	v_exp_f32_e32 v228, v228
	v_exp_f32_e32 v229, v229
	v_exp_f32_e32 v230, v230
	v_exp_f32_e32 v231, v231
	v_exp_f32_e32 v232, v232
	v_exp_f32_e32 v233, v233
	v_pk_fma_f32 v[226:227], v[226:227], v[220:221], v[220:221]
	v_pk_fma_f32 v[228:229], v[228:229], v[220:221], v[220:221]
	v_pk_fma_f32 v[230:231], v[230:231], v[220:221], v[220:221]
	v_pk_fma_f32 v[232:233], v[232:233], v[220:221], v[220:221]
	v_rcp_f32_e32 v226, v226
	v_rcp_f32_e32 v227, v227
	v_rcp_f32_e32 v228, v228
	v_rcp_f32_e32 v229, v229
	v_rcp_f32_e32 v230, v230
	v_rcp_f32_e32 v231, v231
	v_rcp_f32_e32 v232, v232
	v_rcp_f32_e32 v233, v233
	v_pk_mul_f32 v[142:143], v[142:143], v[138:139]
	v_pk_mul_f32 v[144:145], v[144:145], v[140:141]
	v_pk_mul_f32 v[134:135], v[134:135], v[130:131]
	v_pk_mul_f32 v[136:137], v[136:137], v[132:133]
	v_pk_mul_f32 v[142:143], v[142:143], v[226:227]
	v_pk_mul_f32 v[144:145], v[144:145], v[228:229]
	v_pk_mul_f32 v[134:135], v[134:135], v[230:231]
	v_pk_mul_f32 v[136:137], v[136:137], v[232:233]
	v_add_u32_e32 v223, 0x8000, v222
	v_cvt_pk_fp8_f32 v234, v142, v143
	v_cvt_pk_fp8_f32 v235, v134, v135
	v_cvt_pk_fp8_f32 v234, v144, v145 op_sel:[0,0,1]
	v_cvt_pk_fp8_f32 v235, v136, v137 op_sel:[0,0,1]
	s_nop 0
	global_store_dwordx2 v223, v[234:235], s[70:71]
	s_mov_b32 s100, 1
	v_pk_mul_f32 v[226:227], v[126:127], v[218:219]
	v_pk_mul_f32 v[228:229], v[128:129], v[218:219]
	v_pk_mul_f32 v[230:231], v[118:119], v[218:219]
	v_pk_mul_f32 v[232:233], v[120:121], v[218:219]
	v_exp_f32_e32 v226, v226
	v_exp_f32_e32 v227, v227
	v_exp_f32_e32 v228, v228
	v_exp_f32_e32 v229, v229
	v_exp_f32_e32 v230, v230
	v_exp_f32_e32 v231, v231
	v_exp_f32_e32 v232, v232
	v_exp_f32_e32 v233, v233
	v_pk_fma_f32 v[226:227], v[226:227], v[220:221], v[220:221]
	v_pk_fma_f32 v[228:229], v[228:229], v[220:221], v[220:221]
	v_pk_fma_f32 v[230:231], v[230:231], v[220:221], v[220:221]
	v_pk_fma_f32 v[232:233], v[232:233], v[220:221], v[220:221]
	v_rcp_f32_e32 v226, v226
	v_rcp_f32_e32 v227, v227
	v_rcp_f32_e32 v228, v228
	v_rcp_f32_e32 v229, v229
	v_rcp_f32_e32 v230, v230
	v_rcp_f32_e32 v231, v231
	v_rcp_f32_e32 v232, v232
	v_rcp_f32_e32 v233, v233
	v_pk_mul_f32 v[126:127], v[126:127], v[122:123]
	v_pk_mul_f32 v[128:129], v[128:129], v[124:125]
	v_pk_mul_f32 v[118:119], v[118:119], v[114:115]
	v_pk_mul_f32 v[120:121], v[120:121], v[116:117]
	v_pk_mul_f32 v[126:127], v[126:127], v[226:227]
	v_pk_mul_f32 v[128:129], v[128:129], v[228:229]
	v_pk_mul_f32 v[118:119], v[118:119], v[230:231]
	v_pk_mul_f32 v[120:121], v[120:121], v[232:233]
	v_add_u32_e32 v225, 0xc000, v222
	v_cvt_pk_fp8_f32 v236, v126, v127
	v_cvt_pk_fp8_f32 v237, v118, v119
	v_cvt_pk_fp8_f32 v236, v128, v129 op_sel:[0,0,1]
	v_cvt_pk_fp8_f32 v237, v120, v121 op_sel:[0,0,1]
	s_nop 0
	global_store_dwordx2 v225, v[236:237], s[70:71]
	s_mov_b32 s100, 1
	v_pk_mul_f32 v[226:227], v[110:111], v[218:219]
	v_pk_mul_f32 v[228:229], v[112:113], v[218:219]
	v_pk_mul_f32 v[230:231], v[102:103], v[218:219]
	v_pk_mul_f32 v[232:233], v[104:105], v[218:219]
	v_exp_f32_e32 v226, v226
	v_exp_f32_e32 v227, v227
	v_exp_f32_e32 v228, v228
	v_exp_f32_e32 v229, v229
	v_exp_f32_e32 v230, v230
	v_exp_f32_e32 v231, v231
	v_exp_f32_e32 v232, v232
	v_exp_f32_e32 v233, v233
	v_pk_fma_f32 v[226:227], v[226:227], v[220:221], v[220:221]
	v_pk_fma_f32 v[228:229], v[228:229], v[220:221], v[220:221]
	v_pk_fma_f32 v[230:231], v[230:231], v[220:221], v[220:221]
	v_pk_fma_f32 v[232:233], v[232:233], v[220:221], v[220:221]
	v_rcp_f32_e32 v226, v226
	v_rcp_f32_e32 v227, v227
	v_rcp_f32_e32 v228, v228
	v_rcp_f32_e32 v229, v229
	v_rcp_f32_e32 v230, v230
	v_rcp_f32_e32 v231, v231
	v_rcp_f32_e32 v232, v232
	v_rcp_f32_e32 v233, v233
	v_pk_mul_f32 v[110:111], v[110:111], v[106:107]
	v_pk_mul_f32 v[112:113], v[112:113], v[108:109]
	v_pk_mul_f32 v[102:103], v[102:103], v[98:99]
	v_pk_mul_f32 v[104:105], v[104:105], v[100:101]
	v_pk_mul_f32 v[110:111], v[110:111], v[226:227]
	v_pk_mul_f32 v[112:113], v[112:113], v[228:229]
	v_pk_mul_f32 v[102:103], v[102:103], v[230:231]
	v_pk_mul_f32 v[104:105], v[104:105], v[232:233]
	v_add_u32_e32 v223, 0x20000, v222
	v_cvt_pk_fp8_f32 v234, v110, v111
	v_cvt_pk_fp8_f32 v235, v102, v103
	v_cvt_pk_fp8_f32 v234, v112, v113 op_sel:[0,0,1]
	v_cvt_pk_fp8_f32 v235, v104, v105 op_sel:[0,0,1]
	s_nop 0
	global_store_dwordx2 v223, v[234:235], s[70:71]
	s_mov_b32 s100, 1
	v_pk_mul_f32 v[226:227], v[94:95], v[218:219]
	v_pk_mul_f32 v[228:229], v[96:97], v[218:219]
	v_pk_mul_f32 v[230:231], v[86:87], v[218:219]
	v_pk_mul_f32 v[232:233], v[88:89], v[218:219]
	v_exp_f32_e32 v226, v226
	v_exp_f32_e32 v227, v227
	v_exp_f32_e32 v228, v228
	v_exp_f32_e32 v229, v229
	v_exp_f32_e32 v230, v230
	v_exp_f32_e32 v231, v231
	v_exp_f32_e32 v232, v232
	v_exp_f32_e32 v233, v233
	v_pk_fma_f32 v[226:227], v[226:227], v[220:221], v[220:221]
	v_pk_fma_f32 v[228:229], v[228:229], v[220:221], v[220:221]
	v_pk_fma_f32 v[230:231], v[230:231], v[220:221], v[220:221]
	v_pk_fma_f32 v[232:233], v[232:233], v[220:221], v[220:221]
	v_rcp_f32_e32 v226, v226
	v_rcp_f32_e32 v227, v227
	v_rcp_f32_e32 v228, v228
	v_rcp_f32_e32 v229, v229
	v_rcp_f32_e32 v230, v230
	v_rcp_f32_e32 v231, v231
	v_rcp_f32_e32 v232, v232
	v_rcp_f32_e32 v233, v233
	v_pk_mul_f32 v[94:95], v[94:95], v[90:91]
	v_pk_mul_f32 v[96:97], v[96:97], v[92:93]
	v_pk_mul_f32 v[86:87], v[86:87], v[82:83]
	v_pk_mul_f32 v[88:89], v[88:89], v[84:85]
	v_pk_mul_f32 v[94:95], v[94:95], v[226:227]
	v_pk_mul_f32 v[96:97], v[96:97], v[228:229]
	v_pk_mul_f32 v[86:87], v[86:87], v[230:231]
	v_pk_mul_f32 v[88:89], v[88:89], v[232:233]
	v_add_u32_e32 v225, 0x24000, v222
	v_cvt_pk_fp8_f32 v236, v94, v95
	v_cvt_pk_fp8_f32 v237, v86, v87
	v_cvt_pk_fp8_f32 v236, v96, v97 op_sel:[0,0,1]
	v_cvt_pk_fp8_f32 v237, v88, v89 op_sel:[0,0,1]
	s_nop 0
	global_store_dwordx2 v225, v[236:237], s[70:71]
	s_mov_b32 s100, 1
	v_pk_mul_f32 v[226:227], v[78:79], v[218:219]
	v_pk_mul_f32 v[228:229], v[80:81], v[218:219]
	v_pk_mul_f32 v[230:231], v[70:71], v[218:219]
	v_pk_mul_f32 v[232:233], v[72:73], v[218:219]
	v_exp_f32_e32 v226, v226
	v_exp_f32_e32 v227, v227
	v_exp_f32_e32 v228, v228
	v_exp_f32_e32 v229, v229
	v_exp_f32_e32 v230, v230
	v_exp_f32_e32 v231, v231
	v_exp_f32_e32 v232, v232
	v_exp_f32_e32 v233, v233
	v_pk_fma_f32 v[226:227], v[226:227], v[220:221], v[220:221]
	v_pk_fma_f32 v[228:229], v[228:229], v[220:221], v[220:221]
	v_pk_fma_f32 v[230:231], v[230:231], v[220:221], v[220:221]
	v_pk_fma_f32 v[232:233], v[232:233], v[220:221], v[220:221]
	v_rcp_f32_e32 v226, v226
	v_rcp_f32_e32 v227, v227
	v_rcp_f32_e32 v228, v228
	v_rcp_f32_e32 v229, v229
	v_rcp_f32_e32 v230, v230
	v_rcp_f32_e32 v231, v231
	v_rcp_f32_e32 v232, v232
	v_rcp_f32_e32 v233, v233
	v_pk_mul_f32 v[78:79], v[78:79], v[74:75]
	v_pk_mul_f32 v[80:81], v[80:81], v[76:77]
	v_pk_mul_f32 v[70:71], v[70:71], v[66:67]
	v_pk_mul_f32 v[72:73], v[72:73], v[68:69]
	v_pk_mul_f32 v[78:79], v[78:79], v[226:227]
	v_pk_mul_f32 v[80:81], v[80:81], v[228:229]
	v_pk_mul_f32 v[70:71], v[70:71], v[230:231]
	v_pk_mul_f32 v[72:73], v[72:73], v[232:233]
	v_add_u32_e32 v223, 0x28000, v222
	v_cvt_pk_fp8_f32 v234, v78, v79
	v_cvt_pk_fp8_f32 v235, v70, v71
	v_cvt_pk_fp8_f32 v234, v80, v81 op_sel:[0,0,1]
	v_cvt_pk_fp8_f32 v235, v72, v73 op_sel:[0,0,1]
	s_nop 0
	global_store_dwordx2 v223, v[234:235], s[70:71]
	s_mov_b32 s100, 1
	v_pk_mul_f32 v[226:227], v[62:63], v[218:219]
	v_pk_mul_f32 v[228:229], v[64:65], v[218:219]
	v_pk_mul_f32 v[230:231], v[54:55], v[218:219]
	v_pk_mul_f32 v[232:233], v[56:57], v[218:219]
	v_exp_f32_e32 v226, v226
	v_exp_f32_e32 v227, v227
	v_exp_f32_e32 v228, v228
	v_exp_f32_e32 v229, v229
	v_exp_f32_e32 v230, v230
	v_exp_f32_e32 v231, v231
	v_exp_f32_e32 v232, v232
	v_exp_f32_e32 v233, v233
	v_pk_fma_f32 v[226:227], v[226:227], v[220:221], v[220:221]
	v_pk_fma_f32 v[228:229], v[228:229], v[220:221], v[220:221]
	v_pk_fma_f32 v[230:231], v[230:231], v[220:221], v[220:221]
	v_pk_fma_f32 v[232:233], v[232:233], v[220:221], v[220:221]
	v_rcp_f32_e32 v226, v226
	v_rcp_f32_e32 v227, v227
	v_rcp_f32_e32 v228, v228
	v_rcp_f32_e32 v229, v229
	v_rcp_f32_e32 v230, v230
	v_rcp_f32_e32 v231, v231
	v_rcp_f32_e32 v232, v232
	v_rcp_f32_e32 v233, v233
	v_pk_mul_f32 v[62:63], v[62:63], v[58:59]
	v_pk_mul_f32 v[64:65], v[64:65], v[60:61]
	v_pk_mul_f32 v[54:55], v[54:55], v[50:51]
	v_pk_mul_f32 v[56:57], v[56:57], v[52:53]
	v_pk_mul_f32 v[62:63], v[62:63], v[226:227]
	v_pk_mul_f32 v[64:65], v[64:65], v[228:229]
	v_pk_mul_f32 v[54:55], v[54:55], v[230:231]
	v_pk_mul_f32 v[56:57], v[56:57], v[232:233]
	v_add_u32_e32 v225, 0x2c000, v222
	v_cvt_pk_fp8_f32 v236, v62, v63
	v_cvt_pk_fp8_f32 v237, v54, v55
	v_cvt_pk_fp8_f32 v236, v64, v65 op_sel:[0,0,1]
	v_cvt_pk_fp8_f32 v237, v56, v57 op_sel:[0,0,1]
	s_nop 0
	global_store_dwordx2 v225, v[236:237], s[70:71]
	s_mov_b32 s100, 1
	s_and_b64 vcc, exec, s[4:5]
	s_cbranch_vccnz .LBB0_2438

.LBB0_2497:
	s_ashr_i32 s5, s7, 3
	s_add_u32 s8, s52, 0x3db00000
	s_addc_u32 s7, s53, 0
	s_add_i32 s5, s6, s5
	s_ashr_i32 s6, s5, 31
	s_lshr_b32 s6, s6, 27
	v_bfe_i32 v4, v2, 27, 1
	s_add_i32 s6, s5, s6
	v_lshlrev_b32_e32 v1, 4, v2
	v_lshrrev_b32_e32 v4, 22, v4
	s_ashr_i32 s12, s6, 5
	s_andn2_b32 s6, s6, 31
	v_add_u32_e32 v4, v1, v4
	s_sub_i32 s5, s5, s6
	v_and_b32_e32 v4, 0xfffffc00, v4
	s_bfe_i32 s6, s5, 0x80000
	v_sub_u32_e32 v1, v1, v4
	s_bfe_u32 s6, s6, 0x3000c
	v_ashrrev_i32_e32 v3, 31, v2
	v_lshrrev_b32_e32 v4, 4, v1
	s_add_i32 s6, s5, s6
	v_lshrrev_b32_e32 v3, 26, v3
	v_bitop3_b32 v1, v4, v1, 32 bitop3:0x6c
	s_bfe_i32 s13, s6, 0x80000
	s_and_b32 s6, s6, 0xf8
	v_add_u32_e32 v3, v2, v3
	v_ashrrev_i32_e32 v5, 31, v1
	s_sub_i32 s5, s5, s6
	v_ashrrev_i32_e32 v3, 6, v3
	v_lshrrev_b32_e32 v5, 26, v5
	s_lshl_b32 s12, s12, 3
	s_sext_i32_i8 s5, s5
	v_lshlrev_b32_e32 v4, 3, v3
	v_add_u32_e32 v5, v1, v5
	s_add_i32 s78, s12, s5
	v_and_b32_e32 v4, -16, v4
	v_ashrrev_i32_e32 v6, 6, v5
	v_and_b32_e32 v5, 0xc0, v5
	s_ashr_i32 s5, s78, 31
	s_ashr_i32 s4, s3, 6
	v_add_u32_e32 v4, v6, v4
	v_sub_u32_e32 v1, v1, v5
	v_mov_b32_e32 v5, 1
	v_and_b32_e32 v6, 3, v6
	s_mov_b32 s9, 0x3fffe0
	s_lshr_b32 s5, s5, 28
	v_lshlrev_b32_e32 v3, 5, v3
	v_ashrrev_i16_sdwa v1, v5, sext(v1) dst_sel:DWORD dst_unused:UNUSED_PAD src0_sel:DWORD src1_sel:BYTE_0
	v_lshlrev_b32_e32 v5, 1, v4
	v_lshrrev_b32_e32 v7, 2, v4
	v_and_or_b32 v6, v4, s9, v6
	s_and_b32 s9, s7, 0xffff
	s_lshl_b32 s7, s4, 10
	s_sext_i32_i16 s13, s13
	s_add_i32 s5, s78, s5
	v_and_b32_e32 v3, 32, v3
	v_bfe_i32 v1, v1, 0, 16
	v_and_b32_e32 v5, 24, v5
	v_and_b32_e32 v7, 4, v7
	s_ashr_i32 s73, s13, 3
	s_lshl_b32 s5, s5, 16
	s_add_i32 s21, s7, 0
	s_mov_b32 s47, 0x20000
	s_brev_b32 s46, -2
	v_or3_b32 v5, v6, v7, v5
	v_add_lshl_u32 v3, v3, v1, 1
	s_and_b32 s5, s5, 0xfff00000
	s_lshl_b32 s6, s73, 18
	s_add_i32 s22, s21, 0x10000
	v_and_b32_e32 v254, 3, v4
	v_lshrrev_b32_e32 v5, 2, v4
	v_and_b32_e32 v5, 4, v5
	v_or_b32_e32 v254, v254, v5
	v_lshlrev_b32_e32 v5, 2, v4
	v_and_b32_e32 v5, 0x30, v5
	v_or_b32_e32 v254, v254, v5
	v_lshlrev_b32_e32 v5, 1, v4
	v_and_b32_e32 v5, 0x40, v5
	v_or_b32_e32 v254, v254, v5
	v_lshl_add_u32 v134, v254, 10, v3
	s_mov_b32 s10, s46
	s_mov_b32 s11, s47
	s_add_i32 s79, s5, s6
	s_mov_b32 m0, s22
	s_add_i32 s23, s21, 0x12000
	s_mov_b32 s100, 0
	buffer_load_dwordx4 v134, s[8:11], s79 offen lds
	s_or_b32 s5, s79, 0x20000
	s_mov_b32 m0, s23
	s_and_b32 s45, s71, 0xffff
	v_lshrrev_b32_e32 v254, 4, v4
	v_lshlrev_b32_e32 v1, 14, v254
	v_lshrrev_b32_e32 v254, 5, v3
	v_lshl_add_u32 v1, v254, 9, v1
	v_and_b32_e32 v254, 15, v4
	v_lshl_add_u32 v1, v254, 5, v1
	v_and_b32_e32 v254, 31, v3
	v_add_u32_e32 v1, v1, v254
	buffer_load_dwordx4 v134, s[8:11], s5 offen lds
	s_lshl_b32 s84, s78, 18
	s_mov_b32 m0, s21
	s_add_i32 s24, s21, 0x2000
	buffer_load_dwordx4 v1, s[44:47], s84 offen lds
	s_or_b32 s5, s84, 0x10000
	s_mov_b32 m0, s24
	s_add_i32 s25, s21, 0x14000
	buffer_load_dwordx4 v1, s[44:47], s5 offen lds
	s_or_b32 s5, s79, 0x2000
	s_mov_b32 m0, s25
	s_add_i32 s26, s21, 0x16000
	buffer_load_dwordx4 v134, s[8:11], s5 offen lds
	s_or_b32 s5, s79, 0x22000
	s_mov_b32 m0, s26
	s_add_i32 s27, s21, 0x4000
	buffer_load_dwordx4 v134, s[8:11], s5 offen lds
	s_or_b32 s5, s84, 0x20000
	s_mov_b32 m0, s27
	s_add_i32 s28, s21, 0x6000
	buffer_load_dwordx4 v1, s[44:47], s5 offen lds
	s_or_b32 s5, s84, 0x30000
	s_mov_b32 m0, s28
	s_mov_b32 s29, 0
	buffer_load_dwordx4 v1, s[44:47], s5 offen lds
	s_ashr_i32 s5, s3, 8
	s_cmp_lg_u32 s5, 1
	s_cbranch_scc1 .LBB0_2499
	s_barrier
.LBB0_2499:
	s_add_i32 s30, s21, 0x18000
	s_or_b32 s6, s79, 0x80
	s_mov_b32 s10, s46
	s_mov_b32 s11, s47
	s_mov_b32 m0, s30
	s_add_i32 s31, s21, 0x1a000
	s_waitcnt vmcnt(4)
	s_barrier
	buffer_load_dwordx4 v134, s[8:11], s6 offen lds
	s_or_b32 s6, s79, 0x20080
	s_mov_b32 m0, s31
	s_add_i32 s34, s21, 0x8000
	buffer_load_dwordx4 v134, s[8:11], s6 offen lds
	s_or_b32 s6, s84, 0x800
	s_mov_b32 m0, s34
	s_add_i32 s35, s21, 0xa000
	buffer_load_dwordx4 v1, s[44:47], s6 offen lds
	s_or_b32 s6, s84, 0x10800
	s_mov_b32 m0, s35
	s_add_i32 s36, s21, 0x1c000
	buffer_load_dwordx4 v1, s[44:47], s6 offen lds
	s_or_b32 s6, s79, 0x2080
	s_mov_b32 m0, s36
	s_add_i32 s37, s21, 0x1e000
	buffer_load_dwordx4 v134, s[8:11], s6 offen lds
	s_or_b32 s6, s79, 0x22080
	s_mov_b32 m0, s37
	v_and_b32_e32 v3, 15, v2
	buffer_load_dwordx4 v134, s[8:11], s6 offen lds
	v_lshrrev_b32_e32 v4, 1, v2
	s_and_b32 s4, s4, 3
	v_and_b32_e32 v4, 24, v4
	v_lshlrev_b32_e32 v5, 6, v3
	v_lshlrev_b32_e32 v2, 2, v2
	v_lshl_or_b32 v5, v4, 1, v5
	v_and_b32_e32 v2, 32, v2
	s_lshl_b32 s6, s5, 13
	s_lshl_b32 s7, s4, 12
	v_bitop3_b32 v6, v5, s6, v2 bitop3:0xde
	v_bitop3_b32 v2, v5, s7, v2 bitop3:0xde
	s_waitcnt vmcnt(6)
	v_add_u32_e32 v2, 0, v2
	s_add_i32 s38, s21, 0xc000
	v_lshl_or_b32 v135, s5, 6, v3
	s_add_i32 s39, s21, 0xe000
	s_ashr_i32 s41, s56, 31
	v_lshl_or_b32 v136, s4, 5, v4
	v_add_u32_e32 v137, 0x10000, v2
	v_add_u32_e32 v138, 0, v6
	v_add_u32_e32 v139, 0x14000, v2
	v_add_u32_e32 v140, 0x18000, v2
	v_add_u32_e32 v141, 0x1c000, v2
	s_mov_b64 s[12:13], 0x20000
	s_mov_b64 s[14:15], 0x24000
	s_mov_b32 s42, 0x24000
	s_mov_b64 s[16:17], 0x28000
	s_mov_b32 s43, 0x28000
	s_mov_b64 s[18:19], 0x2c000
	s_mov_b32 s49, 0x2c000
	s_barrier

.LBB0_2508:
	s_lshl_b32 s72, s58, 18
	s_and_b64 s[6:7], s[6:7], exec
	v_mov_b32_e32 v2, 0
	s_cselect_b32 s6, s72, s84
	s_add_i32 s7, s84, 0x30800
	s_addk_i32 s79, 0x100
	s_mov_b32 s84, -2
	ds_read_b128 v[142:145], v137
	ds_read_b128 v[146:149], v137 offset:1024
	ds_read_b128 v[150:153], v137 offset:2048
	ds_read_b128 v[154:157], v137 offset:3072
	s_add_i32 s10, s7, 0xfffd0800
	s_cmp_eq_u32 s84, 4
	s_cselect_b32 s86, s6, s10
	s_cselect_b32 s85, s59, s79
	s_or_b32 s87, s86, 0x800
	s_add_i32 s10, s7, 0xffff0000
	s_mov_b32 m0, s38
	ds_read_b128 v[158:161], v138
	ds_read_b128 v[162:165], v138 offset:1024
	ds_read_b128 v[166:169], v138 offset:2048
	ds_read_b128 v[170:173], v138 offset:3072
	ds_read_b128 v[174:177], v138 offset:4096
	ds_read_b128 v[178:181], v138 offset:5120
	ds_read_b128 v[182:185], v138 offset:6144
	ds_read_b128 v[186:189], v138 offset:7168
	buffer_load_dwordx4 v1, s[44:47], s10 offen lds
	s_mov_b32 m0, s39
	s_nop 0
	buffer_load_dwordx4 v1, s[44:47], s7 offen lds
	s_waitcnt lgkmcnt(8)
	s_barrier
	s_waitcnt lgkmcnt(0)
	s_setprio 1
	s_waitcnt lgkmcnt(4)
	v_mfma_f32_16x16x128_f8f6f4 v[114:117], v[142:149], v[166:173], 0
	v_mfma_f32_16x16x128_f8f6f4 v[106:109], v[150:157], v[166:173], 0
	s_waitcnt lgkmcnt(2)
	v_mfma_f32_16x16x128_f8f6f4 v[98:101], v[142:149], v[174:181], 0
	v_mfma_f32_16x16x128_f8f6f4 v[198:201], v[142:149], v[158:165], 0
	v_mfma_f32_16x16x128_f8f6f4 v[202:205], v[150:157], v[158:165], 0
	v_mfma_f32_16x16x128_f8f6f4 v[206:209], v[150:157], v[174:181], 0
	s_waitcnt lgkmcnt(0)
	v_mfma_f32_16x16x128_f8f6f4 v[210:213], v[142:149], v[182:189], 0
	v_mfma_f32_16x16x128_f8f6f4 v[214:217], v[150:157], v[182:189], 0
	s_setprio 0
	s_barrier
	s_mov_b32 m0, s22
	s_mov_b32 s10, s46
	s_mov_b32 s11, s47
	ds_read_b128 v[122:125], v139
	ds_read_b128 v[126:129], v139 offset:1024
	ds_read_b128 v[190:193], v139 offset:2048
	ds_read_b128 v[194:197], v139 offset:3072
	buffer_load_dwordx4 v134, s[8:11], s85 offen lds
	s_add_i32 s33, s85, 0x20000
	s_mov_b32 m0, s23
	s_nop 0
	buffer_load_dwordx4 v134, s[8:11], s33 offen lds
	s_barrier
	s_waitcnt lgkmcnt(0)
	s_setprio 1
	s_waitcnt lgkmcnt(2)
	v_mfma_f32_16x16x128_f8f6f4 v[118:121], v[122:129], v[158:165], 0
	s_waitcnt lgkmcnt(0)
	v_mfma_f32_16x16x128_f8f6f4 v[110:113], v[190:197], v[158:165], 0
	v_mfma_f32_16x16x128_f8f6f4 v[102:105], v[122:129], v[166:173], 0
	v_mfma_f32_16x16x128_f8f6f4 v[158:161], v[190:197], v[166:173], 0
	v_mfma_f32_16x16x128_f8f6f4 v[162:165], v[122:129], v[174:181], 0
	v_mfma_f32_16x16x128_f8f6f4 v[166:169], v[190:197], v[174:181], 0
	v_mfma_f32_16x16x128_f8f6f4 v[170:173], v[122:129], v[182:189], 0
	v_mfma_f32_16x16x128_f8f6f4 v[174:177], v[190:197], v[182:189], 0
	s_setprio 0
	s_mov_b32 m0, s21
	s_barrier
	ds_read_b128 v[66:69], v138 offset:16384
	s_nop 1
	ds_read_b128 v[70:73], v138 offset:17408
	ds_read_b128 v[74:77], v138 offset:18432
	ds_read_b128 v[78:81], v138 offset:19456
	ds_read_b128 v[82:85], v138 offset:20480
	ds_read_b128 v[86:89], v138 offset:21504
	ds_read_b128 v[90:93], v138 offset:22528
	ds_read_b128 v[94:97], v138 offset:23552
	buffer_load_dwordx4 v1, s[44:47], s86 offen lds
	s_add_i32 s33, s86, 0x10000
	s_mov_b32 m0, s24
	s_nop 0
	buffer_load_dwordx4 v1, s[44:47], s33 offen lds
	s_barrier
	s_waitcnt lgkmcnt(0)
	s_setprio 1
	s_waitcnt lgkmcnt(6)
	v_mfma_f32_16x16x128_f8f6f4 v[62:65], v[142:149], v[66:73], 0
	v_mfma_f32_16x16x128_f8f6f4 v[58:61], v[150:157], v[66:73], 0
	s_waitcnt lgkmcnt(4)
	v_mfma_f32_16x16x128_f8f6f4 v[50:53], v[142:149], v[74:81], 0
	s_waitcnt lgkmcnt(0)
	v_mfma_f32_16x16x128_f8f6f4 v[230:233], v[142:149], v[90:97], 0
	v_mfma_f32_16x16x128_f8f6f4 v[218:221], v[150:157], v[74:81], 0
	v_mfma_f32_16x16x128_f8f6f4 v[222:225], v[142:149], v[82:89], 0
	v_mfma_f32_16x16x128_f8f6f4 v[226:229], v[150:157], v[82:89], 0
	v_mfma_f32_16x16x128_f8f6f4 v[234:237], v[150:157], v[90:97], 0
	s_setprio 0
	s_barrier
	s_mov_b32 m0, s25
	s_add_i32 s33, s85, 0x2000
	buffer_load_dwordx4 v134, s[8:11], s33 offen lds
	s_add_i32 s33, s85, 0x22000
	s_mov_b32 m0, s26
	s_nop 0
	buffer_load_dwordx4 v134, s[8:11], s33 offen lds
	s_cmp_eq_u32 s100, 0
	s_cbranch_scc1 .Lfw_12_a_p
	s_waitcnt vmcnt(16)
	s_mov_b32 s100, 0
	s_branch .Lfw_12_b_p

.Lfw_12_b_p:
	s_barrier
	s_setprio 1
	v_mfma_f32_16x16x128_f8f6f4 v[54:57], v[122:129], v[66:73], 0
	v_mfma_f32_16x16x128_f8f6f4 v[238:241], v[190:197], v[66:73], 0
	v_mfma_f32_16x16x128_f8f6f4 v[242:245], v[122:129], v[74:81], 0
	v_mfma_f32_16x16x128_f8f6f4 v[246:249], v[190:197], v[74:81], 0
	v_mfma_f32_16x16x128_f8f6f4 v[250:253], v[122:129], v[82:89], 0
	v_mfma_f32_16x16x128_f8f6f4 v[130:133], v[190:197], v[82:89], 0
	v_mfma_f32_16x16x128_f8f6f4 v[66:69], v[122:129], v[90:97], 0
	v_mfma_f32_16x16x128_f8f6f4 v[190:193], v[190:197], v[90:97], 0
	s_setprio 0
	s_barrier
	s_nop 4
	ds_read_b128 v[2:5], v140
	ds_read_b128 v[6:9], v140 offset:1024
	ds_read_b128 v[10:13], v140 offset:2048
	ds_read_b128 v[14:17], v140 offset:3072
	s_mov_b32 m0, s27
	s_add_i32 s33, s86, 0x20000
	ds_read_b128 v[18:21], v138 offset:32768
	ds_read_b128 v[22:25], v138 offset:33792
	ds_read_b128 v[26:29], v138 offset:34816
	ds_read_b128 v[30:33], v138 offset:35840
	ds_read_b128 v[34:37], v138 offset:36864
	ds_read_b128 v[38:41], v138 offset:37888
	ds_read_b128 v[42:45], v138 offset:38912
	ds_read_b128 v[46:49], v138 offset:39936
	buffer_load_dwordx4 v1, s[44:47], s33 offen lds
	s_add_i32 s33, s86, 0x30000
	s_mov_b32 m0, s28
	s_nop 0
	buffer_load_dwordx4 v1, s[44:47], s33 offen lds
	s_waitcnt lgkmcnt(8)
	s_barrier
	s_waitcnt lgkmcnt(0)
	s_setprio 1
	s_waitcnt lgkmcnt(6)
	v_mfma_f32_16x16x128_f8f6f4 v[126:129], v[2:9], v[18:25], v[198:201]
	v_mfma_f32_16x16x128_f8f6f4 v[122:125], v[10:17], v[18:25], v[202:205]
	s_waitcnt lgkmcnt(4)
	v_mfma_f32_16x16x128_f8f6f4 v[114:117], v[2:9], v[26:33], v[114:117]
	v_mfma_f32_16x16x128_f8f6f4 v[106:109], v[10:17], v[26:33], v[106:109]
	s_waitcnt lgkmcnt(2)
	v_mfma_f32_16x16x128_f8f6f4 v[98:101], v[2:9], v[34:41], v[98:101]
	v_mfma_f32_16x16x128_f8f6f4 v[90:93], v[10:17], v[34:41], v[206:209]
	s_waitcnt lgkmcnt(0)
	v_mfma_f32_16x16x128_f8f6f4 v[82:85], v[2:9], v[42:49], v[210:213]
	v_mfma_f32_16x16x128_f8f6f4 v[74:77], v[10:17], v[42:49], v[214:217]
	s_setprio 0
	s_barrier
	s_mov_b32 m0, s30
	s_add_i32 s33, s85, 0x80
	ds_read_b128 v[142:145], v141
	ds_read_b128 v[146:149], v141 offset:1024
	ds_read_b128 v[150:153], v141 offset:2048
	ds_read_b128 v[154:157], v141 offset:3072
	buffer_load_dwordx4 v134, s[8:11], s33 offen lds
	s_add_i32 s33, s85, 0x20080
	s_mov_b32 m0, s31
	s_nop 0
	buffer_load_dwordx4 v134, s[8:11], s33 offen lds
	s_waitcnt vmcnt(10)
	s_barrier
	s_waitcnt lgkmcnt(0)
	s_setprio 1
	s_waitcnt lgkmcnt(2)
	v_mfma_f32_16x16x128_f8f6f4 v[118:121], v[142:149], v[18:25], v[118:121]
	s_waitcnt lgkmcnt(0)
	v_mfma_f32_16x16x128_f8f6f4 v[110:113], v[150:157], v[18:25], v[110:113]
	v_mfma_f32_16x16x128_f8f6f4 v[102:105], v[142:149], v[26:33], v[102:105]
	v_mfma_f32_16x16x128_f8f6f4 v[94:97], v[150:157], v[26:33], v[158:161]
	v_mfma_f32_16x16x128_f8f6f4 v[86:89], v[142:149], v[34:41], v[162:165]
	v_mfma_f32_16x16x128_f8f6f4 v[78:81], v[150:157], v[34:41], v[166:169]
	v_mfma_f32_16x16x128_f8f6f4 v[70:73], v[142:149], v[42:49], v[170:173]
	v_mfma_f32_16x16x128_f8f6f4 v[18:21], v[150:157], v[42:49], v[174:177]
	s_setprio 0
	s_mov_b32 m0, s34
	s_barrier
	ds_read_b128 v[158:161], v138 offset:49152
	ds_read_b128 v[162:165], v138 offset:50176
	ds_read_b128 v[166:169], v138 offset:51200
	ds_read_b128 v[170:173], v138 offset:52224
	ds_read_b128 v[174:177], v138 offset:53248
	ds_read_b128 v[178:181], v138 offset:54272
	ds_read_b128 v[182:185], v138 offset:55296
	ds_read_b128 v[186:189], v138 offset:56320
	buffer_load_dwordx4 v1, s[44:47], s87 offen lds
	s_add_i32 s86, s86, 0x10800
	s_mov_b32 m0, s35
	s_nop 0
	buffer_load_dwordx4 v1, s[44:47], s86 offen lds
	s_barrier
	s_waitcnt lgkmcnt(0)
	s_setprio 1
	s_waitcnt lgkmcnt(6)
	v_mfma_f32_16x16x128_f8f6f4 v[62:65], v[2:9], v[158:165], v[62:65]
	v_mfma_f32_16x16x128_f8f6f4 v[58:61], v[10:17], v[158:165], v[58:61]
	s_waitcnt lgkmcnt(4)
	v_mfma_f32_16x16x128_f8f6f4 v[50:53], v[2:9], v[166:173], v[50:53]
	v_mfma_f32_16x16x128_f8f6f4 v[42:45], v[10:17], v[166:173], v[218:221]
	s_waitcnt lgkmcnt(2)
	v_mfma_f32_16x16x128_f8f6f4 v[34:37], v[2:9], v[174:181], v[222:225]
	v_mfma_f32_16x16x128_f8f6f4 v[26:29], v[10:17], v[174:181], v[226:229]
	s_waitcnt lgkmcnt(0)
	v_mfma_f32_16x16x128_f8f6f4 v[230:233], v[2:9], v[182:189], v[230:233]
	v_mfma_f32_16x16x128_f8f6f4 v[10:13], v[10:17], v[182:189], v[234:237]
	s_setprio 0
	s_barrier
	s_mov_b32 m0, s36
	s_add_i32 s33, s85, 0x2080
	buffer_load_dwordx4 v134, s[8:11], s33 offen lds
	s_add_i32 s85, s85, 0x22080
	s_mov_b32 m0, s37
	s_nop 0
	buffer_load_dwordx4 v134, s[8:11], s85 offen lds
	s_waitcnt vmcnt(6)
	s_barrier
	s_setprio 1
	v_mfma_f32_16x16x128_f8f6f4 v[54:57], v[142:149], v[158:165], v[54:57]
	v_mfma_f32_16x16x128_f8f6f4 v[46:49], v[150:157], v[158:165], v[238:241]
	v_mfma_f32_16x16x128_f8f6f4 v[38:41], v[142:149], v[166:173], v[242:245]
	v_mfma_f32_16x16x128_f8f6f4 v[30:33], v[150:157], v[166:173], v[246:249]
	v_mfma_f32_16x16x128_f8f6f4 v[22:25], v[142:149], v[174:181], v[250:253]
	v_mfma_f32_16x16x128_f8f6f4 v[14:17], v[150:157], v[174:181], v[130:133]
	v_mfma_f32_16x16x128_f8f6f4 v[6:9], v[142:149], v[182:189], v[66:69]
	v_mfma_f32_16x16x128_f8f6f4 v[2:5], v[150:157], v[182:189], v[190:193]
	s_setprio 0
	s_add_i32 s84, s84, 2
	s_addk_i32 s7, 0x1000
	s_addk_i32 s79, 0x100
	s_cmp_gt_u32 s84, 5
	s_barrier
.LBB0_2509:
	ds_read_b128 v[142:145], v137
	ds_read_b128 v[146:149], v137 offset:1024
	ds_read_b128 v[150:153], v137 offset:2048
	ds_read_b128 v[154:157], v137 offset:3072
	s_add_i32 s10, s7, 0xfffd0800
	s_cmp_eq_u32 s84, 4
	s_cselect_b32 s86, s6, s10
	s_cselect_b32 s85, s59, s79
	s_or_b32 s87, s86, 0x800
	s_add_i32 s10, s7, 0xffff0000
	s_mov_b32 m0, s38
	ds_read_b128 v[158:161], v138
	ds_read_b128 v[162:165], v138 offset:1024
	ds_read_b128 v[166:169], v138 offset:2048
	ds_read_b128 v[170:173], v138 offset:3072
	ds_read_b128 v[174:177], v138 offset:4096
	ds_read_b128 v[178:181], v138 offset:5120
	ds_read_b128 v[182:185], v138 offset:6144
	ds_read_b128 v[186:189], v138 offset:7168
	buffer_load_dwordx4 v1, s[44:47], s10 offen lds
	s_mov_b32 m0, s39
	s_nop 0
	buffer_load_dwordx4 v1, s[44:47], s7 offen lds
	s_waitcnt lgkmcnt(8)
	s_barrier
	s_waitcnt lgkmcnt(0)
	s_setprio 1
	s_waitcnt lgkmcnt(4)
	v_mfma_f32_16x16x128_f8f6f4 v[114:117], v[142:149], v[166:173], v[114:117]
	v_mfma_f32_16x16x128_f8f6f4 v[106:109], v[150:157], v[166:173], v[106:109]
	s_waitcnt lgkmcnt(2)
	v_mfma_f32_16x16x128_f8f6f4 v[98:101], v[142:149], v[174:181], v[98:101]
	v_mfma_f32_16x16x128_f8f6f4 v[198:201], v[142:149], v[158:165], v[126:129]
	v_mfma_f32_16x16x128_f8f6f4 v[202:205], v[150:157], v[158:165], v[122:125]
	v_mfma_f32_16x16x128_f8f6f4 v[206:209], v[150:157], v[174:181], v[90:93]
	s_waitcnt lgkmcnt(0)
	v_mfma_f32_16x16x128_f8f6f4 v[210:213], v[142:149], v[182:189], v[82:85]
	v_mfma_f32_16x16x128_f8f6f4 v[214:217], v[150:157], v[182:189], v[74:77]
	s_setprio 0
	s_barrier
	s_mov_b32 m0, s22
	s_mov_b32 s10, s46
	s_mov_b32 s11, s47
	ds_read_b128 v[122:125], v139
	ds_read_b128 v[126:129], v139 offset:1024
	ds_read_b128 v[190:193], v139 offset:2048
	ds_read_b128 v[194:197], v139 offset:3072
	buffer_load_dwordx4 v134, s[8:11], s85 offen lds
	s_add_i32 s33, s85, 0x20000
	s_mov_b32 m0, s23
	s_nop 0
	buffer_load_dwordx4 v134, s[8:11], s33 offen lds
	s_barrier
	s_waitcnt lgkmcnt(0)
	s_setprio 1
	s_waitcnt lgkmcnt(2)
	v_mfma_f32_16x16x128_f8f6f4 v[118:121], v[122:129], v[158:165], v[118:121]
	s_waitcnt lgkmcnt(0)
	v_mfma_f32_16x16x128_f8f6f4 v[110:113], v[190:197], v[158:165], v[110:113]
	v_mfma_f32_16x16x128_f8f6f4 v[102:105], v[122:129], v[166:173], v[102:105]
	v_mfma_f32_16x16x128_f8f6f4 v[158:161], v[190:197], v[166:173], v[94:97]
	v_mfma_f32_16x16x128_f8f6f4 v[162:165], v[122:129], v[174:181], v[86:89]
	v_mfma_f32_16x16x128_f8f6f4 v[166:169], v[190:197], v[174:181], v[78:81]
	v_mfma_f32_16x16x128_f8f6f4 v[170:173], v[122:129], v[182:189], v[70:73]
	v_mfma_f32_16x16x128_f8f6f4 v[174:177], v[190:197], v[182:189], v[18:21]
	s_setprio 0
	s_mov_b32 m0, s21
	s_barrier
	ds_read_b128 v[66:69], v138 offset:16384
	s_nop 1
	ds_read_b128 v[70:73], v138 offset:17408
	ds_read_b128 v[74:77], v138 offset:18432
	ds_read_b128 v[78:81], v138 offset:19456
	ds_read_b128 v[82:85], v138 offset:20480
	ds_read_b128 v[86:89], v138 offset:21504
	ds_read_b128 v[90:93], v138 offset:22528
	ds_read_b128 v[94:97], v138 offset:23552
	buffer_load_dwordx4 v1, s[44:47], s86 offen lds
	s_add_i32 s33, s86, 0x10000
	s_mov_b32 m0, s24
	s_nop 0
	buffer_load_dwordx4 v1, s[44:47], s33 offen lds
	s_barrier
	s_waitcnt lgkmcnt(0)
	s_setprio 1
	s_waitcnt lgkmcnt(6)
	v_mfma_f32_16x16x128_f8f6f4 v[62:65], v[142:149], v[66:73], v[62:65]
	v_mfma_f32_16x16x128_f8f6f4 v[58:61], v[150:157], v[66:73], v[58:61]
	s_waitcnt lgkmcnt(4)
	v_mfma_f32_16x16x128_f8f6f4 v[50:53], v[142:149], v[74:81], v[50:53]
	s_waitcnt lgkmcnt(0)
	v_mfma_f32_16x16x128_f8f6f4 v[230:233], v[142:149], v[90:97], v[230:233]
	v_mfma_f32_16x16x128_f8f6f4 v[218:221], v[150:157], v[74:81], v[42:45]
	v_mfma_f32_16x16x128_f8f6f4 v[222:225], v[142:149], v[82:89], v[34:37]
	v_mfma_f32_16x16x128_f8f6f4 v[226:229], v[150:157], v[82:89], v[26:29]
	v_mfma_f32_16x16x128_f8f6f4 v[234:237], v[150:157], v[90:97], v[10:13]
	s_setprio 0
	s_barrier
	s_mov_b32 m0, s25
	s_add_i32 s33, s85, 0x2000
	buffer_load_dwordx4 v134, s[8:11], s33 offen lds
	s_add_i32 s33, s85, 0x22000
	s_mov_b32 m0, s26
	s_nop 0
	buffer_load_dwordx4 v134, s[8:11], s33 offen lds
	s_cmp_eq_u32 s100, 0
	s_cbranch_scc1 .Lfw_12_a
	s_waitcnt vmcnt(16)
	s_mov_b32 s100, 0
	s_branch .Lfw_12_b

.Lfw_12_b:
	s_barrier
	s_setprio 1
	v_mfma_f32_16x16x128_f8f6f4 v[54:57], v[122:129], v[66:73], v[54:57]
	v_mfma_f32_16x16x128_f8f6f4 v[238:241], v[190:197], v[66:73], v[46:49]
	v_mfma_f32_16x16x128_f8f6f4 v[242:245], v[122:129], v[74:81], v[38:41]
	v_mfma_f32_16x16x128_f8f6f4 v[246:249], v[190:197], v[74:81], v[30:33]
	v_mfma_f32_16x16x128_f8f6f4 v[250:253], v[122:129], v[82:89], v[22:25]
	v_mfma_f32_16x16x128_f8f6f4 v[130:133], v[190:197], v[82:89], v[14:17]
	v_mfma_f32_16x16x128_f8f6f4 v[66:69], v[122:129], v[90:97], v[6:9]
	v_mfma_f32_16x16x128_f8f6f4 v[190:193], v[190:197], v[90:97], v[2:5]
	s_setprio 0
	s_barrier
	s_nop 4
	ds_read_b128 v[2:5], v140
	ds_read_b128 v[6:9], v140 offset:1024
	ds_read_b128 v[10:13], v140 offset:2048
	ds_read_b128 v[14:17], v140 offset:3072
	s_mov_b32 m0, s27
	s_add_i32 s33, s86, 0x20000
	ds_read_b128 v[18:21], v138 offset:32768
	ds_read_b128 v[22:25], v138 offset:33792
	ds_read_b128 v[26:29], v138 offset:34816
	ds_read_b128 v[30:33], v138 offset:35840
	ds_read_b128 v[34:37], v138 offset:36864
	ds_read_b128 v[38:41], v138 offset:37888
	ds_read_b128 v[42:45], v138 offset:38912
	ds_read_b128 v[46:49], v138 offset:39936
	buffer_load_dwordx4 v1, s[44:47], s33 offen lds
	s_add_i32 s33, s86, 0x30000
	s_mov_b32 m0, s28
	s_nop 0
	buffer_load_dwordx4 v1, s[44:47], s33 offen lds
	s_waitcnt lgkmcnt(8)
	s_barrier
	s_waitcnt lgkmcnt(0)
	s_setprio 1
	s_waitcnt lgkmcnt(6)
	v_mfma_f32_16x16x128_f8f6f4 v[126:129], v[2:9], v[18:25], v[198:201]
	v_mfma_f32_16x16x128_f8f6f4 v[122:125], v[10:17], v[18:25], v[202:205]
	s_waitcnt lgkmcnt(4)
	v_mfma_f32_16x16x128_f8f6f4 v[114:117], v[2:9], v[26:33], v[114:117]
	v_mfma_f32_16x16x128_f8f6f4 v[106:109], v[10:17], v[26:33], v[106:109]
	s_waitcnt lgkmcnt(2)
	v_mfma_f32_16x16x128_f8f6f4 v[98:101], v[2:9], v[34:41], v[98:101]
	v_mfma_f32_16x16x128_f8f6f4 v[90:93], v[10:17], v[34:41], v[206:209]
	s_waitcnt lgkmcnt(0)
	v_mfma_f32_16x16x128_f8f6f4 v[82:85], v[2:9], v[42:49], v[210:213]
	v_mfma_f32_16x16x128_f8f6f4 v[74:77], v[10:17], v[42:49], v[214:217]
	s_setprio 0
	s_barrier
	s_mov_b32 m0, s30
	s_add_i32 s33, s85, 0x80
	ds_read_b128 v[142:145], v141
	ds_read_b128 v[146:149], v141 offset:1024
	ds_read_b128 v[150:153], v141 offset:2048
	ds_read_b128 v[154:157], v141 offset:3072
	buffer_load_dwordx4 v134, s[8:11], s33 offen lds
	s_add_i32 s33, s85, 0x20080
	s_mov_b32 m0, s31
	s_nop 0
	buffer_load_dwordx4 v134, s[8:11], s33 offen lds
	s_waitcnt vmcnt(10)
	s_barrier
	s_waitcnt lgkmcnt(0)
	s_setprio 1
	s_waitcnt lgkmcnt(2)
	v_mfma_f32_16x16x128_f8f6f4 v[118:121], v[142:149], v[18:25], v[118:121]
	s_waitcnt lgkmcnt(0)
	v_mfma_f32_16x16x128_f8f6f4 v[110:113], v[150:157], v[18:25], v[110:113]
	v_mfma_f32_16x16x128_f8f6f4 v[102:105], v[142:149], v[26:33], v[102:105]
	v_mfma_f32_16x16x128_f8f6f4 v[94:97], v[150:157], v[26:33], v[158:161]
	v_mfma_f32_16x16x128_f8f6f4 v[86:89], v[142:149], v[34:41], v[162:165]
	v_mfma_f32_16x16x128_f8f6f4 v[78:81], v[150:157], v[34:41], v[166:169]
	v_mfma_f32_16x16x128_f8f6f4 v[70:73], v[142:149], v[42:49], v[170:173]
	v_mfma_f32_16x16x128_f8f6f4 v[18:21], v[150:157], v[42:49], v[174:177]
	s_setprio 0
	s_mov_b32 m0, s34
	s_barrier
	ds_read_b128 v[158:161], v138 offset:49152
	ds_read_b128 v[162:165], v138 offset:50176
	ds_read_b128 v[166:169], v138 offset:51200
	ds_read_b128 v[170:173], v138 offset:52224
	ds_read_b128 v[174:177], v138 offset:53248
	ds_read_b128 v[178:181], v138 offset:54272
	ds_read_b128 v[182:185], v138 offset:55296
	ds_read_b128 v[186:189], v138 offset:56320
	buffer_load_dwordx4 v1, s[44:47], s87 offen lds
	s_add_i32 s86, s86, 0x10800
	s_mov_b32 m0, s35
	s_nop 0
	buffer_load_dwordx4 v1, s[44:47], s86 offen lds
	s_barrier
	s_waitcnt lgkmcnt(0)
	s_setprio 1
	s_waitcnt lgkmcnt(6)
	v_mfma_f32_16x16x128_f8f6f4 v[62:65], v[2:9], v[158:165], v[62:65]
	v_mfma_f32_16x16x128_f8f6f4 v[58:61], v[10:17], v[158:165], v[58:61]
	s_waitcnt lgkmcnt(4)
	v_mfma_f32_16x16x128_f8f6f4 v[50:53], v[2:9], v[166:173], v[50:53]
	v_mfma_f32_16x16x128_f8f6f4 v[42:45], v[10:17], v[166:173], v[218:221]
	s_waitcnt lgkmcnt(2)
	v_mfma_f32_16x16x128_f8f6f4 v[34:37], v[2:9], v[174:181], v[222:225]
	v_mfma_f32_16x16x128_f8f6f4 v[26:29], v[10:17], v[174:181], v[226:229]
	s_waitcnt lgkmcnt(0)
	v_mfma_f32_16x16x128_f8f6f4 v[230:233], v[2:9], v[182:189], v[230:233]
	v_mfma_f32_16x16x128_f8f6f4 v[10:13], v[10:17], v[182:189], v[234:237]
	s_setprio 0
	s_barrier
	s_mov_b32 m0, s36
	s_add_i32 s33, s85, 0x2080
	buffer_load_dwordx4 v134, s[8:11], s33 offen lds
	s_add_i32 s85, s85, 0x22080
	s_mov_b32 m0, s37
	s_nop 0
	buffer_load_dwordx4 v134, s[8:11], s85 offen lds
	s_waitcnt vmcnt(6)
	s_barrier
	s_setprio 1
	v_mfma_f32_16x16x128_f8f6f4 v[54:57], v[142:149], v[158:165], v[54:57]
	v_mfma_f32_16x16x128_f8f6f4 v[46:49], v[150:157], v[158:165], v[238:241]
	v_mfma_f32_16x16x128_f8f6f4 v[38:41], v[142:149], v[166:173], v[242:245]
	v_mfma_f32_16x16x128_f8f6f4 v[30:33], v[150:157], v[166:173], v[246:249]
	v_mfma_f32_16x16x128_f8f6f4 v[22:25], v[142:149], v[174:181], v[250:253]
	v_mfma_f32_16x16x128_f8f6f4 v[14:17], v[150:157], v[174:181], v[130:133]
	v_mfma_f32_16x16x128_f8f6f4 v[6:9], v[142:149], v[182:189], v[66:69]
	v_mfma_f32_16x16x128_f8f6f4 v[2:5], v[150:157], v[182:189], v[190:193]
	s_setprio 0
	s_add_i32 s84, s84, 2
	s_addk_i32 s7, 0x1000
	s_addk_i32 s79, 0x100
	s_cmp_gt_u32 s84, 5
	s_barrier
	s_cbranch_scc0 .LBB0_2509
	v_lshl_add_u32 v152, s78, 8, v135
	v_lshlrev_b32_e32 v153, 1, v136
	v_lshl_or_b32 v153, s73, 8, v153
	v_lshl_add_u32 v152, v152, 10, v153
	s_mov_b32 s73, s57
	s_mov_b32 s78, s58
	s_mov_b32 s79, s59
	s_mov_b32 s84, s72
	v_pk_mul_f32 v[126:127], v[126:127], 0.5 op_sel_hi:[1,0]
	v_pk_mul_f32 v[128:129], v[128:129], 0.5 op_sel_hi:[1,0]
	v_pk_mul_f32 v[122:123], v[122:123], 0.5 op_sel_hi:[1,0]
	v_pk_mul_f32 v[124:125], v[124:125], 0.5 op_sel_hi:[1,0]
	v_pk_mul_f32 v[118:119], v[118:119], 0.5 op_sel_hi:[1,0]
	v_pk_mul_f32 v[120:121], v[120:121], 0.5 op_sel_hi:[1,0]
	v_pk_mul_f32 v[110:111], v[110:111], 0.5 op_sel_hi:[1,0]
	v_pk_mul_f32 v[112:113], v[112:113], 0.5 op_sel_hi:[1,0]
	v_cvt_pk_fp8_f32 v144, v126, v127
	v_cvt_pk_fp8_f32 v145, v122, v123
	v_cvt_pk_fp8_f32 v146, v118, v119
	v_cvt_pk_fp8_f32 v147, v110, v111
	v_cvt_pk_fp8_f32 v144, v128, v129 op_sel:[0,0,1]
	v_cvt_pk_fp8_f32 v145, v124, v125 op_sel:[0,0,1]
	v_cvt_pk_fp8_f32 v146, v120, v121 op_sel:[0,0,1]
	v_cvt_pk_fp8_f32 v147, v112, v113 op_sel:[0,0,1]
	v_mov_b32_e32 v154, v152
	s_nop 0
	global_store_dwordx4 v154, v[144:147], s[68:69]
	s_mov_b32 s100, 1
	v_pk_mul_f32 v[114:115], v[114:115], 0.5 op_sel_hi:[1,0]
	v_pk_mul_f32 v[116:117], v[116:117], 0.5 op_sel_hi:[1,0]
	v_pk_mul_f32 v[106:107], v[106:107], 0.5 op_sel_hi:[1,0]
	v_pk_mul_f32 v[108:109], v[108:109], 0.5 op_sel_hi:[1,0]
	v_pk_mul_f32 v[102:103], v[102:103], 0.5 op_sel_hi:[1,0]
	v_pk_mul_f32 v[104:105], v[104:105], 0.5 op_sel_hi:[1,0]
	v_pk_mul_f32 v[94:95], v[94:95], 0.5 op_sel_hi:[1,0]
	v_pk_mul_f32 v[96:97], v[96:97], 0.5 op_sel_hi:[1,0]
	v_cvt_pk_fp8_f32 v148, v114, v115
	v_cvt_pk_fp8_f32 v149, v106, v107
	v_cvt_pk_fp8_f32 v150, v102, v103
	v_cvt_pk_fp8_f32 v151, v94, v95
	v_cvt_pk_fp8_f32 v148, v116, v117 op_sel:[0,0,1]
	v_cvt_pk_fp8_f32 v149, v108, v109 op_sel:[0,0,1]
	v_cvt_pk_fp8_f32 v150, v104, v105 op_sel:[0,0,1]
	v_cvt_pk_fp8_f32 v151, v96, v97 op_sel:[0,0,1]
	v_add_u32_e32 v155, 0x4000, v152
	s_nop 0
	global_store_dwordx4 v155, v[148:151], s[68:69]
	s_mov_b32 s100, 1
	v_pk_mul_f32 v[98:99], v[98:99], 0.5 op_sel_hi:[1,0]
	v_pk_mul_f32 v[100:101], v[100:101], 0.5 op_sel_hi:[1,0]
	v_pk_mul_f32 v[90:91], v[90:91], 0.5 op_sel_hi:[1,0]
	v_pk_mul_f32 v[92:93], v[92:93], 0.5 op_sel_hi:[1,0]
	v_pk_mul_f32 v[86:87], v[86:87], 0.5 op_sel_hi:[1,0]
	v_pk_mul_f32 v[88:89], v[88:89], 0.5 op_sel_hi:[1,0]
	v_pk_mul_f32 v[78:79], v[78:79], 0.5 op_sel_hi:[1,0]
	v_pk_mul_f32 v[80:81], v[80:81], 0.5 op_sel_hi:[1,0]
	v_cvt_pk_fp8_f32 v144, v98, v99
	v_cvt_pk_fp8_f32 v145, v90, v91
	v_cvt_pk_fp8_f32 v146, v86, v87
	v_cvt_pk_fp8_f32 v147, v78, v79
	v_cvt_pk_fp8_f32 v144, v100, v101 op_sel:[0,0,1]
	v_cvt_pk_fp8_f32 v145, v92, v93 op_sel:[0,0,1]
	v_cvt_pk_fp8_f32 v146, v88, v89 op_sel:[0,0,1]
	v_cvt_pk_fp8_f32 v147, v80, v81 op_sel:[0,0,1]
	v_add_u32_e32 v154, 0x8000, v152
	s_nop 0
	global_store_dwordx4 v154, v[144:147], s[68:69]
	s_mov_b32 s100, 1
	v_pk_mul_f32 v[82:83], v[82:83], 0.5 op_sel_hi:[1,0]
	v_pk_mul_f32 v[84:85], v[84:85], 0.5 op_sel_hi:[1,0]
	v_pk_mul_f32 v[74:75], v[74:75], 0.5 op_sel_hi:[1,0]
	v_pk_mul_f32 v[76:77], v[76:77], 0.5 op_sel_hi:[1,0]
	v_pk_mul_f32 v[70:71], v[70:71], 0.5 op_sel_hi:[1,0]
	v_pk_mul_f32 v[72:73], v[72:73], 0.5 op_sel_hi:[1,0]
	v_pk_mul_f32 v[18:19], v[18:19], 0.5 op_sel_hi:[1,0]
	v_pk_mul_f32 v[20:21], v[20:21], 0.5 op_sel_hi:[1,0]
	v_cvt_pk_fp8_f32 v148, v82, v83
	v_cvt_pk_fp8_f32 v149, v74, v75
	v_cvt_pk_fp8_f32 v150, v70, v71
	v_cvt_pk_fp8_f32 v151, v18, v19
	v_cvt_pk_fp8_f32 v148, v84, v85 op_sel:[0,0,1]
	v_cvt_pk_fp8_f32 v149, v76, v77 op_sel:[0,0,1]
	v_cvt_pk_fp8_f32 v150, v72, v73 op_sel:[0,0,1]
	v_cvt_pk_fp8_f32 v151, v20, v21 op_sel:[0,0,1]
	v_add_u32_e32 v155, 0xc000, v152
	s_nop 0
	global_store_dwordx4 v155, v[148:151], s[68:69]
	s_mov_b32 s100, 1
	v_pk_mul_f32 v[62:63], v[62:63], 0.5 op_sel_hi:[1,0]
	v_pk_mul_f32 v[64:65], v[64:65], 0.5 op_sel_hi:[1,0]
	v_pk_mul_f32 v[58:59], v[58:59], 0.5 op_sel_hi:[1,0]
	v_pk_mul_f32 v[60:61], v[60:61], 0.5 op_sel_hi:[1,0]
	v_pk_mul_f32 v[54:55], v[54:55], 0.5 op_sel_hi:[1,0]
	v_pk_mul_f32 v[56:57], v[56:57], 0.5 op_sel_hi:[1,0]
	v_pk_mul_f32 v[46:47], v[46:47], 0.5 op_sel_hi:[1,0]
	v_pk_mul_f32 v[48:49], v[48:49], 0.5 op_sel_hi:[1,0]
	v_cvt_pk_fp8_f32 v144, v62, v63
	v_cvt_pk_fp8_f32 v145, v58, v59
	v_cvt_pk_fp8_f32 v146, v54, v55
	v_cvt_pk_fp8_f32 v147, v46, v47
	v_cvt_pk_fp8_f32 v144, v64, v65 op_sel:[0,0,1]
	v_cvt_pk_fp8_f32 v145, v60, v61 op_sel:[0,0,1]
	v_cvt_pk_fp8_f32 v146, v56, v57 op_sel:[0,0,1]
	v_cvt_pk_fp8_f32 v147, v48, v49 op_sel:[0,0,1]
	v_add_u32_e32 v154, 0x20000, v152
	s_nop 0
	global_store_dwordx4 v154, v[144:147], s[68:69]
	s_mov_b32 s100, 1
	v_pk_mul_f32 v[50:51], v[50:51], 0.5 op_sel_hi:[1,0]
	v_pk_mul_f32 v[52:53], v[52:53], 0.5 op_sel_hi:[1,0]
	v_pk_mul_f32 v[42:43], v[42:43], 0.5 op_sel_hi:[1,0]
	v_pk_mul_f32 v[44:45], v[44:45], 0.5 op_sel_hi:[1,0]
	v_pk_mul_f32 v[38:39], v[38:39], 0.5 op_sel_hi:[1,0]
	v_pk_mul_f32 v[40:41], v[40:41], 0.5 op_sel_hi:[1,0]
	v_pk_mul_f32 v[30:31], v[30:31], 0.5 op_sel_hi:[1,0]
	v_pk_mul_f32 v[32:33], v[32:33], 0.5 op_sel_hi:[1,0]
	v_cvt_pk_fp8_f32 v148, v50, v51
	v_cvt_pk_fp8_f32 v149, v42, v43
	v_cvt_pk_fp8_f32 v150, v38, v39
	v_cvt_pk_fp8_f32 v151, v30, v31
	v_cvt_pk_fp8_f32 v148, v52, v53 op_sel:[0,0,1]
	v_cvt_pk_fp8_f32 v149, v44, v45 op_sel:[0,0,1]
	v_cvt_pk_fp8_f32 v150, v40, v41 op_sel:[0,0,1]
	v_cvt_pk_fp8_f32 v151, v32, v33 op_sel:[0,0,1]
	v_add_u32_e32 v155, 0x24000, v152
	s_nop 0
	global_store_dwordx4 v155, v[148:151], s[68:69]
	s_mov_b32 s100, 1
	v_pk_mul_f32 v[34:35], v[34:35], 0.5 op_sel_hi:[1,0]
	v_pk_mul_f32 v[36:37], v[36:37], 0.5 op_sel_hi:[1,0]
	v_pk_mul_f32 v[26:27], v[26:27], 0.5 op_sel_hi:[1,0]
	v_pk_mul_f32 v[28:29], v[28:29], 0.5 op_sel_hi:[1,0]
	v_pk_mul_f32 v[22:23], v[22:23], 0.5 op_sel_hi:[1,0]
	v_pk_mul_f32 v[24:25], v[24:25], 0.5 op_sel_hi:[1,0]
	v_pk_mul_f32 v[14:15], v[14:15], 0.5 op_sel_hi:[1,0]
	v_pk_mul_f32 v[16:17], v[16:17], 0.5 op_sel_hi:[1,0]
	v_cvt_pk_fp8_f32 v144, v34, v35
	v_cvt_pk_fp8_f32 v145, v26, v27
	v_cvt_pk_fp8_f32 v146, v22, v23
	v_cvt_pk_fp8_f32 v147, v14, v15
	v_cvt_pk_fp8_f32 v144, v36, v37 op_sel:[0,0,1]
	v_cvt_pk_fp8_f32 v145, v28, v29 op_sel:[0,0,1]
	v_cvt_pk_fp8_f32 v146, v24, v25 op_sel:[0,0,1]
	v_cvt_pk_fp8_f32 v147, v16, v17 op_sel:[0,0,1]
	v_add_u32_e32 v154, 0x28000, v152
	s_nop 0
	global_store_dwordx4 v154, v[144:147], s[68:69]
	s_mov_b32 s100, 1
	v_pk_mul_f32 v[230:231], v[230:231], 0.5 op_sel_hi:[1,0]
	v_pk_mul_f32 v[232:233], v[232:233], 0.5 op_sel_hi:[1,0]
	v_pk_mul_f32 v[10:11], v[10:11], 0.5 op_sel_hi:[1,0]
	v_pk_mul_f32 v[12:13], v[12:13], 0.5 op_sel_hi:[1,0]
	v_pk_mul_f32 v[6:7], v[6:7], 0.5 op_sel_hi:[1,0]
	v_pk_mul_f32 v[8:9], v[8:9], 0.5 op_sel_hi:[1,0]
	v_pk_mul_f32 v[2:3], v[2:3], 0.5 op_sel_hi:[1,0]
	v_pk_mul_f32 v[4:5], v[4:5], 0.5 op_sel_hi:[1,0]
	v_cvt_pk_fp8_f32 v148, v230, v231
	v_cvt_pk_fp8_f32 v149, v10, v11
	v_cvt_pk_fp8_f32 v150, v6, v7
	v_cvt_pk_fp8_f32 v151, v2, v3
	v_cvt_pk_fp8_f32 v148, v232, v233 op_sel:[0,0,1]
	v_cvt_pk_fp8_f32 v149, v12, v13 op_sel:[0,0,1]
	v_cvt_pk_fp8_f32 v150, v8, v9 op_sel:[0,0,1]
	v_cvt_pk_fp8_f32 v151, v4, v5 op_sel:[0,0,1]
	v_add_u32_e32 v155, 0x2c000, v152
	s_nop 0
	global_store_dwordx4 v155, v[148:151], s[68:69]
	s_mov_b32 s100, 1
	s_and_b64 vcc, exec, s[4:5]
	s_cbranch_vccz .LBB0_2500
	s_waitcnt vmcnt(0)
	s_cmpk_gt_u32 s3, 0xff
	s_cbranch_scc1 .LBB0_2513
	s_barrier

.LBB0_3099:
	v_mov_b32_e32 v218, 0xbd38aa3b
	v_mov_b32_e32 v219, 0xbd38aa3b
	v_mov_b32_e32 v220, 0x44800000
	v_mov_b32_e32 v221, 0x44800000
	v_lshrrev_b32_e32 v224, 4, v188
	v_lshl_add_u32 v224, s47, 4, v224
	v_lshlrev_b32_e32 v222, 14, v224
	v_lshrrev_b32_e32 v224, 5, v189
	v_lshl_add_u32 v224, s46, 2, v224
	v_lshl_add_u32 v222, v224, 9, v222
	v_and_b32_e32 v224, 15, v188
	v_lshl_add_u32 v222, v224, 5, v222
	v_and_b32_e32 v224, 31, v189
	v_add_u32_e32 v222, v222, v224
	s_mov_b32 s46, s38
	s_mov_b32 s47, s39
	s_mov_b32 s50, s45
	v_pk_mul_f32 v[226:227], v[174:175], v[218:219]
	v_pk_mul_f32 v[228:229], v[176:177], v[218:219]
	v_pk_mul_f32 v[230:231], v[166:167], v[218:219]
	v_pk_mul_f32 v[232:233], v[168:169], v[218:219]
	v_exp_f32_e32 v226, v226
	v_exp_f32_e32 v227, v227
	v_exp_f32_e32 v228, v228
	v_exp_f32_e32 v229, v229
	v_exp_f32_e32 v230, v230
	v_exp_f32_e32 v231, v231
	v_exp_f32_e32 v232, v232
	v_exp_f32_e32 v233, v233
	v_pk_fma_f32 v[226:227], v[226:227], v[220:221], v[220:221]
	v_pk_fma_f32 v[228:229], v[228:229], v[220:221], v[220:221]
	v_pk_fma_f32 v[230:231], v[230:231], v[220:221], v[220:221]
	v_pk_fma_f32 v[232:233], v[232:233], v[220:221], v[220:221]
	v_rcp_f32_e32 v226, v226
	v_rcp_f32_e32 v227, v227
	v_rcp_f32_e32 v228, v228
	v_rcp_f32_e32 v229, v229
	v_rcp_f32_e32 v230, v230
	v_rcp_f32_e32 v231, v231
	v_rcp_f32_e32 v232, v232
	v_rcp_f32_e32 v233, v233
	v_pk_mul_f32 v[174:175], v[174:175], v[170:171]
	v_pk_mul_f32 v[176:177], v[176:177], v[172:173]
	v_pk_mul_f32 v[166:167], v[166:167], v[162:163]
	v_pk_mul_f32 v[168:169], v[168:169], v[164:165]
	v_pk_mul_f32 v[174:175], v[174:175], v[226:227]
	v_pk_mul_f32 v[176:177], v[176:177], v[228:229]
	v_pk_mul_f32 v[166:167], v[166:167], v[230:231]
	v_pk_mul_f32 v[168:169], v[168:169], v[232:233]
	v_mov_b32_e32 v223, v222
	v_cvt_pk_fp8_f32 v234, v174, v175
	v_cvt_pk_fp8_f32 v235, v166, v167
	v_cvt_pk_fp8_f32 v234, v176, v177 op_sel:[0,0,1]
	v_cvt_pk_fp8_f32 v235, v168, v169 op_sel:[0,0,1]
	s_nop 0
	global_store_dwordx2 v223, v[234:235], s[70:71]
	s_mov_b32 s100, 1
	v_pk_mul_f32 v[226:227], v[158:159], v[218:219]
	v_pk_mul_f32 v[228:229], v[160:161], v[218:219]
	v_pk_mul_f32 v[230:231], v[150:151], v[218:219]
	v_pk_mul_f32 v[232:233], v[152:153], v[218:219]
	v_exp_f32_e32 v226, v226
	v_exp_f32_e32 v227, v227
	v_exp_f32_e32 v228, v228
	v_exp_f32_e32 v229, v229
	v_exp_f32_e32 v230, v230
	v_exp_f32_e32 v231, v231
	v_exp_f32_e32 v232, v232
	v_exp_f32_e32 v233, v233
	v_pk_fma_f32 v[226:227], v[226:227], v[220:221], v[220:221]
	v_pk_fma_f32 v[228:229], v[228:229], v[220:221], v[220:221]
	v_pk_fma_f32 v[230:231], v[230:231], v[220:221], v[220:221]
	v_pk_fma_f32 v[232:233], v[232:233], v[220:221], v[220:221]
	v_rcp_f32_e32 v226, v226
	v_rcp_f32_e32 v227, v227
	v_rcp_f32_e32 v228, v228
	v_rcp_f32_e32 v229, v229
	v_rcp_f32_e32 v230, v230
	v_rcp_f32_e32 v231, v231
	v_rcp_f32_e32 v232, v232
	v_rcp_f32_e32 v233, v233
	v_pk_mul_f32 v[158:159], v[158:159], v[154:155]
	v_pk_mul_f32 v[160:161], v[160:161], v[156:157]
	v_pk_mul_f32 v[150:151], v[150:151], v[146:147]
	v_pk_mul_f32 v[152:153], v[152:153], v[148:149]
	v_pk_mul_f32 v[158:159], v[158:159], v[226:227]
	v_pk_mul_f32 v[160:161], v[160:161], v[228:229]
	v_pk_mul_f32 v[150:151], v[150:151], v[230:231]
	v_pk_mul_f32 v[152:153], v[152:153], v[232:233]
	v_add_u32_e32 v225, 0x4000, v222
	v_cvt_pk_fp8_f32 v236, v158, v159
	v_cvt_pk_fp8_f32 v237, v150, v151
	v_cvt_pk_fp8_f32 v236, v160, v161 op_sel:[0,0,1]
	v_cvt_pk_fp8_f32 v237, v152, v153 op_sel:[0,0,1]
	s_nop 0
	global_store_dwordx2 v225, v[236:237], s[70:71]
	s_mov_b32 s100, 1
	v_pk_mul_f32 v[226:227], v[142:143], v[218:219]
	v_pk_mul_f32 v[228:229], v[144:145], v[218:219]
	v_pk_mul_f32 v[230:231], v[134:135], v[218:219]
	v_pk_mul_f32 v[232:233], v[136:137], v[218:219]
	v_exp_f32_e32 v226, v226
	v_exp_f32_e32 v227, v227
	v_exp_f32_e32 v228, v228
	v_exp_f32_e32 v229, v229
	v_exp_f32_e32 v230, v230
	v_exp_f32_e32 v231, v231
	v_exp_f32_e32 v232, v232
	v_exp_f32_e32 v233, v233
	v_pk_fma_f32 v[226:227], v[226:227], v[220:221], v[220:221]
	v_pk_fma_f32 v[228:229], v[228:229], v[220:221], v[220:221]
	v_pk_fma_f32 v[230:231], v[230:231], v[220:221], v[220:221]
	v_pk_fma_f32 v[232:233], v[232:233], v[220:221], v[220:221]
	v_rcp_f32_e32 v226, v226
	v_rcp_f32_e32 v227, v227
	v_rcp_f32_e32 v228, v228
	v_rcp_f32_e32 v229, v229
	v_rcp_f32_e32 v230, v230
	v_rcp_f32_e32 v231, v231
	v_rcp_f32_e32 v232, v232
	v_rcp_f32_e32 v233, v233
	v_pk_mul_f32 v[142:143], v[142:143], v[138:139]
	v_pk_mul_f32 v[144:145], v[144:145], v[140:141]
	v_pk_mul_f32 v[134:135], v[134:135], v[130:131]
	v_pk_mul_f32 v[136:137], v[136:137], v[132:133]
	v_pk_mul_f32 v[142:143], v[142:143], v[226:227]
	v_pk_mul_f32 v[144:145], v[144:145], v[228:229]
	v_pk_mul_f32 v[134:135], v[134:135], v[230:231]
	v_pk_mul_f32 v[136:137], v[136:137], v[232:233]
	v_add_u32_e32 v223, 0x8000, v222
	v_cvt_pk_fp8_f32 v234, v142, v143
	v_cvt_pk_fp8_f32 v235, v134, v135
	v_cvt_pk_fp8_f32 v234, v144, v145 op_sel:[0,0,1]
	v_cvt_pk_fp8_f32 v235, v136, v137 op_sel:[0,0,1]
	s_nop 0
	global_store_dwordx2 v223, v[234:235], s[70:71]
	s_mov_b32 s100, 1
	v_pk_mul_f32 v[226:227], v[126:127], v[218:219]
	v_pk_mul_f32 v[228:229], v[128:129], v[218:219]
	v_pk_mul_f32 v[230:231], v[118:119], v[218:219]
	v_pk_mul_f32 v[232:233], v[120:121], v[218:219]
	v_exp_f32_e32 v226, v226
	v_exp_f32_e32 v227, v227
	v_exp_f32_e32 v228, v228
	v_exp_f32_e32 v229, v229
	v_exp_f32_e32 v230, v230
	v_exp_f32_e32 v231, v231
	v_exp_f32_e32 v232, v232
	v_exp_f32_e32 v233, v233
	v_pk_fma_f32 v[226:227], v[226:227], v[220:221], v[220:221]
	v_pk_fma_f32 v[228:229], v[228:229], v[220:221], v[220:221]
	v_pk_fma_f32 v[230:231], v[230:231], v[220:221], v[220:221]
	v_pk_fma_f32 v[232:233], v[232:233], v[220:221], v[220:221]
	v_rcp_f32_e32 v226, v226
	v_rcp_f32_e32 v227, v227
	v_rcp_f32_e32 v228, v228
	v_rcp_f32_e32 v229, v229
	v_rcp_f32_e32 v230, v230
	v_rcp_f32_e32 v231, v231
	v_rcp_f32_e32 v232, v232
	v_rcp_f32_e32 v233, v233
	v_pk_mul_f32 v[126:127], v[126:127], v[122:123]
	v_pk_mul_f32 v[128:129], v[128:129], v[124:125]
	v_pk_mul_f32 v[118:119], v[118:119], v[114:115]
	v_pk_mul_f32 v[120:121], v[120:121], v[116:117]
	v_pk_mul_f32 v[126:127], v[126:127], v[226:227]
	v_pk_mul_f32 v[128:129], v[128:129], v[228:229]
	v_pk_mul_f32 v[118:119], v[118:119], v[230:231]
	v_pk_mul_f32 v[120:121], v[120:121], v[232:233]
	v_add_u32_e32 v225, 0xc000, v222
	v_cvt_pk_fp8_f32 v236, v126, v127
	v_cvt_pk_fp8_f32 v237, v118, v119
	v_cvt_pk_fp8_f32 v236, v128, v129 op_sel:[0,0,1]
	v_cvt_pk_fp8_f32 v237, v120, v121 op_sel:[0,0,1]
	s_nop 0
	global_store_dwordx2 v225, v[236:237], s[70:71]
	s_mov_b32 s100, 1
	v_pk_mul_f32 v[226:227], v[110:111], v[218:219]
	v_pk_mul_f32 v[228:229], v[112:113], v[218:219]
	v_pk_mul_f32 v[230:231], v[102:103], v[218:219]
	v_pk_mul_f32 v[232:233], v[104:105], v[218:219]
	v_exp_f32_e32 v226, v226
	v_exp_f32_e32 v227, v227
	v_exp_f32_e32 v228, v228
	v_exp_f32_e32 v229, v229
	v_exp_f32_e32 v230, v230
	v_exp_f32_e32 v231, v231
	v_exp_f32_e32 v232, v232
	v_exp_f32_e32 v233, v233
	v_pk_fma_f32 v[226:227], v[226:227], v[220:221], v[220:221]
	v_pk_fma_f32 v[228:229], v[228:229], v[220:221], v[220:221]
	v_pk_fma_f32 v[230:231], v[230:231], v[220:221], v[220:221]
	v_pk_fma_f32 v[232:233], v[232:233], v[220:221], v[220:221]
	v_rcp_f32_e32 v226, v226
	v_rcp_f32_e32 v227, v227
	v_rcp_f32_e32 v228, v228
	v_rcp_f32_e32 v229, v229
	v_rcp_f32_e32 v230, v230
	v_rcp_f32_e32 v231, v231
	v_rcp_f32_e32 v232, v232
	v_rcp_f32_e32 v233, v233
	v_pk_mul_f32 v[110:111], v[110:111], v[106:107]
	v_pk_mul_f32 v[112:113], v[112:113], v[108:109]
	v_pk_mul_f32 v[102:103], v[102:103], v[98:99]
	v_pk_mul_f32 v[104:105], v[104:105], v[100:101]
	v_pk_mul_f32 v[110:111], v[110:111], v[226:227]
	v_pk_mul_f32 v[112:113], v[112:113], v[228:229]
	v_pk_mul_f32 v[102:103], v[102:103], v[230:231]
	v_pk_mul_f32 v[104:105], v[104:105], v[232:233]
	v_add_u32_e32 v223, 0x20000, v222
	v_cvt_pk_fp8_f32 v234, v110, v111
	v_cvt_pk_fp8_f32 v235, v102, v103
	v_cvt_pk_fp8_f32 v234, v112, v113 op_sel:[0,0,1]
	v_cvt_pk_fp8_f32 v235, v104, v105 op_sel:[0,0,1]
	s_nop 0
	global_store_dwordx2 v223, v[234:235], s[70:71]
	s_mov_b32 s100, 1
	v_pk_mul_f32 v[226:227], v[94:95], v[218:219]
	v_pk_mul_f32 v[228:229], v[96:97], v[218:219]
	v_pk_mul_f32 v[230:231], v[86:87], v[218:219]
	v_pk_mul_f32 v[232:233], v[88:89], v[218:219]
	v_exp_f32_e32 v226, v226
	v_exp_f32_e32 v227, v227
	v_exp_f32_e32 v228, v228
	v_exp_f32_e32 v229, v229
	v_exp_f32_e32 v230, v230
	v_exp_f32_e32 v231, v231
	v_exp_f32_e32 v232, v232
	v_exp_f32_e32 v233, v233
	v_pk_fma_f32 v[226:227], v[226:227], v[220:221], v[220:221]
	v_pk_fma_f32 v[228:229], v[228:229], v[220:221], v[220:221]
	v_pk_fma_f32 v[230:231], v[230:231], v[220:221], v[220:221]
	v_pk_fma_f32 v[232:233], v[232:233], v[220:221], v[220:221]
	v_rcp_f32_e32 v226, v226
	v_rcp_f32_e32 v227, v227
	v_rcp_f32_e32 v228, v228
	v_rcp_f32_e32 v229, v229
	v_rcp_f32_e32 v230, v230
	v_rcp_f32_e32 v231, v231
	v_rcp_f32_e32 v232, v232
	v_rcp_f32_e32 v233, v233
	v_pk_mul_f32 v[94:95], v[94:95], v[90:91]
	v_pk_mul_f32 v[96:97], v[96:97], v[92:93]
	v_pk_mul_f32 v[86:87], v[86:87], v[82:83]
	v_pk_mul_f32 v[88:89], v[88:89], v[84:85]
	v_pk_mul_f32 v[94:95], v[94:95], v[226:227]
	v_pk_mul_f32 v[96:97], v[96:97], v[228:229]
	v_pk_mul_f32 v[86:87], v[86:87], v[230:231]
	v_pk_mul_f32 v[88:89], v[88:89], v[232:233]
	v_add_u32_e32 v225, 0x24000, v222
	v_cvt_pk_fp8_f32 v236, v94, v95
	v_cvt_pk_fp8_f32 v237, v86, v87
	v_cvt_pk_fp8_f32 v236, v96, v97 op_sel:[0,0,1]
	v_cvt_pk_fp8_f32 v237, v88, v89 op_sel:[0,0,1]
	s_nop 0
	global_store_dwordx2 v225, v[236:237], s[70:71]
	s_mov_b32 s100, 1
	v_pk_mul_f32 v[226:227], v[78:79], v[218:219]
	v_pk_mul_f32 v[228:229], v[80:81], v[218:219]
	v_pk_mul_f32 v[230:231], v[70:71], v[218:219]
	v_pk_mul_f32 v[232:233], v[72:73], v[218:219]
	v_exp_f32_e32 v226, v226
	v_exp_f32_e32 v227, v227
	v_exp_f32_e32 v228, v228
	v_exp_f32_e32 v229, v229
	v_exp_f32_e32 v230, v230
	v_exp_f32_e32 v231, v231
	v_exp_f32_e32 v232, v232
	v_exp_f32_e32 v233, v233
	v_pk_fma_f32 v[226:227], v[226:227], v[220:221], v[220:221]
	v_pk_fma_f32 v[228:229], v[228:229], v[220:221], v[220:221]
	v_pk_fma_f32 v[230:231], v[230:231], v[220:221], v[220:221]
	v_pk_fma_f32 v[232:233], v[232:233], v[220:221], v[220:221]
	v_rcp_f32_e32 v226, v226
	v_rcp_f32_e32 v227, v227
	v_rcp_f32_e32 v228, v228
	v_rcp_f32_e32 v229, v229
	v_rcp_f32_e32 v230, v230
	v_rcp_f32_e32 v231, v231
	v_rcp_f32_e32 v232, v232
	v_rcp_f32_e32 v233, v233
	v_pk_mul_f32 v[78:79], v[78:79], v[74:75]
	v_pk_mul_f32 v[80:81], v[80:81], v[76:77]
	v_pk_mul_f32 v[70:71], v[70:71], v[66:67]
	v_pk_mul_f32 v[72:73], v[72:73], v[68:69]
	v_pk_mul_f32 v[78:79], v[78:79], v[226:227]
	v_pk_mul_f32 v[80:81], v[80:81], v[228:229]
	v_pk_mul_f32 v[70:71], v[70:71], v[230:231]
	v_pk_mul_f32 v[72:73], v[72:73], v[232:233]
	v_add_u32_e32 v223, 0x28000, v222
	v_cvt_pk_fp8_f32 v234, v78, v79
	v_cvt_pk_fp8_f32 v235, v70, v71
	v_cvt_pk_fp8_f32 v234, v80, v81 op_sel:[0,0,1]
	v_cvt_pk_fp8_f32 v235, v72, v73 op_sel:[0,0,1]
	s_nop 0
	global_store_dwordx2 v223, v[234:235], s[70:71]
	s_mov_b32 s100, 1
	v_pk_mul_f32 v[226:227], v[62:63], v[218:219]
	v_pk_mul_f32 v[228:229], v[64:65], v[218:219]
	v_pk_mul_f32 v[230:231], v[54:55], v[218:219]
	v_pk_mul_f32 v[232:233], v[56:57], v[218:219]
	v_exp_f32_e32 v226, v226
	v_exp_f32_e32 v227, v227
	v_exp_f32_e32 v228, v228
	v_exp_f32_e32 v229, v229
	v_exp_f32_e32 v230, v230
	v_exp_f32_e32 v231, v231
	v_exp_f32_e32 v232, v232
	v_exp_f32_e32 v233, v233
	v_pk_fma_f32 v[226:227], v[226:227], v[220:221], v[220:221]
	v_pk_fma_f32 v[228:229], v[228:229], v[220:221], v[220:221]
	v_pk_fma_f32 v[230:231], v[230:231], v[220:221], v[220:221]
	v_pk_fma_f32 v[232:233], v[232:233], v[220:221], v[220:221]
	v_rcp_f32_e32 v226, v226
	v_rcp_f32_e32 v227, v227
	v_rcp_f32_e32 v228, v228
	v_rcp_f32_e32 v229, v229
	v_rcp_f32_e32 v230, v230
	v_rcp_f32_e32 v231, v231
	v_rcp_f32_e32 v232, v232
	v_rcp_f32_e32 v233, v233
	v_pk_mul_f32 v[62:63], v[62:63], v[58:59]
	v_pk_mul_f32 v[64:65], v[64:65], v[60:61]
	v_pk_mul_f32 v[54:55], v[54:55], v[50:51]
	v_pk_mul_f32 v[56:57], v[56:57], v[52:53]
	v_pk_mul_f32 v[62:63], v[62:63], v[226:227]
	v_pk_mul_f32 v[64:65], v[64:65], v[228:229]
	v_pk_mul_f32 v[54:55], v[54:55], v[230:231]
	v_pk_mul_f32 v[56:57], v[56:57], v[232:233]
	v_add_u32_e32 v225, 0x2c000, v222
	v_cvt_pk_fp8_f32 v236, v62, v63
	v_cvt_pk_fp8_f32 v237, v54, v55
	v_cvt_pk_fp8_f32 v236, v64, v65 op_sel:[0,0,1]
	v_cvt_pk_fp8_f32 v237, v56, v57 op_sel:[0,0,1]
	s_nop 0
	global_store_dwordx2 v225, v[236:237], s[70:71]
	s_mov_b32 s100, 1
	s_and_b64 vcc, exec, s[4:5]
	s_cbranch_vccnz .LBB0_3114

.LBB0_3173:
	s_add_u32 s8, s52, 0x6b00000
	s_addc_u32 s7, s53, 0
	s_add_i32 s5, s6, s5
	s_ashr_i32 s6, s5, 31
	s_lshr_b32 s6, s6, 27
	v_bfe_i32 v5, v2, 27, 1
	s_add_i32 s6, s5, s6
	v_lshlrev_b32_e32 v3, 4, v2
	v_lshrrev_b32_e32 v5, 22, v5
	s_ashr_i32 s12, s6, 5
	s_and_b32 s6, s6, 0xffe0
	v_add_u32_e32 v5, v3, v5
	s_sub_i32 s5, s5, s6
	v_and_b32_e32 v5, 0xfffffc00, v5
	s_bfe_i32 s6, s5, 0x80000
	v_sub_u32_e32 v3, v3, v5
	s_bfe_u32 s6, s6, 0x3000c
	v_ashrrev_i32_e32 v4, 31, v2
	v_lshrrev_b32_e32 v5, 4, v3
	s_add_i32 s6, s5, s6
	v_lshrrev_b32_e32 v4, 26, v4
	v_bitop3_b32 v3, v5, v3, 32 bitop3:0x6c
	s_bfe_i32 s13, s6, 0x80000
	s_and_b32 s6, s6, 0xf8
	v_add_u32_e32 v4, v2, v4
	v_ashrrev_i32_e32 v6, 31, v3
	s_sub_i32 s5, s5, s6
	v_ashrrev_i32_e32 v4, 6, v4
	v_lshrrev_b32_e32 v6, 26, v6
	s_lshl_b32 s12, s12, 3
	s_sext_i32_i8 s5, s5
	v_lshlrev_b32_e32 v5, 3, v4
	v_add_u32_e32 v6, v3, v6
	s_add_i32 s70, s12, s5
	v_and_b32_e32 v5, -16, v5
	v_ashrrev_i32_e32 v7, 6, v6
	v_and_b32_e32 v6, 0xc0, v6
	s_ashr_i32 s5, s70, 31
	s_ashr_i32 s4, s3, 6
	v_add_u32_e32 v5, v7, v5
	v_sub_u32_e32 v3, v3, v6
	v_mov_b32_e32 v6, 1
	v_and_b32_e32 v7, 3, v7
	s_mov_b32 s9, 0x3fffe0
	s_lshr_b32 s5, s5, 28
	v_lshlrev_b32_e32 v4, 5, v4
	v_ashrrev_i16_sdwa v3, v6, sext(v3) dst_sel:DWORD dst_unused:UNUSED_PAD src0_sel:DWORD src1_sel:BYTE_0
	v_lshlrev_b32_e32 v6, 1, v5
	v_lshrrev_b32_e32 v8, 2, v5
	v_and_or_b32 v7, v5, s9, v7
	s_and_b32 s9, s7, 0xffff
	s_lshl_b32 s7, s4, 10
	s_sext_i32_i16 s13, s13
	s_add_i32 s5, s70, s5
	v_and_b32_e32 v4, 32, v4
	v_bfe_i32 v3, v3, 0, 16
	v_and_b32_e32 v6, 24, v6
	v_and_b32_e32 v8, 4, v8
	s_ashr_i32 s59, s13, 3
	s_lshl_b32 s5, s5, 16
	s_add_i32 s21, s7, 0
	s_mov_b32 s47, 0x20000
	s_brev_b32 s46, -2
	v_or3_b32 v6, v7, v8, v6
	v_add_lshl_u32 v3, v4, v3, 1
	s_and_b32 s5, s5, 0xfff00000
	s_lshl_b32 s6, s59, 18
	s_add_i32 s22, s21, 0x10000
	s_and_b32 s45, s71, 0xffff
	v_and_b32_e32 v254, 3, v5
	v_lshrrev_b32_e32 v6, 2, v5
	v_and_b32_e32 v6, 4, v6
	v_or_b32_e32 v254, v254, v6
	v_lshlrev_b32_e32 v6, 2, v5
	v_and_b32_e32 v6, 0x30, v6
	v_or_b32_e32 v254, v254, v6
	v_lshlrev_b32_e32 v6, 1, v5
	v_and_b32_e32 v6, 0x40, v6
	v_or_b32_e32 v254, v254, v6
	v_lshl_add_u32 v135, v254, 10, v3
	s_mov_b32 s10, s46
	s_mov_b32 s11, s47
	s_add_i32 s71, s5, s6
	s_mov_b32 m0, s22
	s_add_i32 s23, s21, 0x12000
	s_mov_b32 s100, 0
	buffer_load_dwordx4 v135, s[8:11], s71 offen lds
	s_or_b32 s5, s71, 0x20000
	s_mov_b32 m0, s23
	v_lshrrev_b32_e32 v254, 4, v5
	v_lshlrev_b32_e32 v134, 14, v254
	v_lshrrev_b32_e32 v254, 5, v3
	v_lshl_add_u32 v134, v254, 9, v134
	v_and_b32_e32 v254, 15, v5
	v_lshl_add_u32 v134, v254, 5, v134
	v_and_b32_e32 v254, 31, v3
	v_add_u32_e32 v134, v134, v254
	buffer_load_dwordx4 v135, s[8:11], s5 offen lds
	s_lshl_b32 s72, s70, 18
	s_mov_b32 m0, s21
	s_add_i32 s24, s21, 0x2000
	buffer_load_dwordx4 v134, s[44:47], s72 offen lds
	s_or_b32 s5, s72, 0x10000
	s_mov_b32 m0, s24
	s_add_i32 s25, s21, 0x14000
	buffer_load_dwordx4 v134, s[44:47], s5 offen lds
	s_or_b32 s5, s71, 0x2000
	s_mov_b32 m0, s25
	s_add_i32 s26, s21, 0x16000
	buffer_load_dwordx4 v135, s[8:11], s5 offen lds
	s_or_b32 s5, s71, 0x22000
	s_mov_b32 m0, s26
	s_add_i32 s27, s21, 0x4000
	buffer_load_dwordx4 v135, s[8:11], s5 offen lds
	s_or_b32 s5, s72, 0x20000
	s_mov_b32 m0, s27
	s_add_i32 s28, s21, 0x6000
	buffer_load_dwordx4 v134, s[44:47], s5 offen lds
	s_or_b32 s5, s72, 0x30000
	s_mov_b32 m0, s28
	s_mov_b32 s29, 0
	buffer_load_dwordx4 v134, s[44:47], s5 offen lds
	s_ashr_i32 s5, s3, 8
	s_cmp_lg_u32 s5, 1
	s_cbranch_scc1 .LBB0_3175
	s_barrier
.LBB0_3175:
	s_add_i32 s30, s21, 0x18000
	s_or_b32 s6, s71, 0x80
	s_mov_b32 s10, s46
	s_mov_b32 s11, s47
	s_mov_b32 m0, s30
	s_add_i32 s31, s21, 0x1a000
	s_waitcnt vmcnt(4)
	s_barrier
	buffer_load_dwordx4 v135, s[8:11], s6 offen lds
	s_or_b32 s6, s71, 0x20080
	s_mov_b32 m0, s31
	s_add_i32 s34, s21, 0x8000
	buffer_load_dwordx4 v135, s[8:11], s6 offen lds
	s_or_b32 s6, s72, 0x800
	s_mov_b32 m0, s34
	s_add_i32 s35, s21, 0xa000
	buffer_load_dwordx4 v134, s[44:47], s6 offen lds
	s_or_b32 s6, s72, 0x10800
	s_mov_b32 m0, s35
	s_add_i32 s36, s21, 0x1c000
	buffer_load_dwordx4 v134, s[44:47], s6 offen lds
	s_or_b32 s6, s71, 0x2080
	s_mov_b32 m0, s36
	s_add_i32 s37, s21, 0x1e000
	buffer_load_dwordx4 v135, s[8:11], s6 offen lds
	s_or_b32 s6, s71, 0x22080
	s_mov_b32 m0, s37
	v_and_b32_e32 v3, 15, v2
	buffer_load_dwordx4 v135, s[8:11], s6 offen lds
	v_lshrrev_b32_e32 v4, 1, v2
	s_and_b32 s4, s4, 3
	v_and_b32_e32 v4, 24, v4
	v_lshlrev_b32_e32 v5, 6, v3
	v_lshlrev_b32_e32 v2, 2, v2
	v_lshl_or_b32 v5, v4, 1, v5
	v_and_b32_e32 v2, 32, v2
	s_lshl_b32 s6, s5, 13
	s_lshl_b32 s7, s4, 12
	v_bitop3_b32 v6, v5, s6, v2 bitop3:0xde
	v_bitop3_b32 v2, v5, s7, v2 bitop3:0xde
	s_waitcnt vmcnt(6)
	v_add_u32_e32 v2, 0, v2
	s_add_i32 s38, s21, 0xc000
	v_lshl_or_b32 v136, s5, 6, v3
	s_add_i32 s39, s21, 0xe000
	s_ashr_i32 s40, s56, 31
	v_lshl_or_b32 v137, s4, 5, v4
	v_add_u32_e32 v138, 0x10000, v2
	v_add_u32_e32 v139, 0, v6
	v_add_u32_e32 v254, 0x14000, v2
	v_add_u32_e32 v252, 0x18000, v2
	v_add_u32_e32 v253, 0x1c000, v2
	s_mov_b64 s[12:13], 0x20000
	s_mov_b64 s[14:15], 0x24000
	s_mov_b32 s41, 0x24000
	s_mov_b64 s[16:17], 0x28000
	s_mov_b32 s42, 0x28000
	s_mov_b64 s[18:19], 0x2c000
	s_mov_b32 s43, 0x2c000
	s_barrier

.LBB0_3184:
	s_lshl_b32 s58, s51, 18
	s_and_b64 s[6:7], s[6:7], exec
	v_mov_b32_e32 v2, 0
	s_cselect_b32 s6, s58, s72
	s_add_i32 s7, s72, 0x30800
	s_addk_i32 s71, 0x100
	s_mov_b32 s72, -2
	ds_read_b128 v[144:147], v138
	ds_read_b128 v[148:151], v138 offset:1024
	ds_read_b128 v[152:155], v138 offset:2048
	ds_read_b128 v[156:159], v138 offset:3072
	s_add_i32 s10, s7, 0xfffd0800
	s_cmp_eq_u32 s72, 4
	s_cselect_b32 s74, s6, s10
	s_cselect_b32 s73, s57, s71
	s_or_b32 s75, s74, 0x800
	s_add_i32 s10, s7, 0xffff0000
	s_mov_b32 m0, s38
	ds_read_b128 v[160:163], v139
	ds_read_b128 v[164:167], v139 offset:1024
	ds_read_b128 v[168:171], v139 offset:2048
	ds_read_b128 v[172:175], v139 offset:3072
	ds_read_b128 v[176:179], v139 offset:4096
	ds_read_b128 v[180:183], v139 offset:5120
	ds_read_b128 v[184:187], v139 offset:6144
	ds_read_b128 v[188:191], v139 offset:7168
	buffer_load_dwordx4 v134, s[44:47], s10 offen lds
	s_mov_b32 m0, s39
	s_nop 0
	buffer_load_dwordx4 v134, s[44:47], s7 offen lds
	s_waitcnt lgkmcnt(8)
	s_barrier
	s_waitcnt lgkmcnt(0)
	s_setprio 1
	s_waitcnt lgkmcnt(4)
	v_mfma_f32_16x16x128_f8f6f4 v[114:117], v[144:151], v[168:175], 0
	v_mfma_f32_16x16x128_f8f6f4 v[106:109], v[152:159], v[168:175], 0
	s_waitcnt lgkmcnt(2)
	v_mfma_f32_16x16x128_f8f6f4 v[98:101], v[144:151], v[176:183], 0
	v_mfma_f32_16x16x128_f8f6f4 v[200:203], v[144:151], v[160:167], 0
	v_mfma_f32_16x16x128_f8f6f4 v[204:207], v[152:159], v[160:167], 0
	v_mfma_f32_16x16x128_f8f6f4 v[208:211], v[152:159], v[176:183], 0
	s_waitcnt lgkmcnt(0)
	v_mfma_f32_16x16x128_f8f6f4 v[212:215], v[144:151], v[184:191], 0
	v_mfma_f32_16x16x128_f8f6f4 v[216:219], v[152:159], v[184:191], 0
	s_setprio 0
	s_barrier
	s_mov_b32 m0, s22
	s_mov_b32 s10, s46
	s_mov_b32 s11, s47
	ds_read_b128 v[122:125], v254
	ds_read_b128 v[126:129], v254 offset:1024
	ds_read_b128 v[192:195], v254 offset:2048
	ds_read_b128 v[196:199], v254 offset:3072
	buffer_load_dwordx4 v135, s[8:11], s73 offen lds
	s_add_i32 s33, s73, 0x20000
	s_mov_b32 m0, s23
	s_nop 0
	buffer_load_dwordx4 v135, s[8:11], s33 offen lds
	s_barrier
	s_waitcnt lgkmcnt(0)
	s_setprio 1
	s_waitcnt lgkmcnt(2)
	v_mfma_f32_16x16x128_f8f6f4 v[118:121], v[122:129], v[160:167], 0
	s_waitcnt lgkmcnt(0)
	v_mfma_f32_16x16x128_f8f6f4 v[110:113], v[192:199], v[160:167], 0
	v_mfma_f32_16x16x128_f8f6f4 v[102:105], v[122:129], v[168:175], 0
	v_mfma_f32_16x16x128_f8f6f4 v[160:163], v[192:199], v[168:175], 0
	v_mfma_f32_16x16x128_f8f6f4 v[164:167], v[122:129], v[176:183], 0
	v_mfma_f32_16x16x128_f8f6f4 v[168:171], v[192:199], v[176:183], 0
	v_mfma_f32_16x16x128_f8f6f4 v[172:175], v[122:129], v[184:191], 0
	v_mfma_f32_16x16x128_f8f6f4 v[176:179], v[192:199], v[184:191], 0
	s_setprio 0
	s_mov_b32 m0, s21
	s_barrier
	ds_read_b128 v[66:69], v139 offset:16384
	s_nop 1
	ds_read_b128 v[70:73], v139 offset:17408
	ds_read_b128 v[74:77], v139 offset:18432
	ds_read_b128 v[78:81], v139 offset:19456
	ds_read_b128 v[82:85], v139 offset:20480
	ds_read_b128 v[86:89], v139 offset:21504
	ds_read_b128 v[90:93], v139 offset:22528
	ds_read_b128 v[94:97], v139 offset:23552
	buffer_load_dwordx4 v134, s[44:47], s74 offen lds
	s_add_i32 s33, s74, 0x10000
	s_mov_b32 m0, s24
	s_nop 0
	buffer_load_dwordx4 v134, s[44:47], s33 offen lds
	s_barrier
	s_waitcnt lgkmcnt(0)
	s_setprio 1
	s_waitcnt lgkmcnt(6)
	v_mfma_f32_16x16x128_f8f6f4 v[62:65], v[144:151], v[66:73], 0
	v_mfma_f32_16x16x128_f8f6f4 v[58:61], v[152:159], v[66:73], 0
	s_waitcnt lgkmcnt(4)
	v_mfma_f32_16x16x128_f8f6f4 v[50:53], v[144:151], v[74:81], 0
	s_waitcnt lgkmcnt(0)
	v_mfma_f32_16x16x128_f8f6f4 v[232:235], v[144:151], v[90:97], 0
	v_mfma_f32_16x16x128_f8f6f4 v[220:223], v[152:159], v[74:81], 0
	v_mfma_f32_16x16x128_f8f6f4 v[224:227], v[144:151], v[82:89], 0
	v_mfma_f32_16x16x128_f8f6f4 v[228:231], v[152:159], v[82:89], 0
	v_mfma_f32_16x16x128_f8f6f4 v[236:239], v[152:159], v[90:97], 0
	s_setprio 0
	s_barrier
	s_mov_b32 m0, s25
	s_add_i32 s33, s73, 0x2000
	buffer_load_dwordx4 v135, s[8:11], s33 offen lds
	s_add_i32 s33, s73, 0x22000
	s_mov_b32 m0, s26
	s_nop 0
	buffer_load_dwordx4 v135, s[8:11], s33 offen lds
	s_cmp_eq_u32 s100, 0
	s_cbranch_scc1 .Lfw_16_a_p
	s_waitcnt vmcnt(16)
	s_mov_b32 s100, 0
	s_branch .Lfw_16_b_p

.Lfw_16_b_p:
	s_barrier
	s_setprio 1
	v_mfma_f32_16x16x128_f8f6f4 v[54:57], v[122:129], v[66:73], 0
	v_mfma_f32_16x16x128_f8f6f4 v[240:243], v[192:199], v[66:73], 0
	v_mfma_f32_16x16x128_f8f6f4 v[244:247], v[122:129], v[74:81], 0
	v_mfma_f32_16x16x128_f8f6f4 v[248:251], v[192:199], v[74:81], 0
	v_mfma_f32_16x16x128_f8f6f4 v[130:133], v[122:129], v[82:89], 0
	v_mfma_f32_16x16x128_f8f6f4 v[140:143], v[192:199], v[82:89], 0
	v_mfma_f32_16x16x128_f8f6f4 v[66:69], v[122:129], v[90:97], 0
	v_mfma_f32_16x16x128_f8f6f4 v[192:195], v[192:199], v[90:97], 0
	s_setprio 0
	s_barrier
	s_nop 4
	ds_read_b128 v[2:5], v252
	ds_read_b128 v[6:9], v252 offset:1024
	ds_read_b128 v[10:13], v252 offset:2048
	ds_read_b128 v[14:17], v252 offset:3072
	s_mov_b32 m0, s27
	s_add_i32 s33, s74, 0x20000
	ds_read_b128 v[18:21], v139 offset:32768
	ds_read_b128 v[22:25], v139 offset:33792
	ds_read_b128 v[26:29], v139 offset:34816
	ds_read_b128 v[30:33], v139 offset:35840
	ds_read_b128 v[34:37], v139 offset:36864
	ds_read_b128 v[38:41], v139 offset:37888
	ds_read_b128 v[42:45], v139 offset:38912
	ds_read_b128 v[46:49], v139 offset:39936
	buffer_load_dwordx4 v134, s[44:47], s33 offen lds
	s_add_i32 s33, s74, 0x30000
	s_mov_b32 m0, s28
	s_nop 0
	buffer_load_dwordx4 v134, s[44:47], s33 offen lds
	s_waitcnt lgkmcnt(8)
	s_barrier
	s_waitcnt lgkmcnt(0)
	s_setprio 1
	s_waitcnt lgkmcnt(6)
	v_mfma_f32_16x16x128_f8f6f4 v[126:129], v[2:9], v[18:25], v[200:203]
	v_mfma_f32_16x16x128_f8f6f4 v[122:125], v[10:17], v[18:25], v[204:207]
	s_waitcnt lgkmcnt(4)
	v_mfma_f32_16x16x128_f8f6f4 v[114:117], v[2:9], v[26:33], v[114:117]
	v_mfma_f32_16x16x128_f8f6f4 v[106:109], v[10:17], v[26:33], v[106:109]
	s_waitcnt lgkmcnt(2)
	v_mfma_f32_16x16x128_f8f6f4 v[98:101], v[2:9], v[34:41], v[98:101]
	v_mfma_f32_16x16x128_f8f6f4 v[90:93], v[10:17], v[34:41], v[208:211]
	s_waitcnt lgkmcnt(0)
	v_mfma_f32_16x16x128_f8f6f4 v[82:85], v[2:9], v[42:49], v[212:215]
	v_mfma_f32_16x16x128_f8f6f4 v[74:77], v[10:17], v[42:49], v[216:219]
	s_setprio 0
	s_barrier
	s_mov_b32 m0, s30
	s_add_i32 s33, s73, 0x80
	ds_read_b128 v[144:147], v253
	ds_read_b128 v[148:151], v253 offset:1024
	ds_read_b128 v[152:155], v253 offset:2048
	ds_read_b128 v[156:159], v253 offset:3072
	buffer_load_dwordx4 v135, s[8:11], s33 offen lds
	s_add_i32 s33, s73, 0x20080
	s_mov_b32 m0, s31
	s_nop 0
	buffer_load_dwordx4 v135, s[8:11], s33 offen lds
	s_waitcnt vmcnt(10)
	s_barrier
	s_waitcnt lgkmcnt(0)
	s_setprio 1
	s_waitcnt lgkmcnt(2)
	v_mfma_f32_16x16x128_f8f6f4 v[118:121], v[144:151], v[18:25], v[118:121]
	s_waitcnt lgkmcnt(0)
	v_mfma_f32_16x16x128_f8f6f4 v[110:113], v[152:159], v[18:25], v[110:113]
	v_mfma_f32_16x16x128_f8f6f4 v[102:105], v[144:151], v[26:33], v[102:105]
	v_mfma_f32_16x16x128_f8f6f4 v[94:97], v[152:159], v[26:33], v[160:163]
	v_mfma_f32_16x16x128_f8f6f4 v[86:89], v[144:151], v[34:41], v[164:167]
	v_mfma_f32_16x16x128_f8f6f4 v[78:81], v[152:159], v[34:41], v[168:171]
	v_mfma_f32_16x16x128_f8f6f4 v[70:73], v[144:151], v[42:49], v[172:175]
	v_mfma_f32_16x16x128_f8f6f4 v[18:21], v[152:159], v[42:49], v[176:179]
	s_setprio 0
	s_mov_b32 m0, s34
	s_barrier
	ds_read_b128 v[160:163], v139 offset:49152
	ds_read_b128 v[164:167], v139 offset:50176
	ds_read_b128 v[168:171], v139 offset:51200
	ds_read_b128 v[172:175], v139 offset:52224
	ds_read_b128 v[176:179], v139 offset:53248
	ds_read_b128 v[180:183], v139 offset:54272
	ds_read_b128 v[184:187], v139 offset:55296
	ds_read_b128 v[188:191], v139 offset:56320
	buffer_load_dwordx4 v134, s[44:47], s75 offen lds
	s_add_i32 s74, s74, 0x10800
	s_mov_b32 m0, s35
	s_nop 0
	buffer_load_dwordx4 v134, s[44:47], s74 offen lds
	s_barrier
	s_waitcnt lgkmcnt(0)
	s_setprio 1
	s_waitcnt lgkmcnt(6)
	v_mfma_f32_16x16x128_f8f6f4 v[62:65], v[2:9], v[160:167], v[62:65]
	v_mfma_f32_16x16x128_f8f6f4 v[58:61], v[10:17], v[160:167], v[58:61]
	s_waitcnt lgkmcnt(4)
	v_mfma_f32_16x16x128_f8f6f4 v[50:53], v[2:9], v[168:175], v[50:53]
	v_mfma_f32_16x16x128_f8f6f4 v[42:45], v[10:17], v[168:175], v[220:223]
	s_waitcnt lgkmcnt(2)
	v_mfma_f32_16x16x128_f8f6f4 v[34:37], v[2:9], v[176:183], v[224:227]
	v_mfma_f32_16x16x128_f8f6f4 v[26:29], v[10:17], v[176:183], v[228:231]
	s_waitcnt lgkmcnt(0)
	v_mfma_f32_16x16x128_f8f6f4 v[232:235], v[2:9], v[184:191], v[232:235]
	v_mfma_f32_16x16x128_f8f6f4 v[10:13], v[10:17], v[184:191], v[236:239]
	s_setprio 0
	s_barrier
	s_mov_b32 m0, s36
	s_add_i32 s33, s73, 0x2080
	buffer_load_dwordx4 v135, s[8:11], s33 offen lds
	s_add_i32 s73, s73, 0x22080
	s_mov_b32 m0, s37
	s_nop 0
	buffer_load_dwordx4 v135, s[8:11], s73 offen lds
	s_waitcnt vmcnt(6)
	s_barrier
	s_setprio 1
	v_mfma_f32_16x16x128_f8f6f4 v[54:57], v[144:151], v[160:167], v[54:57]
	v_mfma_f32_16x16x128_f8f6f4 v[46:49], v[152:159], v[160:167], v[240:243]
	v_mfma_f32_16x16x128_f8f6f4 v[38:41], v[144:151], v[168:175], v[244:247]
	v_mfma_f32_16x16x128_f8f6f4 v[30:33], v[152:159], v[168:175], v[248:251]
	v_mfma_f32_16x16x128_f8f6f4 v[22:25], v[144:151], v[176:183], v[130:133]
	v_mfma_f32_16x16x128_f8f6f4 v[14:17], v[152:159], v[176:183], v[140:143]
	v_mfma_f32_16x16x128_f8f6f4 v[6:9], v[144:151], v[184:191], v[66:69]
	v_mfma_f32_16x16x128_f8f6f4 v[2:5], v[152:159], v[184:191], v[192:195]
	s_setprio 0
	s_add_i32 s72, s72, 2
	s_addk_i32 s7, 0x1000
	s_addk_i32 s71, 0x100
	s_cmp_gt_u32 s72, 5
	s_barrier
.LBB0_3185:
	ds_read_b128 v[144:147], v138
	ds_read_b128 v[148:151], v138 offset:1024
	ds_read_b128 v[152:155], v138 offset:2048
	ds_read_b128 v[156:159], v138 offset:3072
	s_add_i32 s10, s7, 0xfffd0800
	s_cmp_eq_u32 s72, 4
	s_cselect_b32 s74, s6, s10
	s_cselect_b32 s73, s57, s71
	s_or_b32 s75, s74, 0x800
	s_add_i32 s10, s7, 0xffff0000
	s_mov_b32 m0, s38
	ds_read_b128 v[160:163], v139
	ds_read_b128 v[164:167], v139 offset:1024
	ds_read_b128 v[168:171], v139 offset:2048
	ds_read_b128 v[172:175], v139 offset:3072
	ds_read_b128 v[176:179], v139 offset:4096
	ds_read_b128 v[180:183], v139 offset:5120
	ds_read_b128 v[184:187], v139 offset:6144
	ds_read_b128 v[188:191], v139 offset:7168
	buffer_load_dwordx4 v134, s[44:47], s10 offen lds
	s_mov_b32 m0, s39
	s_nop 0
	buffer_load_dwordx4 v134, s[44:47], s7 offen lds
	s_waitcnt lgkmcnt(8)
	s_barrier
	s_waitcnt lgkmcnt(0)
	s_setprio 1
	s_waitcnt lgkmcnt(4)
	v_mfma_f32_16x16x128_f8f6f4 v[114:117], v[144:151], v[168:175], v[114:117]
	v_mfma_f32_16x16x128_f8f6f4 v[106:109], v[152:159], v[168:175], v[106:109]
	s_waitcnt lgkmcnt(2)
	v_mfma_f32_16x16x128_f8f6f4 v[98:101], v[144:151], v[176:183], v[98:101]
	v_mfma_f32_16x16x128_f8f6f4 v[200:203], v[144:151], v[160:167], v[126:129]
	v_mfma_f32_16x16x128_f8f6f4 v[204:207], v[152:159], v[160:167], v[122:125]
	v_mfma_f32_16x16x128_f8f6f4 v[208:211], v[152:159], v[176:183], v[90:93]
	s_waitcnt lgkmcnt(0)
	v_mfma_f32_16x16x128_f8f6f4 v[212:215], v[144:151], v[184:191], v[82:85]
	v_mfma_f32_16x16x128_f8f6f4 v[216:219], v[152:159], v[184:191], v[74:77]
	s_setprio 0
	s_barrier
	s_mov_b32 m0, s22
	s_mov_b32 s10, s46
	s_mov_b32 s11, s47
	ds_read_b128 v[122:125], v254
	ds_read_b128 v[126:129], v254 offset:1024
	ds_read_b128 v[192:195], v254 offset:2048
	ds_read_b128 v[196:199], v254 offset:3072
	buffer_load_dwordx4 v135, s[8:11], s73 offen lds
	s_add_i32 s33, s73, 0x20000
	s_mov_b32 m0, s23
	s_nop 0
	buffer_load_dwordx4 v135, s[8:11], s33 offen lds
	s_barrier
	s_waitcnt lgkmcnt(0)
	s_setprio 1
	s_waitcnt lgkmcnt(2)
	v_mfma_f32_16x16x128_f8f6f4 v[118:121], v[122:129], v[160:167], v[118:121]
	s_waitcnt lgkmcnt(0)
	v_mfma_f32_16x16x128_f8f6f4 v[110:113], v[192:199], v[160:167], v[110:113]
	v_mfma_f32_16x16x128_f8f6f4 v[102:105], v[122:129], v[168:175], v[102:105]
	v_mfma_f32_16x16x128_f8f6f4 v[160:163], v[192:199], v[168:175], v[94:97]
	v_mfma_f32_16x16x128_f8f6f4 v[164:167], v[122:129], v[176:183], v[86:89]
	v_mfma_f32_16x16x128_f8f6f4 v[168:171], v[192:199], v[176:183], v[78:81]
	v_mfma_f32_16x16x128_f8f6f4 v[172:175], v[122:129], v[184:191], v[70:73]
	v_mfma_f32_16x16x128_f8f6f4 v[176:179], v[192:199], v[184:191], v[18:21]
	s_setprio 0
	s_mov_b32 m0, s21
	s_barrier
	ds_read_b128 v[66:69], v139 offset:16384
	s_nop 1
	ds_read_b128 v[70:73], v139 offset:17408
	ds_read_b128 v[74:77], v139 offset:18432
	ds_read_b128 v[78:81], v139 offset:19456
	ds_read_b128 v[82:85], v139 offset:20480
	ds_read_b128 v[86:89], v139 offset:21504
	ds_read_b128 v[90:93], v139 offset:22528
	ds_read_b128 v[94:97], v139 offset:23552
	buffer_load_dwordx4 v134, s[44:47], s74 offen lds
	s_add_i32 s33, s74, 0x10000
	s_mov_b32 m0, s24
	s_nop 0
	buffer_load_dwordx4 v134, s[44:47], s33 offen lds
	s_barrier
	s_waitcnt lgkmcnt(0)
	s_setprio 1
	s_waitcnt lgkmcnt(6)
	v_mfma_f32_16x16x128_f8f6f4 v[62:65], v[144:151], v[66:73], v[62:65]
	v_mfma_f32_16x16x128_f8f6f4 v[58:61], v[152:159], v[66:73], v[58:61]
	s_waitcnt lgkmcnt(4)
	v_mfma_f32_16x16x128_f8f6f4 v[50:53], v[144:151], v[74:81], v[50:53]
	s_waitcnt lgkmcnt(0)
	v_mfma_f32_16x16x128_f8f6f4 v[232:235], v[144:151], v[90:97], v[232:235]
	v_mfma_f32_16x16x128_f8f6f4 v[220:223], v[152:159], v[74:81], v[42:45]
	v_mfma_f32_16x16x128_f8f6f4 v[224:227], v[144:151], v[82:89], v[34:37]
	v_mfma_f32_16x16x128_f8f6f4 v[228:231], v[152:159], v[82:89], v[26:29]
	v_mfma_f32_16x16x128_f8f6f4 v[236:239], v[152:159], v[90:97], v[10:13]
	s_setprio 0
	s_barrier
	s_mov_b32 m0, s25
	s_add_i32 s33, s73, 0x2000
	buffer_load_dwordx4 v135, s[8:11], s33 offen lds
	s_add_i32 s33, s73, 0x22000
	s_mov_b32 m0, s26
	s_nop 0
	buffer_load_dwordx4 v135, s[8:11], s33 offen lds
	s_cmp_eq_u32 s100, 0
	s_cbranch_scc1 .Lfw_16_a
	s_waitcnt vmcnt(16)
	s_mov_b32 s100, 0
	s_branch .Lfw_16_b

.Lfw_16_b:
	s_barrier
	s_setprio 1
	v_mfma_f32_16x16x128_f8f6f4 v[54:57], v[122:129], v[66:73], v[54:57]
	v_mfma_f32_16x16x128_f8f6f4 v[240:243], v[192:199], v[66:73], v[46:49]
	v_mfma_f32_16x16x128_f8f6f4 v[244:247], v[122:129], v[74:81], v[38:41]
	v_mfma_f32_16x16x128_f8f6f4 v[248:251], v[192:199], v[74:81], v[30:33]
	v_mfma_f32_16x16x128_f8f6f4 v[130:133], v[122:129], v[82:89], v[22:25]
	v_mfma_f32_16x16x128_f8f6f4 v[140:143], v[192:199], v[82:89], v[14:17]
	v_mfma_f32_16x16x128_f8f6f4 v[66:69], v[122:129], v[90:97], v[6:9]
	v_mfma_f32_16x16x128_f8f6f4 v[192:195], v[192:199], v[90:97], v[2:5]
	s_setprio 0
	s_barrier
	s_nop 4
	ds_read_b128 v[2:5], v252
	ds_read_b128 v[6:9], v252 offset:1024
	ds_read_b128 v[10:13], v252 offset:2048
	ds_read_b128 v[14:17], v252 offset:3072
	s_mov_b32 m0, s27
	s_add_i32 s33, s74, 0x20000
	ds_read_b128 v[18:21], v139 offset:32768
	ds_read_b128 v[22:25], v139 offset:33792
	ds_read_b128 v[26:29], v139 offset:34816
	ds_read_b128 v[30:33], v139 offset:35840
	ds_read_b128 v[34:37], v139 offset:36864
	ds_read_b128 v[38:41], v139 offset:37888
	ds_read_b128 v[42:45], v139 offset:38912
	ds_read_b128 v[46:49], v139 offset:39936
	buffer_load_dwordx4 v134, s[44:47], s33 offen lds
	s_add_i32 s33, s74, 0x30000
	s_mov_b32 m0, s28
	s_nop 0
	buffer_load_dwordx4 v134, s[44:47], s33 offen lds
	s_waitcnt lgkmcnt(8)
	s_barrier
	s_waitcnt lgkmcnt(0)
	s_setprio 1
	s_waitcnt lgkmcnt(6)
	v_mfma_f32_16x16x128_f8f6f4 v[126:129], v[2:9], v[18:25], v[200:203]
	v_mfma_f32_16x16x128_f8f6f4 v[122:125], v[10:17], v[18:25], v[204:207]
	s_waitcnt lgkmcnt(4)
	v_mfma_f32_16x16x128_f8f6f4 v[114:117], v[2:9], v[26:33], v[114:117]
	v_mfma_f32_16x16x128_f8f6f4 v[106:109], v[10:17], v[26:33], v[106:109]
	s_waitcnt lgkmcnt(2)
	v_mfma_f32_16x16x128_f8f6f4 v[98:101], v[2:9], v[34:41], v[98:101]
	v_mfma_f32_16x16x128_f8f6f4 v[90:93], v[10:17], v[34:41], v[208:211]
	s_waitcnt lgkmcnt(0)
	v_mfma_f32_16x16x128_f8f6f4 v[82:85], v[2:9], v[42:49], v[212:215]
	v_mfma_f32_16x16x128_f8f6f4 v[74:77], v[10:17], v[42:49], v[216:219]
	s_setprio 0
	s_barrier
	s_mov_b32 m0, s30
	s_add_i32 s33, s73, 0x80
	ds_read_b128 v[144:147], v253
	ds_read_b128 v[148:151], v253 offset:1024
	ds_read_b128 v[152:155], v253 offset:2048
	ds_read_b128 v[156:159], v253 offset:3072
	buffer_load_dwordx4 v135, s[8:11], s33 offen lds
	s_add_i32 s33, s73, 0x20080
	s_mov_b32 m0, s31
	s_nop 0
	buffer_load_dwordx4 v135, s[8:11], s33 offen lds
	s_waitcnt vmcnt(10)
	s_barrier
	s_waitcnt lgkmcnt(0)
	s_setprio 1
	s_waitcnt lgkmcnt(2)
	v_mfma_f32_16x16x128_f8f6f4 v[118:121], v[144:151], v[18:25], v[118:121]
	s_waitcnt lgkmcnt(0)
	v_mfma_f32_16x16x128_f8f6f4 v[110:113], v[152:159], v[18:25], v[110:113]
	v_mfma_f32_16x16x128_f8f6f4 v[102:105], v[144:151], v[26:33], v[102:105]
	v_mfma_f32_16x16x128_f8f6f4 v[94:97], v[152:159], v[26:33], v[160:163]
	v_mfma_f32_16x16x128_f8f6f4 v[86:89], v[144:151], v[34:41], v[164:167]
	v_mfma_f32_16x16x128_f8f6f4 v[78:81], v[152:159], v[34:41], v[168:171]
	v_mfma_f32_16x16x128_f8f6f4 v[70:73], v[144:151], v[42:49], v[172:175]
	v_mfma_f32_16x16x128_f8f6f4 v[18:21], v[152:159], v[42:49], v[176:179]
	s_setprio 0
	s_mov_b32 m0, s34
	s_barrier
	ds_read_b128 v[160:163], v139 offset:49152
	ds_read_b128 v[164:167], v139 offset:50176
	ds_read_b128 v[168:171], v139 offset:51200
	ds_read_b128 v[172:175], v139 offset:52224
	ds_read_b128 v[176:179], v139 offset:53248
	ds_read_b128 v[180:183], v139 offset:54272
	ds_read_b128 v[184:187], v139 offset:55296
	ds_read_b128 v[188:191], v139 offset:56320
	buffer_load_dwordx4 v134, s[44:47], s75 offen lds
	s_add_i32 s74, s74, 0x10800
	s_mov_b32 m0, s35
	s_nop 0
	buffer_load_dwordx4 v134, s[44:47], s74 offen lds
	s_barrier
	s_waitcnt lgkmcnt(0)
	s_setprio 1
	s_waitcnt lgkmcnt(6)
	v_mfma_f32_16x16x128_f8f6f4 v[62:65], v[2:9], v[160:167], v[62:65]
	v_mfma_f32_16x16x128_f8f6f4 v[58:61], v[10:17], v[160:167], v[58:61]
	s_waitcnt lgkmcnt(4)
	v_mfma_f32_16x16x128_f8f6f4 v[50:53], v[2:9], v[168:175], v[50:53]
	v_mfma_f32_16x16x128_f8f6f4 v[42:45], v[10:17], v[168:175], v[220:223]
	s_waitcnt lgkmcnt(2)
	v_mfma_f32_16x16x128_f8f6f4 v[34:37], v[2:9], v[176:183], v[224:227]
	v_mfma_f32_16x16x128_f8f6f4 v[26:29], v[10:17], v[176:183], v[228:231]
	s_waitcnt lgkmcnt(0)
	v_mfma_f32_16x16x128_f8f6f4 v[232:235], v[2:9], v[184:191], v[232:235]
	v_mfma_f32_16x16x128_f8f6f4 v[10:13], v[10:17], v[184:191], v[236:239]
	s_setprio 0
	s_barrier
	s_mov_b32 m0, s36
	s_add_i32 s33, s73, 0x2080
	buffer_load_dwordx4 v135, s[8:11], s33 offen lds
	s_add_i32 s73, s73, 0x22080
	s_mov_b32 m0, s37
	s_nop 0
	buffer_load_dwordx4 v135, s[8:11], s73 offen lds
	s_waitcnt vmcnt(6)
	s_barrier
	s_setprio 1
	v_mfma_f32_16x16x128_f8f6f4 v[54:57], v[144:151], v[160:167], v[54:57]
	v_mfma_f32_16x16x128_f8f6f4 v[46:49], v[152:159], v[160:167], v[240:243]
	v_mfma_f32_16x16x128_f8f6f4 v[38:41], v[144:151], v[168:175], v[244:247]
	v_mfma_f32_16x16x128_f8f6f4 v[30:33], v[152:159], v[168:175], v[248:251]
	v_mfma_f32_16x16x128_f8f6f4 v[22:25], v[144:151], v[176:183], v[130:133]
	v_mfma_f32_16x16x128_f8f6f4 v[14:17], v[152:159], v[176:183], v[140:143]
	v_mfma_f32_16x16x128_f8f6f4 v[6:9], v[144:151], v[184:191], v[66:69]
	v_mfma_f32_16x16x128_f8f6f4 v[2:5], v[152:159], v[184:191], v[192:195]
	s_setprio 0
	s_add_i32 s72, s72, 2
	s_addk_i32 s7, 0x1000
	s_addk_i32 s71, 0x100
	s_cmp_gt_u32 s72, 5
	s_barrier
	s_cbranch_scc0 .LBB0_3185
	v_lshl_add_u32 v152, s70, 8, v136
	v_lshlrev_b32_e32 v153, 1, v137
	v_lshl_or_b32 v153, s59, 8, v153
	v_lshl_add_u32 v152, v152, 10, v153
	s_mov_b32 s59, s50
	s_mov_b32 s70, s51
	s_mov_b32 s71, s57
	s_mov_b32 s72, s58
	v_pk_mul_f32 v[126:127], v[126:127], 0.5 op_sel_hi:[1,0]
	v_pk_mul_f32 v[128:129], v[128:129], 0.5 op_sel_hi:[1,0]
	v_pk_mul_f32 v[122:123], v[122:123], 0.5 op_sel_hi:[1,0]
	v_pk_mul_f32 v[124:125], v[124:125], 0.5 op_sel_hi:[1,0]
	v_pk_mul_f32 v[118:119], v[118:119], 0.5 op_sel_hi:[1,0]
	v_pk_mul_f32 v[120:121], v[120:121], 0.5 op_sel_hi:[1,0]
	v_pk_mul_f32 v[110:111], v[110:111], 0.5 op_sel_hi:[1,0]
	v_pk_mul_f32 v[112:113], v[112:113], 0.5 op_sel_hi:[1,0]
	v_cvt_pk_fp8_f32 v144, v126, v127
	v_cvt_pk_fp8_f32 v145, v122, v123
	v_cvt_pk_fp8_f32 v146, v118, v119
	v_cvt_pk_fp8_f32 v147, v110, v111
	v_cvt_pk_fp8_f32 v144, v128, v129 op_sel:[0,0,1]
	v_cvt_pk_fp8_f32 v145, v124, v125 op_sel:[0,0,1]
	v_cvt_pk_fp8_f32 v146, v120, v121 op_sel:[0,0,1]
	v_cvt_pk_fp8_f32 v147, v112, v113 op_sel:[0,0,1]
	v_mov_b32_e32 v154, v152
	s_nop 0
	global_store_dwordx4 v154, v[144:147], s[68:69]
	s_mov_b32 s100, 1
	v_pk_mul_f32 v[114:115], v[114:115], 0.5 op_sel_hi:[1,0]
	v_pk_mul_f32 v[116:117], v[116:117], 0.5 op_sel_hi:[1,0]
	v_pk_mul_f32 v[106:107], v[106:107], 0.5 op_sel_hi:[1,0]
	v_pk_mul_f32 v[108:109], v[108:109], 0.5 op_sel_hi:[1,0]
	v_pk_mul_f32 v[102:103], v[102:103], 0.5 op_sel_hi:[1,0]
	v_pk_mul_f32 v[104:105], v[104:105], 0.5 op_sel_hi:[1,0]
	v_pk_mul_f32 v[94:95], v[94:95], 0.5 op_sel_hi:[1,0]
	v_pk_mul_f32 v[96:97], v[96:97], 0.5 op_sel_hi:[1,0]
	v_cvt_pk_fp8_f32 v148, v114, v115
	v_cvt_pk_fp8_f32 v149, v106, v107
	v_cvt_pk_fp8_f32 v150, v102, v103
	v_cvt_pk_fp8_f32 v151, v94, v95
	v_cvt_pk_fp8_f32 v148, v116, v117 op_sel:[0,0,1]
	v_cvt_pk_fp8_f32 v149, v108, v109 op_sel:[0,0,1]
	v_cvt_pk_fp8_f32 v150, v104, v105 op_sel:[0,0,1]
	v_cvt_pk_fp8_f32 v151, v96, v97 op_sel:[0,0,1]
	v_add_u32_e32 v155, 0x4000, v152
	s_nop 0
	global_store_dwordx4 v155, v[148:151], s[68:69]
	s_mov_b32 s100, 1
	v_pk_mul_f32 v[98:99], v[98:99], 0.5 op_sel_hi:[1,0]
	v_pk_mul_f32 v[100:101], v[100:101], 0.5 op_sel_hi:[1,0]
	v_pk_mul_f32 v[90:91], v[90:91], 0.5 op_sel_hi:[1,0]
	v_pk_mul_f32 v[92:93], v[92:93], 0.5 op_sel_hi:[1,0]
	v_pk_mul_f32 v[86:87], v[86:87], 0.5 op_sel_hi:[1,0]
	v_pk_mul_f32 v[88:89], v[88:89], 0.5 op_sel_hi:[1,0]
	v_pk_mul_f32 v[78:79], v[78:79], 0.5 op_sel_hi:[1,0]
	v_pk_mul_f32 v[80:81], v[80:81], 0.5 op_sel_hi:[1,0]
	v_cvt_pk_fp8_f32 v144, v98, v99
	v_cvt_pk_fp8_f32 v145, v90, v91
	v_cvt_pk_fp8_f32 v146, v86, v87
	v_cvt_pk_fp8_f32 v147, v78, v79
	v_cvt_pk_fp8_f32 v144, v100, v101 op_sel:[0,0,1]
	v_cvt_pk_fp8_f32 v145, v92, v93 op_sel:[0,0,1]
	v_cvt_pk_fp8_f32 v146, v88, v89 op_sel:[0,0,1]
	v_cvt_pk_fp8_f32 v147, v80, v81 op_sel:[0,0,1]
	v_add_u32_e32 v154, 0x8000, v152
	s_nop 0
	global_store_dwordx4 v154, v[144:147], s[68:69]
	s_mov_b32 s100, 1
	v_pk_mul_f32 v[82:83], v[82:83], 0.5 op_sel_hi:[1,0]
	v_pk_mul_f32 v[84:85], v[84:85], 0.5 op_sel_hi:[1,0]
	v_pk_mul_f32 v[74:75], v[74:75], 0.5 op_sel_hi:[1,0]
	v_pk_mul_f32 v[76:77], v[76:77], 0.5 op_sel_hi:[1,0]
	v_pk_mul_f32 v[70:71], v[70:71], 0.5 op_sel_hi:[1,0]
	v_pk_mul_f32 v[72:73], v[72:73], 0.5 op_sel_hi:[1,0]
	v_pk_mul_f32 v[18:19], v[18:19], 0.5 op_sel_hi:[1,0]
	v_pk_mul_f32 v[20:21], v[20:21], 0.5 op_sel_hi:[1,0]
	v_cvt_pk_fp8_f32 v148, v82, v83
	v_cvt_pk_fp8_f32 v149, v74, v75
	v_cvt_pk_fp8_f32 v150, v70, v71
	v_cvt_pk_fp8_f32 v151, v18, v19
	v_cvt_pk_fp8_f32 v148, v84, v85 op_sel:[0,0,1]
	v_cvt_pk_fp8_f32 v149, v76, v77 op_sel:[0,0,1]
	v_cvt_pk_fp8_f32 v150, v72, v73 op_sel:[0,0,1]
	v_cvt_pk_fp8_f32 v151, v20, v21 op_sel:[0,0,1]
	v_add_u32_e32 v155, 0xc000, v152
	s_nop 0
	global_store_dwordx4 v155, v[148:151], s[68:69]
	s_mov_b32 s100, 1
	v_pk_mul_f32 v[62:63], v[62:63], 0.5 op_sel_hi:[1,0]
	v_pk_mul_f32 v[64:65], v[64:65], 0.5 op_sel_hi:[1,0]
	v_pk_mul_f32 v[58:59], v[58:59], 0.5 op_sel_hi:[1,0]
	v_pk_mul_f32 v[60:61], v[60:61], 0.5 op_sel_hi:[1,0]
	v_pk_mul_f32 v[54:55], v[54:55], 0.5 op_sel_hi:[1,0]
	v_pk_mul_f32 v[56:57], v[56:57], 0.5 op_sel_hi:[1,0]
	v_pk_mul_f32 v[46:47], v[46:47], 0.5 op_sel_hi:[1,0]
	v_pk_mul_f32 v[48:49], v[48:49], 0.5 op_sel_hi:[1,0]
	v_cvt_pk_fp8_f32 v144, v62, v63
	v_cvt_pk_fp8_f32 v145, v58, v59
	v_cvt_pk_fp8_f32 v146, v54, v55
	v_cvt_pk_fp8_f32 v147, v46, v47
	v_cvt_pk_fp8_f32 v144, v64, v65 op_sel:[0,0,1]
	v_cvt_pk_fp8_f32 v145, v60, v61 op_sel:[0,0,1]
	v_cvt_pk_fp8_f32 v146, v56, v57 op_sel:[0,0,1]
	v_cvt_pk_fp8_f32 v147, v48, v49 op_sel:[0,0,1]
	v_add_u32_e32 v154, 0x20000, v152
	s_nop 0
	global_store_dwordx4 v154, v[144:147], s[68:69]
	s_mov_b32 s100, 1
	v_pk_mul_f32 v[50:51], v[50:51], 0.5 op_sel_hi:[1,0]
	v_pk_mul_f32 v[52:53], v[52:53], 0.5 op_sel_hi:[1,0]
	v_pk_mul_f32 v[42:43], v[42:43], 0.5 op_sel_hi:[1,0]
	v_pk_mul_f32 v[44:45], v[44:45], 0.5 op_sel_hi:[1,0]
	v_pk_mul_f32 v[38:39], v[38:39], 0.5 op_sel_hi:[1,0]
	v_pk_mul_f32 v[40:41], v[40:41], 0.5 op_sel_hi:[1,0]
	v_pk_mul_f32 v[30:31], v[30:31], 0.5 op_sel_hi:[1,0]
	v_pk_mul_f32 v[32:33], v[32:33], 0.5 op_sel_hi:[1,0]
	v_cvt_pk_fp8_f32 v148, v50, v51
	v_cvt_pk_fp8_f32 v149, v42, v43
	v_cvt_pk_fp8_f32 v150, v38, v39
	v_cvt_pk_fp8_f32 v151, v30, v31
	v_cvt_pk_fp8_f32 v148, v52, v53 op_sel:[0,0,1]
	v_cvt_pk_fp8_f32 v149, v44, v45 op_sel:[0,0,1]
	v_cvt_pk_fp8_f32 v150, v40, v41 op_sel:[0,0,1]
	v_cvt_pk_fp8_f32 v151, v32, v33 op_sel:[0,0,1]
	v_add_u32_e32 v155, 0x24000, v152
	s_nop 0
	global_store_dwordx4 v155, v[148:151], s[68:69]
	s_mov_b32 s100, 1
	v_pk_mul_f32 v[34:35], v[34:35], 0.5 op_sel_hi:[1,0]
	v_pk_mul_f32 v[36:37], v[36:37], 0.5 op_sel_hi:[1,0]
	v_pk_mul_f32 v[26:27], v[26:27], 0.5 op_sel_hi:[1,0]
	v_pk_mul_f32 v[28:29], v[28:29], 0.5 op_sel_hi:[1,0]
	v_pk_mul_f32 v[22:23], v[22:23], 0.5 op_sel_hi:[1,0]
	v_pk_mul_f32 v[24:25], v[24:25], 0.5 op_sel_hi:[1,0]
	v_pk_mul_f32 v[14:15], v[14:15], 0.5 op_sel_hi:[1,0]
	v_pk_mul_f32 v[16:17], v[16:17], 0.5 op_sel_hi:[1,0]
	v_cvt_pk_fp8_f32 v144, v34, v35
	v_cvt_pk_fp8_f32 v145, v26, v27
	v_cvt_pk_fp8_f32 v146, v22, v23
	v_cvt_pk_fp8_f32 v147, v14, v15
	v_cvt_pk_fp8_f32 v144, v36, v37 op_sel:[0,0,1]
	v_cvt_pk_fp8_f32 v145, v28, v29 op_sel:[0,0,1]
	v_cvt_pk_fp8_f32 v146, v24, v25 op_sel:[0,0,1]
	v_cvt_pk_fp8_f32 v147, v16, v17 op_sel:[0,0,1]
	v_add_u32_e32 v154, 0x28000, v152
	s_nop 0
	global_store_dwordx4 v154, v[144:147], s[68:69]
	s_mov_b32 s100, 1
	v_pk_mul_f32 v[232:233], v[232:233], 0.5 op_sel_hi:[1,0]
	v_pk_mul_f32 v[234:235], v[234:235], 0.5 op_sel_hi:[1,0]
	v_pk_mul_f32 v[10:11], v[10:11], 0.5 op_sel_hi:[1,0]
	v_pk_mul_f32 v[12:13], v[12:13], 0.5 op_sel_hi:[1,0]
	v_pk_mul_f32 v[6:7], v[6:7], 0.5 op_sel_hi:[1,0]
	v_pk_mul_f32 v[8:9], v[8:9], 0.5 op_sel_hi:[1,0]
	v_pk_mul_f32 v[2:3], v[2:3], 0.5 op_sel_hi:[1,0]
	v_pk_mul_f32 v[4:5], v[4:5], 0.5 op_sel_hi:[1,0]
	v_cvt_pk_fp8_f32 v148, v232, v233
	v_cvt_pk_fp8_f32 v149, v10, v11
	v_cvt_pk_fp8_f32 v150, v6, v7
	v_cvt_pk_fp8_f32 v151, v2, v3
	v_cvt_pk_fp8_f32 v148, v234, v235 op_sel:[0,0,1]
	v_cvt_pk_fp8_f32 v149, v12, v13 op_sel:[0,0,1]
	v_cvt_pk_fp8_f32 v150, v8, v9 op_sel:[0,0,1]
	v_cvt_pk_fp8_f32 v151, v4, v5 op_sel:[0,0,1]
	v_add_u32_e32 v155, 0x2c000, v152
	s_nop 0
	global_store_dwordx4 v155, v[148:151], s[68:69]
	s_mov_b32 s100, 1
	s_and_b64 vcc, exec, s[4:5]
	s_cbranch_vccz .LBB0_3176
	s_waitcnt vmcnt(0)
	s_cmpk_gt_u32 s3, 0xff
	s_cbranch_scc1 .LBB0_3189
	s_barrier
